# GEMM K loops: LDS-DMA loads use SGPR-base (saddr) addressing, 16 v_lshl_add_u64 per K-tile pair removed in all 13 loops
# speedup vs baseline: 1.0077x; 1.0047x over previous
.LBB0_249:
	ds_read_b128 v[152:155], v146
	ds_read_b128 v[156:159], v146 offset:1024
	ds_read_b128 v[160:163], v146 offset:2048
	ds_read_b128 v[164:167], v146 offset:3072
	ds_read_b128 v[168:171], v147
	ds_read_b128 v[172:175], v147 offset:1024
	ds_read_b128 v[176:179], v147 offset:2048
	ds_read_b128 v[180:183], v147 offset:3072
	s_add_u32 s16, s70, 0xfff00080
	s_addc_u32 s17, s71, -1
	s_cmp_eq_u32 s15, 60
	s_cselect_b32 s75, s47, s17
	s_cselect_b32 s74, s93, s16
	s_cselect_b32 s67, s4, s14
	s_cselect_b32 s66, s94, s57
	s_mov_b32 m0, s78
	ds_read_b128 v[184:187], v148
	ds_read_b128 v[188:191], v148 offset:1024
	ds_read_b128 v[192:195], v148 offset:2048
	ds_read_b128 v[196:199], v148 offset:3072
	ds_read_b128 v[200:203], v148 offset:4096
	ds_read_b128 v[204:207], v148 offset:5120
	ds_read_b128 v[208:211], v148 offset:6144
	ds_read_b128 v[212:215], v148 offset:7168
	global_load_lds_dwordx4 v138, s[70:71]
	s_mov_b32 m0, s79
	s_nop 0
	global_load_lds_dwordx4 v140, s[70:71]
	s_waitcnt vmcnt(8)
	s_waitcnt lgkmcnt(0)
	s_barrier
	s_setprio 1
	s_waitcnt lgkmcnt(0)
	v_mfma_f32_16x16x32_bf16 v[122:125], v[152:155], v[184:187], v[122:125]
	v_mfma_f32_16x16x32_bf16 v[114:117], v[160:163], v[184:187], v[114:117]
	v_mfma_f32_16x16x32_bf16 v[106:109], v[152:155], v[192:195], v[106:109]
	v_mfma_f32_16x16x32_bf16 v[98:101], v[160:163], v[192:195], v[98:101]
	v_mfma_f32_16x16x32_bf16 v[90:93], v[152:155], v[200:203], v[90:93]
	v_mfma_f32_16x16x32_bf16 v[82:85], v[160:163], v[200:203], v[82:85]
	v_mfma_f32_16x16x32_bf16 v[74:77], v[152:155], v[208:211], v[74:77]
	v_mfma_f32_16x16x32_bf16 v[58:61], v[160:163], v[208:211], v[58:61]
	v_mfma_f32_16x16x32_bf16 v[122:125], v[156:159], v[188:191], v[122:125]
	v_mfma_f32_16x16x32_bf16 v[114:117], v[164:167], v[188:191], v[114:117]
	v_mfma_f32_16x16x32_bf16 v[106:109], v[156:159], v[196:199], v[106:109]
	v_mfma_f32_16x16x32_bf16 v[98:101], v[164:167], v[196:199], v[98:101]
	v_mfma_f32_16x16x32_bf16 v[90:93], v[156:159], v[204:207], v[90:93]
	v_mfma_f32_16x16x32_bf16 v[82:85], v[164:167], v[204:207], v[82:85]
	v_mfma_f32_16x16x32_bf16 v[74:77], v[156:159], v[212:215], v[74:77]
	v_mfma_f32_16x16x32_bf16 v[58:61], v[164:167], v[212:215], v[58:61]
	s_setprio 0
	s_setprio 1
	v_mfma_f32_16x16x32_bf16 v[126:129], v[168:171], v[184:187], v[126:129]
	v_mfma_f32_16x16x32_bf16 v[118:121], v[176:179], v[184:187], v[118:121]
	v_mfma_f32_16x16x32_bf16 v[110:113], v[168:171], v[192:195], v[110:113]
	v_mfma_f32_16x16x32_bf16 v[102:105], v[176:179], v[192:195], v[102:105]
	v_mfma_f32_16x16x32_bf16 v[94:97], v[168:171], v[200:203], v[94:97]
	v_mfma_f32_16x16x32_bf16 v[86:89], v[176:179], v[200:203], v[86:89]
	v_mfma_f32_16x16x32_bf16 v[78:81], v[168:171], v[208:211], v[78:81]
	v_mfma_f32_16x16x32_bf16 v[66:69], v[176:179], v[208:211], v[66:69]
	v_mfma_f32_16x16x32_bf16 v[126:129], v[172:175], v[188:191], v[126:129]
	v_mfma_f32_16x16x32_bf16 v[118:121], v[180:183], v[188:191], v[118:121]
	v_mfma_f32_16x16x32_bf16 v[110:113], v[172:175], v[196:199], v[110:113]
	v_mfma_f32_16x16x32_bf16 v[102:105], v[180:183], v[196:199], v[102:105]
	v_mfma_f32_16x16x32_bf16 v[94:97], v[172:175], v[204:207], v[94:97]
	v_mfma_f32_16x16x32_bf16 v[86:89], v[180:183], v[204:207], v[86:89]
	v_mfma_f32_16x16x32_bf16 v[78:81], v[172:175], v[212:215], v[78:81]
	v_mfma_f32_16x16x32_bf16 v[66:69], v[180:183], v[212:215], v[66:69]
	s_setprio 0
	s_barrier
	s_mov_b32 m0, s81
	s_mov_b64 s[98:99], s[66:67]
	s_add_u32 s16, s66, 0x100000
	ds_read_b128 v[184:187], v148 offset:16384
	ds_read_b128 v[188:191], v148 offset:17408
	ds_read_b128 v[192:195], v148 offset:18432
	ds_read_b128 v[196:199], v148 offset:19456
	ds_read_b128 v[200:203], v148 offset:20480
	ds_read_b128 v[204:207], v148 offset:21504
	ds_read_b128 v[208:211], v148 offset:22528
	ds_read_b128 v[212:215], v148 offset:23552
	global_load_lds_dwordx4 v134, s[66:67]
	s_mov_b32 m0, s82
	s_addc_u32 s17, s67, 0
	global_load_lds_dwordx4 v130, s[66:67]
	s_mov_b32 m0, s83
	s_mov_b64 s[100:101], s[74:75]
	global_load_lds_dwordx4 v134, s[16:17]
	s_mov_b32 m0, s86
	s_nop 0
	global_load_lds_dwordx4 v130, s[16:17]
	s_mov_b32 m0, s29
	s_nop 0
	global_load_lds_dwordx4 v136, s[74:75]
	s_mov_b32 m0, s33
	s_nop 0
	global_load_lds_dwordx4 v132, s[74:75]
	s_waitcnt vmcnt(8)
	s_waitcnt lgkmcnt(0)
	s_barrier
	s_setprio 1
	s_waitcnt lgkmcnt(0)
	v_mfma_f32_16x16x32_bf16 v[62:65], v[152:155], v[184:187], v[62:65]
	v_mfma_f32_16x16x32_bf16 v[50:53], v[160:163], v[184:187], v[50:53]
	v_mfma_f32_16x16x32_bf16 v[42:45], v[152:155], v[192:195], v[42:45]
	v_mfma_f32_16x16x32_bf16 v[34:37], v[160:163], v[192:195], v[34:37]
	v_mfma_f32_16x16x32_bf16 v[26:29], v[152:155], v[200:203], v[26:29]
	v_mfma_f32_16x16x32_bf16 v[18:21], v[160:163], v[200:203], v[18:21]
	v_mfma_f32_16x16x32_bf16 v[10:13], v[152:155], v[208:211], v[10:13]
	v_mfma_f32_16x16x32_bf16 v[2:5], v[160:163], v[208:211], v[2:5]
	v_mfma_f32_16x16x32_bf16 v[62:65], v[156:159], v[188:191], v[62:65]
	v_mfma_f32_16x16x32_bf16 v[50:53], v[164:167], v[188:191], v[50:53]
	v_mfma_f32_16x16x32_bf16 v[42:45], v[156:159], v[196:199], v[42:45]
	v_mfma_f32_16x16x32_bf16 v[34:37], v[164:167], v[196:199], v[34:37]
	v_mfma_f32_16x16x32_bf16 v[26:29], v[156:159], v[204:207], v[26:29]
	v_mfma_f32_16x16x32_bf16 v[18:21], v[164:167], v[204:207], v[18:21]
	v_mfma_f32_16x16x32_bf16 v[10:13], v[156:159], v[212:215], v[10:13]
	v_mfma_f32_16x16x32_bf16 v[2:5], v[164:167], v[212:215], v[2:5]
	s_setprio 0
	s_setprio 1
	v_mfma_f32_16x16x32_bf16 v[70:73], v[168:171], v[184:187], v[70:73]
	v_mfma_f32_16x16x32_bf16 v[54:57], v[176:179], v[184:187], v[54:57]
	v_mfma_f32_16x16x32_bf16 v[46:49], v[168:171], v[192:195], v[46:49]
	v_mfma_f32_16x16x32_bf16 v[38:41], v[176:179], v[192:195], v[38:41]
	v_mfma_f32_16x16x32_bf16 v[30:33], v[168:171], v[200:203], v[30:33]
	v_mfma_f32_16x16x32_bf16 v[22:25], v[176:179], v[200:203], v[22:25]
	v_mfma_f32_16x16x32_bf16 v[14:17], v[168:171], v[208:211], v[14:17]
	v_mfma_f32_16x16x32_bf16 v[6:9], v[176:179], v[208:211], v[6:9]
	v_mfma_f32_16x16x32_bf16 v[70:73], v[172:175], v[188:191], v[70:73]
	v_mfma_f32_16x16x32_bf16 v[54:57], v[180:183], v[188:191], v[54:57]
	v_mfma_f32_16x16x32_bf16 v[46:49], v[172:175], v[196:199], v[46:49]
	v_mfma_f32_16x16x32_bf16 v[38:41], v[180:183], v[196:199], v[38:41]
	v_mfma_f32_16x16x32_bf16 v[30:33], v[172:175], v[204:207], v[30:33]
	v_mfma_f32_16x16x32_bf16 v[22:25], v[180:183], v[204:207], v[22:25]
	v_mfma_f32_16x16x32_bf16 v[14:17], v[172:175], v[212:215], v[14:17]
	v_mfma_f32_16x16x32_bf16 v[6:9], v[180:183], v[212:215], v[6:9]
	s_setprio 0
	s_barrier
	ds_read_b128 v[152:155], v149
	ds_read_b128 v[156:159], v149 offset:1024
	ds_read_b128 v[160:163], v149 offset:2048
	ds_read_b128 v[164:167], v149 offset:3072
	ds_read_b128 v[168:171], v150
	ds_read_b128 v[172:175], v150 offset:1024
	ds_read_b128 v[176:179], v150 offset:2048
	ds_read_b128 v[180:183], v150 offset:3072
	s_add_u32 s16, s74, 0x100000
	s_addc_u32 s17, s75, 0
	s_mov_b32 m0, s58
	ds_read_b128 v[184:187], v148 offset:32768
	ds_read_b128 v[188:191], v148 offset:33792
	ds_read_b128 v[192:195], v148 offset:34816
	ds_read_b128 v[196:199], v148 offset:35840
	ds_read_b128 v[200:203], v148 offset:36864
	ds_read_b128 v[204:207], v148 offset:37888
	ds_read_b128 v[208:211], v148 offset:38912
	ds_read_b128 v[212:215], v148 offset:39936
	global_load_lds_dwordx4 v136, s[16:17]
	s_mov_b32 m0, s59
	s_nop 0
	global_load_lds_dwordx4 v132, s[16:17]
	s_waitcnt vmcnt(8)
	s_waitcnt lgkmcnt(0)
	s_barrier
	s_setprio 1
	s_waitcnt lgkmcnt(0)
	v_mfma_f32_16x16x32_bf16 v[122:125], v[152:155], v[184:187], v[122:125]
	v_mfma_f32_16x16x32_bf16 v[114:117], v[160:163], v[184:187], v[114:117]
	v_mfma_f32_16x16x32_bf16 v[106:109], v[152:155], v[192:195], v[106:109]
	v_mfma_f32_16x16x32_bf16 v[98:101], v[160:163], v[192:195], v[98:101]
	v_mfma_f32_16x16x32_bf16 v[90:93], v[152:155], v[200:203], v[90:93]
	v_mfma_f32_16x16x32_bf16 v[82:85], v[160:163], v[200:203], v[82:85]
	v_mfma_f32_16x16x32_bf16 v[74:77], v[152:155], v[208:211], v[74:77]
	v_mfma_f32_16x16x32_bf16 v[58:61], v[160:163], v[208:211], v[58:61]
	v_mfma_f32_16x16x32_bf16 v[122:125], v[156:159], v[188:191], v[122:125]
	v_mfma_f32_16x16x32_bf16 v[114:117], v[164:167], v[188:191], v[114:117]
	v_mfma_f32_16x16x32_bf16 v[106:109], v[156:159], v[196:199], v[106:109]
	v_mfma_f32_16x16x32_bf16 v[98:101], v[164:167], v[196:199], v[98:101]
	v_mfma_f32_16x16x32_bf16 v[90:93], v[156:159], v[204:207], v[90:93]
	v_mfma_f32_16x16x32_bf16 v[82:85], v[164:167], v[204:207], v[82:85]
	v_mfma_f32_16x16x32_bf16 v[74:77], v[156:159], v[212:215], v[74:77]
	v_mfma_f32_16x16x32_bf16 v[58:61], v[164:167], v[212:215], v[58:61]
	s_setprio 0
	s_setprio 1
	v_mfma_f32_16x16x32_bf16 v[126:129], v[168:171], v[184:187], v[126:129]
	v_mfma_f32_16x16x32_bf16 v[118:121], v[176:179], v[184:187], v[118:121]
	v_mfma_f32_16x16x32_bf16 v[110:113], v[168:171], v[192:195], v[110:113]
	v_mfma_f32_16x16x32_bf16 v[102:105], v[176:179], v[192:195], v[102:105]
	v_mfma_f32_16x16x32_bf16 v[94:97], v[168:171], v[200:203], v[94:97]
	v_mfma_f32_16x16x32_bf16 v[86:89], v[176:179], v[200:203], v[86:89]
	v_mfma_f32_16x16x32_bf16 v[78:81], v[168:171], v[208:211], v[78:81]
	v_mfma_f32_16x16x32_bf16 v[66:69], v[176:179], v[208:211], v[66:69]
	v_mfma_f32_16x16x32_bf16 v[126:129], v[172:175], v[188:191], v[126:129]
	v_mfma_f32_16x16x32_bf16 v[118:121], v[180:183], v[188:191], v[118:121]
	v_mfma_f32_16x16x32_bf16 v[110:113], v[172:175], v[196:199], v[110:113]
	v_mfma_f32_16x16x32_bf16 v[102:105], v[180:183], v[196:199], v[102:105]
	v_mfma_f32_16x16x32_bf16 v[94:97], v[172:175], v[204:207], v[94:97]
	v_mfma_f32_16x16x32_bf16 v[86:89], v[180:183], v[204:207], v[86:89]
	v_mfma_f32_16x16x32_bf16 v[78:81], v[172:175], v[212:215], v[78:81]
	v_mfma_f32_16x16x32_bf16 v[66:69], v[180:183], v[212:215], v[66:69]
	s_setprio 0
	s_barrier
	s_mov_b32 m0, s87
	s_add_u32 s98, s98, 0x80
	s_addc_u32 s99, s99, 0
	s_add_u32 s100, s100, 0x80
	s_addc_u32 s101, s101, 0
	s_add_u32 s16, s66, 0x100080
	ds_read_b128 v[184:187], v148 offset:49152
	ds_read_b128 v[188:191], v148 offset:50176
	ds_read_b128 v[192:195], v148 offset:51200
	ds_read_b128 v[196:199], v148 offset:52224
	ds_read_b128 v[200:203], v148 offset:53248
	ds_read_b128 v[204:207], v148 offset:54272
	ds_read_b128 v[208:211], v148 offset:55296
	ds_read_b128 v[212:215], v148 offset:56320
	global_load_lds_dwordx4 v134, s[98:99]
	s_mov_b32 m0, s88
	s_addc_u32 s17, s67, 0
	global_load_lds_dwordx4 v130, s[98:99]
	s_mov_b32 m0, s89
	s_nop 0
	global_load_lds_dwordx4 v134, s[16:17]
	s_mov_b32 m0, s56
	s_nop 0
	global_load_lds_dwordx4 v130, s[16:17]
	s_mov_b32 m0, s65
	s_nop 0
	global_load_lds_dwordx4 v136, s[100:101]
	s_mov_b32 m0, s76
	s_nop 0
	global_load_lds_dwordx4 v132, s[100:101]
	s_waitcnt vmcnt(8)
	s_waitcnt lgkmcnt(0)
	s_barrier
	s_setprio 1
	s_waitcnt lgkmcnt(0)
	v_mfma_f32_16x16x32_bf16 v[62:65], v[152:155], v[184:187], v[62:65]
	v_mfma_f32_16x16x32_bf16 v[50:53], v[160:163], v[184:187], v[50:53]
	v_mfma_f32_16x16x32_bf16 v[42:45], v[152:155], v[192:195], v[42:45]
	v_mfma_f32_16x16x32_bf16 v[34:37], v[160:163], v[192:195], v[34:37]
	v_mfma_f32_16x16x32_bf16 v[26:29], v[152:155], v[200:203], v[26:29]
	v_mfma_f32_16x16x32_bf16 v[18:21], v[160:163], v[200:203], v[18:21]
	v_mfma_f32_16x16x32_bf16 v[10:13], v[152:155], v[208:211], v[10:13]
	v_mfma_f32_16x16x32_bf16 v[2:5], v[160:163], v[208:211], v[2:5]
	v_mfma_f32_16x16x32_bf16 v[62:65], v[156:159], v[188:191], v[62:65]
	v_mfma_f32_16x16x32_bf16 v[50:53], v[164:167], v[188:191], v[50:53]
	v_mfma_f32_16x16x32_bf16 v[42:45], v[156:159], v[196:199], v[42:45]
	v_mfma_f32_16x16x32_bf16 v[34:37], v[164:167], v[196:199], v[34:37]
	v_mfma_f32_16x16x32_bf16 v[26:29], v[156:159], v[204:207], v[26:29]
	v_mfma_f32_16x16x32_bf16 v[18:21], v[164:167], v[204:207], v[18:21]
	v_mfma_f32_16x16x32_bf16 v[10:13], v[156:159], v[212:215], v[10:13]
	v_mfma_f32_16x16x32_bf16 v[2:5], v[164:167], v[212:215], v[2:5]
	s_setprio 0
	s_setprio 1
	v_mfma_f32_16x16x32_bf16 v[70:73], v[168:171], v[184:187], v[70:73]
	v_mfma_f32_16x16x32_bf16 v[54:57], v[176:179], v[184:187], v[54:57]
	v_mfma_f32_16x16x32_bf16 v[46:49], v[168:171], v[192:195], v[46:49]
	v_mfma_f32_16x16x32_bf16 v[38:41], v[176:179], v[192:195], v[38:41]
	v_mfma_f32_16x16x32_bf16 v[30:33], v[168:171], v[200:203], v[30:33]
	v_mfma_f32_16x16x32_bf16 v[22:25], v[176:179], v[200:203], v[22:25]
	v_mfma_f32_16x16x32_bf16 v[14:17], v[168:171], v[208:211], v[14:17]
	v_mfma_f32_16x16x32_bf16 v[6:9], v[176:179], v[208:211], v[6:9]
	v_mfma_f32_16x16x32_bf16 v[70:73], v[172:175], v[188:191], v[70:73]
	v_mfma_f32_16x16x32_bf16 v[54:57], v[180:183], v[188:191], v[54:57]
	v_mfma_f32_16x16x32_bf16 v[46:49], v[172:175], v[196:199], v[46:49]
	v_mfma_f32_16x16x32_bf16 v[38:41], v[180:183], v[196:199], v[38:41]
	v_mfma_f32_16x16x32_bf16 v[30:33], v[172:175], v[204:207], v[30:33]
	v_mfma_f32_16x16x32_bf16 v[22:25], v[180:183], v[204:207], v[22:25]
	v_mfma_f32_16x16x32_bf16 v[14:17], v[172:175], v[212:215], v[14:17]
	v_mfma_f32_16x16x32_bf16 v[6:9], v[180:183], v[212:215], v[6:9]
	s_setprio 0
	s_barrier
	s_add_i32 s15, s15, 2
	s_add_u32 s70, s70, 0x100
	s_addc_u32 s71, s71, 0
	s_add_u32 s57, s57, 0x100
	s_addc_u32 s14, s14, 0
	s_cmp_gt_u32 s15, 61
	s_cbranch_scc0 .LBB0_249
	s_and_b64 vcc, exec, s[12:13]
	s_cbranch_vccz .LBB0_252
	s_barrier

.LBB0_331:
	ds_read_b128 v[132:135], v207
	ds_read_b128 v[136:139], v207 offset:1024
	ds_read_b128 v[140:143], v207 offset:2048
	ds_read_b128 v[144:147], v207 offset:3072
	ds_read_b128 v[148:151], v208
	ds_read_b128 v[152:155], v208 offset:1024
	ds_read_b128 v[156:159], v208 offset:2048
	ds_read_b128 v[160:163], v208 offset:3072
	s_add_u32 s16, s66, 0x200
	s_addc_u32 s17, s67, 0
	s_cmpk_eq_i32 s15, 0xa8
	s_cselect_b32 s75, s1, s17
	s_cselect_b32 s74, s0, s16
	s_cselect_b32 s71, s65, s14
	s_cselect_b32 s70, s64, s90
	s_mov_b32 m0, s86
	ds_read_b128 v[164:167], v209
	ds_read_b128 v[168:171], v209 offset:1024
	ds_read_b128 v[172:175], v209 offset:2048
	ds_read_b128 v[194:197], v209 offset:3072
	ds_read_b128 v[198:201], v209 offset:4096
	ds_read_b128 v[202:205], v209 offset:5120
	ds_read_b128 v[210:213], v209 offset:6144
	ds_read_b128 v[214:217], v209 offset:7168
	global_load_lds_dwordx4 v186, s[66:67]
	s_mov_b32 m0, s87
	s_nop 0
	global_load_lds_dwordx4 v188, s[66:67]
	s_waitcnt vmcnt(8)
	s_waitcnt lgkmcnt(0)
	s_barrier
	s_setprio 1
	s_waitcnt lgkmcnt(0)
	v_mfma_f32_16x16x32_bf16 v[122:125], v[132:135], v[164:167], v[122:125]
	v_mfma_f32_16x16x32_bf16 v[118:121], v[140:143], v[164:167], v[118:121]
	v_mfma_f32_16x16x32_bf16 v[110:113], v[132:135], v[172:175], v[110:113]
	v_mfma_f32_16x16x32_bf16 v[106:109], v[140:143], v[172:175], v[106:109]
	v_mfma_f32_16x16x32_bf16 v[94:97], v[132:135], v[198:201], v[94:97]
	v_mfma_f32_16x16x32_bf16 v[90:93], v[140:143], v[198:201], v[90:93]
	v_mfma_f32_16x16x32_bf16 v[78:81], v[132:135], v[210:213], v[78:81]
	v_mfma_f32_16x16x32_bf16 v[74:77], v[140:143], v[210:213], v[74:77]
	v_mfma_f32_16x16x32_bf16 v[122:125], v[136:139], v[168:171], v[122:125]
	v_mfma_f32_16x16x32_bf16 v[118:121], v[144:147], v[168:171], v[118:121]
	v_mfma_f32_16x16x32_bf16 v[110:113], v[136:139], v[194:197], v[110:113]
	v_mfma_f32_16x16x32_bf16 v[106:109], v[144:147], v[194:197], v[106:109]
	v_mfma_f32_16x16x32_bf16 v[94:97], v[136:139], v[202:205], v[94:97]
	v_mfma_f32_16x16x32_bf16 v[90:93], v[144:147], v[202:205], v[90:93]
	v_mfma_f32_16x16x32_bf16 v[78:81], v[136:139], v[214:217], v[78:81]
	v_mfma_f32_16x16x32_bf16 v[74:77], v[144:147], v[214:217], v[74:77]
	s_setprio 0
	s_setprio 1
	v_mfma_f32_16x16x32_bf16 v[126:129], v[148:151], v[164:167], v[126:129]
	v_mfma_f32_16x16x32_bf16 v[114:117], v[156:159], v[164:167], v[114:117]
	v_mfma_f32_16x16x32_bf16 v[102:105], v[148:151], v[172:175], v[102:105]
	v_mfma_f32_16x16x32_bf16 v[98:101], v[156:159], v[172:175], v[98:101]
	v_mfma_f32_16x16x32_bf16 v[86:89], v[148:151], v[198:201], v[86:89]
	v_mfma_f32_16x16x32_bf16 v[82:85], v[156:159], v[198:201], v[82:85]
	v_mfma_f32_16x16x32_bf16 v[70:73], v[148:151], v[210:213], v[70:73]
	v_mfma_f32_16x16x32_bf16 v[66:69], v[156:159], v[210:213], v[66:69]
	v_mfma_f32_16x16x32_bf16 v[126:129], v[152:155], v[168:171], v[126:129]
	v_mfma_f32_16x16x32_bf16 v[114:117], v[160:163], v[168:171], v[114:117]
	v_mfma_f32_16x16x32_bf16 v[102:105], v[152:155], v[194:197], v[102:105]
	v_mfma_f32_16x16x32_bf16 v[98:101], v[160:163], v[194:197], v[98:101]
	v_mfma_f32_16x16x32_bf16 v[86:89], v[152:155], v[202:205], v[86:89]
	v_mfma_f32_16x16x32_bf16 v[82:85], v[160:163], v[202:205], v[82:85]
	v_mfma_f32_16x16x32_bf16 v[70:73], v[152:155], v[214:217], v[70:73]
	v_mfma_f32_16x16x32_bf16 v[66:69], v[160:163], v[214:217], v[66:69]
	s_setprio 0
	s_barrier
	s_mov_b32 m0, s88
	s_mov_b64 s[98:99], s[70:71]
	s_add_u32 s16, s70, 0x2b0000
	ds_read_b128 v[164:167], v209 offset:16384
	ds_read_b128 v[168:171], v209 offset:17408
	ds_read_b128 v[172:175], v209 offset:18432
	ds_read_b128 v[194:197], v209 offset:19456
	ds_read_b128 v[198:201], v209 offset:20480
	ds_read_b128 v[202:205], v209 offset:21504
	ds_read_b128 v[210:213], v209 offset:22528
	ds_read_b128 v[214:217], v209 offset:23552
	global_load_lds_dwordx4 v180, s[70:71]
	s_mov_b32 m0, s84
	s_addc_u32 s17, s71, 0
	global_load_lds_dwordx4 v184, s[70:71]
	s_mov_b32 m0, s85
	s_mov_b64 s[100:101], s[74:75]
	global_load_lds_dwordx4 v180, s[16:17]
	s_mov_b32 m0, s46
	s_nop 0
	global_load_lds_dwordx4 v184, s[16:17]
	s_mov_b32 m0, s11
	s_nop 0
	global_load_lds_dwordx4 v178, s[74:75]
	s_mov_b32 m0, s12
	s_nop 0
	global_load_lds_dwordx4 v182, s[74:75]
	s_waitcnt vmcnt(8)
	s_waitcnt lgkmcnt(0)
	s_barrier
	s_setprio 1
	s_waitcnt lgkmcnt(0)
	v_mfma_f32_16x16x32_bf16 v[58:61], v[132:135], v[164:167], v[58:61]
	v_mfma_f32_16x16x32_bf16 v[54:57], v[140:143], v[164:167], v[54:57]
	v_mfma_f32_16x16x32_bf16 v[46:49], v[132:135], v[172:175], v[46:49]
	v_mfma_f32_16x16x32_bf16 v[42:45], v[140:143], v[172:175], v[42:45]
	v_mfma_f32_16x16x32_bf16 v[30:33], v[132:135], v[198:201], v[30:33]
	v_mfma_f32_16x16x32_bf16 v[26:29], v[140:143], v[198:201], v[26:29]
	v_mfma_f32_16x16x32_bf16 v[14:17], v[132:135], v[210:213], v[14:17]
	v_mfma_f32_16x16x32_bf16 v[10:13], v[140:143], v[210:213], v[10:13]
	v_mfma_f32_16x16x32_bf16 v[58:61], v[136:139], v[168:171], v[58:61]
	v_mfma_f32_16x16x32_bf16 v[54:57], v[144:147], v[168:171], v[54:57]
	v_mfma_f32_16x16x32_bf16 v[46:49], v[136:139], v[194:197], v[46:49]
	v_mfma_f32_16x16x32_bf16 v[42:45], v[144:147], v[194:197], v[42:45]
	v_mfma_f32_16x16x32_bf16 v[30:33], v[136:139], v[202:205], v[30:33]
	v_mfma_f32_16x16x32_bf16 v[26:29], v[144:147], v[202:205], v[26:29]
	v_mfma_f32_16x16x32_bf16 v[14:17], v[136:139], v[214:217], v[14:17]
	v_mfma_f32_16x16x32_bf16 v[10:13], v[144:147], v[214:217], v[10:13]
	s_setprio 0
	s_setprio 1
	v_mfma_f32_16x16x32_bf16 v[62:65], v[148:151], v[164:167], v[62:65]
	v_mfma_f32_16x16x32_bf16 v[50:53], v[156:159], v[164:167], v[50:53]
	v_mfma_f32_16x16x32_bf16 v[38:41], v[148:151], v[172:175], v[38:41]
	v_mfma_f32_16x16x32_bf16 v[34:37], v[156:159], v[172:175], v[34:37]
	v_mfma_f32_16x16x32_bf16 v[22:25], v[148:151], v[198:201], v[22:25]
	v_mfma_f32_16x16x32_bf16 v[18:21], v[156:159], v[198:201], v[18:21]
	v_mfma_f32_16x16x32_bf16 v[6:9], v[148:151], v[210:213], v[6:9]
	v_mfma_f32_16x16x32_bf16 v[2:5], v[156:159], v[210:213], v[2:5]
	v_mfma_f32_16x16x32_bf16 v[62:65], v[152:155], v[168:171], v[62:65]
	v_mfma_f32_16x16x32_bf16 v[50:53], v[160:163], v[168:171], v[50:53]
	v_mfma_f32_16x16x32_bf16 v[38:41], v[152:155], v[194:197], v[38:41]
	v_mfma_f32_16x16x32_bf16 v[34:37], v[160:163], v[194:197], v[34:37]
	v_mfma_f32_16x16x32_bf16 v[22:25], v[152:155], v[202:205], v[22:25]
	v_mfma_f32_16x16x32_bf16 v[18:21], v[160:163], v[202:205], v[18:21]
	v_mfma_f32_16x16x32_bf16 v[6:9], v[152:155], v[214:217], v[6:9]
	v_mfma_f32_16x16x32_bf16 v[2:5], v[160:163], v[214:217], v[2:5]
	s_setprio 0
	s_barrier
	ds_read_b128 v[132:135], v130
	ds_read_b128 v[136:139], v130 offset:1024
	ds_read_b128 v[140:143], v130 offset:2048
	ds_read_b128 v[144:147], v130 offset:3072
	ds_read_b128 v[148:151], v131
	ds_read_b128 v[152:155], v131 offset:1024
	ds_read_b128 v[156:159], v131 offset:2048
	ds_read_b128 v[160:163], v131 offset:3072
	s_add_u32 s16, s74, 0x2b0000
	s_addc_u32 s17, s75, 0
	s_mov_b32 m0, s13
	ds_read_b128 v[164:167], v209 offset:32768
	ds_read_b128 v[168:171], v209 offset:33792
	ds_read_b128 v[172:175], v209 offset:34816
	ds_read_b128 v[194:197], v209 offset:35840
	ds_read_b128 v[198:201], v209 offset:36864
	ds_read_b128 v[202:205], v209 offset:37888
	ds_read_b128 v[210:213], v209 offset:38912
	ds_read_b128 v[214:217], v209 offset:39936
	global_load_lds_dwordx4 v178, s[16:17]
	s_mov_b32 m0, s29
	s_nop 0
	global_load_lds_dwordx4 v182, s[16:17]
	s_waitcnt vmcnt(8)
	s_waitcnt lgkmcnt(0)
	s_barrier
	s_setprio 1
	s_waitcnt lgkmcnt(0)
	v_mfma_f32_16x16x32_bf16 v[122:125], v[132:135], v[164:167], v[122:125]
	v_mfma_f32_16x16x32_bf16 v[118:121], v[140:143], v[164:167], v[118:121]
	v_mfma_f32_16x16x32_bf16 v[110:113], v[132:135], v[172:175], v[110:113]
	v_mfma_f32_16x16x32_bf16 v[106:109], v[140:143], v[172:175], v[106:109]
	v_mfma_f32_16x16x32_bf16 v[94:97], v[132:135], v[198:201], v[94:97]
	v_mfma_f32_16x16x32_bf16 v[90:93], v[140:143], v[198:201], v[90:93]
	v_mfma_f32_16x16x32_bf16 v[78:81], v[132:135], v[210:213], v[78:81]
	v_mfma_f32_16x16x32_bf16 v[74:77], v[140:143], v[210:213], v[74:77]
	v_mfma_f32_16x16x32_bf16 v[122:125], v[136:139], v[168:171], v[122:125]
	v_mfma_f32_16x16x32_bf16 v[118:121], v[144:147], v[168:171], v[118:121]
	v_mfma_f32_16x16x32_bf16 v[110:113], v[136:139], v[194:197], v[110:113]
	v_mfma_f32_16x16x32_bf16 v[106:109], v[144:147], v[194:197], v[106:109]
	v_mfma_f32_16x16x32_bf16 v[94:97], v[136:139], v[202:205], v[94:97]
	v_mfma_f32_16x16x32_bf16 v[90:93], v[144:147], v[202:205], v[90:93]
	v_mfma_f32_16x16x32_bf16 v[78:81], v[136:139], v[214:217], v[78:81]
	v_mfma_f32_16x16x32_bf16 v[74:77], v[144:147], v[214:217], v[74:77]
	s_setprio 0
	s_setprio 1
	v_mfma_f32_16x16x32_bf16 v[126:129], v[148:151], v[164:167], v[126:129]
	v_mfma_f32_16x16x32_bf16 v[114:117], v[156:159], v[164:167], v[114:117]
	v_mfma_f32_16x16x32_bf16 v[102:105], v[148:151], v[172:175], v[102:105]
	v_mfma_f32_16x16x32_bf16 v[98:101], v[156:159], v[172:175], v[98:101]
	v_mfma_f32_16x16x32_bf16 v[86:89], v[148:151], v[198:201], v[86:89]
	v_mfma_f32_16x16x32_bf16 v[82:85], v[156:159], v[198:201], v[82:85]
	v_mfma_f32_16x16x32_bf16 v[70:73], v[148:151], v[210:213], v[70:73]
	v_mfma_f32_16x16x32_bf16 v[66:69], v[156:159], v[210:213], v[66:69]
	v_mfma_f32_16x16x32_bf16 v[126:129], v[152:155], v[168:171], v[126:129]
	v_mfma_f32_16x16x32_bf16 v[114:117], v[160:163], v[168:171], v[114:117]
	v_mfma_f32_16x16x32_bf16 v[102:105], v[152:155], v[194:197], v[102:105]
	v_mfma_f32_16x16x32_bf16 v[98:101], v[160:163], v[194:197], v[98:101]
	v_mfma_f32_16x16x32_bf16 v[86:89], v[152:155], v[202:205], v[86:89]
	v_mfma_f32_16x16x32_bf16 v[82:85], v[160:163], v[202:205], v[82:85]
	v_mfma_f32_16x16x32_bf16 v[70:73], v[152:155], v[214:217], v[70:73]
	v_mfma_f32_16x16x32_bf16 v[66:69], v[160:163], v[214:217], v[66:69]
	s_setprio 0
	s_barrier
	s_mov_b32 m0, s47
	s_add_u32 s98, s98, 0x80
	s_addc_u32 s99, s99, 0
	s_add_u32 s100, s100, 0x80
	s_addc_u32 s101, s101, 0
	s_add_u32 s16, s70, 0x2b0080
	ds_read_b128 v[164:167], v209 offset:49152
	ds_read_b128 v[168:171], v209 offset:50176
	ds_read_b128 v[172:175], v209 offset:51200
	ds_read_b128 v[194:197], v209 offset:52224
	ds_read_b128 v[198:201], v209 offset:53248
	ds_read_b128 v[202:205], v209 offset:54272
	ds_read_b128 v[210:213], v209 offset:55296
	ds_read_b128 v[214:217], v209 offset:56320
	global_load_lds_dwordx4 v180, s[98:99]
	s_mov_b32 m0, s89
	s_addc_u32 s17, s71, 0
	global_load_lds_dwordx4 v184, s[98:99]
	s_mov_b32 m0, s56
	s_nop 0
	global_load_lds_dwordx4 v180, s[16:17]
	s_mov_b32 m0, s57
	s_nop 0
	global_load_lds_dwordx4 v184, s[16:17]
	s_mov_b32 m0, s58
	s_nop 0
	global_load_lds_dwordx4 v178, s[100:101]
	s_mov_b32 m0, s59
	s_nop 0
	global_load_lds_dwordx4 v182, s[100:101]
	s_waitcnt vmcnt(8)
	s_waitcnt lgkmcnt(0)
	s_barrier
	s_setprio 1
	s_waitcnt lgkmcnt(0)
	v_mfma_f32_16x16x32_bf16 v[58:61], v[132:135], v[164:167], v[58:61]
	v_mfma_f32_16x16x32_bf16 v[54:57], v[140:143], v[164:167], v[54:57]
	v_mfma_f32_16x16x32_bf16 v[46:49], v[132:135], v[172:175], v[46:49]
	v_mfma_f32_16x16x32_bf16 v[42:45], v[140:143], v[172:175], v[42:45]
	v_mfma_f32_16x16x32_bf16 v[30:33], v[132:135], v[198:201], v[30:33]
	v_mfma_f32_16x16x32_bf16 v[26:29], v[140:143], v[198:201], v[26:29]
	v_mfma_f32_16x16x32_bf16 v[14:17], v[132:135], v[210:213], v[14:17]
	v_mfma_f32_16x16x32_bf16 v[10:13], v[140:143], v[210:213], v[10:13]
	v_mfma_f32_16x16x32_bf16 v[58:61], v[136:139], v[168:171], v[58:61]
	v_mfma_f32_16x16x32_bf16 v[54:57], v[144:147], v[168:171], v[54:57]
	v_mfma_f32_16x16x32_bf16 v[46:49], v[136:139], v[194:197], v[46:49]
	v_mfma_f32_16x16x32_bf16 v[42:45], v[144:147], v[194:197], v[42:45]
	v_mfma_f32_16x16x32_bf16 v[30:33], v[136:139], v[202:205], v[30:33]
	v_mfma_f32_16x16x32_bf16 v[26:29], v[144:147], v[202:205], v[26:29]
	v_mfma_f32_16x16x32_bf16 v[14:17], v[136:139], v[214:217], v[14:17]
	v_mfma_f32_16x16x32_bf16 v[10:13], v[144:147], v[214:217], v[10:13]
	s_setprio 0
	s_setprio 1
	v_mfma_f32_16x16x32_bf16 v[62:65], v[148:151], v[164:167], v[62:65]
	v_mfma_f32_16x16x32_bf16 v[50:53], v[156:159], v[164:167], v[50:53]
	v_mfma_f32_16x16x32_bf16 v[38:41], v[148:151], v[172:175], v[38:41]
	v_mfma_f32_16x16x32_bf16 v[34:37], v[156:159], v[172:175], v[34:37]
	v_mfma_f32_16x16x32_bf16 v[22:25], v[148:151], v[198:201], v[22:25]
	v_mfma_f32_16x16x32_bf16 v[18:21], v[156:159], v[198:201], v[18:21]
	v_mfma_f32_16x16x32_bf16 v[6:9], v[148:151], v[210:213], v[6:9]
	v_mfma_f32_16x16x32_bf16 v[2:5], v[156:159], v[210:213], v[2:5]
	v_mfma_f32_16x16x32_bf16 v[62:65], v[152:155], v[168:171], v[62:65]
	v_mfma_f32_16x16x32_bf16 v[50:53], v[160:163], v[168:171], v[50:53]
	v_mfma_f32_16x16x32_bf16 v[38:41], v[152:155], v[194:197], v[38:41]
	v_mfma_f32_16x16x32_bf16 v[34:37], v[160:163], v[194:197], v[34:37]
	v_mfma_f32_16x16x32_bf16 v[22:25], v[152:155], v[202:205], v[22:25]
	v_mfma_f32_16x16x32_bf16 v[18:21], v[160:163], v[202:205], v[18:21]
	v_mfma_f32_16x16x32_bf16 v[6:9], v[152:155], v[214:217], v[6:9]
	v_mfma_f32_16x16x32_bf16 v[2:5], v[160:163], v[214:217], v[2:5]
	s_setprio 0
	s_barrier
	s_add_i32 s15, s15, 2
	s_add_u32 s66, s66, 0x100
	s_addc_u32 s67, s67, 0
	s_add_u32 s90, s90, 0x100
	s_addc_u32 s14, s14, 0
	s_cmpk_gt_u32 s15, 0xa9
	s_cbranch_scc0 .LBB0_331
	s_and_b64 vcc, exec, s[30:31]
	s_cbranch_vccz .LBB0_334
	s_barrier

.LBB0_415:
	ds_read_b128 v[150:153], v163
	ds_read_b128 v[154:157], v163 offset:1024
	ds_read_b128 v[158:161], v163 offset:2048
	ds_read_b128 v[168:171], v163 offset:3072
	ds_read_b128 v[172:175], v164
	ds_read_b128 v[176:179], v164 offset:1024
	ds_read_b128 v[180:183], v164 offset:2048
	ds_read_b128 v[184:187], v164 offset:3072
	s_add_u32 s6, s80, 0xfff00080
	s_addc_u32 s7, s81, -1
	s_cmp_eq_u32 s15, 60
	s_cselect_b32 s83, s1, s7
	s_cselect_b32 s82, s75, s6
	s_cselect_b32 s7, s18, s14
	s_cselect_b32 s6, vcc_lo, s30
	s_mov_b32 m0, s89
	ds_read_b128 v[188:191], v165
	ds_read_b128 v[192:195], v165 offset:1024
	ds_read_b128 v[196:199], v165 offset:2048
	ds_read_b128 v[200:203], v165 offset:3072
	ds_read_b128 v[204:207], v165 offset:4096
	ds_read_b128 v[208:211], v165 offset:5120
	ds_read_b128 v[212:215], v165 offset:6144
	ds_read_b128 v[216:219], v165 offset:7168
	global_load_lds_dwordx4 v140, s[80:81]
	s_mov_b32 m0, s92
	s_nop 0
	global_load_lds_dwordx4 v142, s[80:81]
	s_waitcnt vmcnt(8)
	s_waitcnt lgkmcnt(0)
	s_barrier
	s_setprio 1
	s_waitcnt lgkmcnt(0)
	v_mfma_f32_16x16x32_bf16 v[118:121], v[150:153], v[188:191], v[118:121]
	v_mfma_f32_16x16x32_bf16 v[114:117], v[158:161], v[188:191], v[114:117]
	v_mfma_f32_16x16x32_bf16 v[102:105], v[150:153], v[196:199], v[102:105]
	v_mfma_f32_16x16x32_bf16 v[98:101], v[158:161], v[196:199], v[98:101]
	v_mfma_f32_16x16x32_bf16 v[86:89], v[150:153], v[204:207], v[86:89]
	v_mfma_f32_16x16x32_bf16 v[82:85], v[158:161], v[204:207], v[82:85]
	v_mfma_f32_16x16x32_bf16 v[70:73], v[150:153], v[212:215], v[70:73]
	v_mfma_f32_16x16x32_bf16 v[66:69], v[158:161], v[212:215], v[66:69]
	v_mfma_f32_16x16x32_bf16 v[118:121], v[154:157], v[192:195], v[118:121]
	v_mfma_f32_16x16x32_bf16 v[114:117], v[168:171], v[192:195], v[114:117]
	v_mfma_f32_16x16x32_bf16 v[102:105], v[154:157], v[200:203], v[102:105]
	v_mfma_f32_16x16x32_bf16 v[98:101], v[168:171], v[200:203], v[98:101]
	v_mfma_f32_16x16x32_bf16 v[86:89], v[154:157], v[208:211], v[86:89]
	v_mfma_f32_16x16x32_bf16 v[82:85], v[168:171], v[208:211], v[82:85]
	v_mfma_f32_16x16x32_bf16 v[70:73], v[154:157], v[216:219], v[70:73]
	v_mfma_f32_16x16x32_bf16 v[66:69], v[168:171], v[216:219], v[66:69]
	s_setprio 0
	s_setprio 1
	v_mfma_f32_16x16x32_bf16 v[126:129], v[172:175], v[188:191], v[126:129]
	v_mfma_f32_16x16x32_bf16 v[122:125], v[180:183], v[188:191], v[122:125]
	v_mfma_f32_16x16x32_bf16 v[110:113], v[172:175], v[196:199], v[110:113]
	v_mfma_f32_16x16x32_bf16 v[106:109], v[180:183], v[196:199], v[106:109]
	v_mfma_f32_16x16x32_bf16 v[94:97], v[172:175], v[204:207], v[94:97]
	v_mfma_f32_16x16x32_bf16 v[90:93], v[180:183], v[204:207], v[90:93]
	v_mfma_f32_16x16x32_bf16 v[78:81], v[172:175], v[212:215], v[78:81]
	v_mfma_f32_16x16x32_bf16 v[74:77], v[180:183], v[212:215], v[74:77]
	v_mfma_f32_16x16x32_bf16 v[126:129], v[176:179], v[192:195], v[126:129]
	v_mfma_f32_16x16x32_bf16 v[122:125], v[184:187], v[192:195], v[122:125]
	v_mfma_f32_16x16x32_bf16 v[110:113], v[176:179], v[200:203], v[110:113]
	v_mfma_f32_16x16x32_bf16 v[106:109], v[184:187], v[200:203], v[106:109]
	v_mfma_f32_16x16x32_bf16 v[94:97], v[176:179], v[208:211], v[94:97]
	v_mfma_f32_16x16x32_bf16 v[90:93], v[184:187], v[208:211], v[90:93]
	v_mfma_f32_16x16x32_bf16 v[78:81], v[176:179], v[216:219], v[78:81]
	v_mfma_f32_16x16x32_bf16 v[74:77], v[184:187], v[216:219], v[74:77]
	s_setprio 0
	s_barrier
	s_mov_b32 m0, vcc_hi
	s_mov_b64 s[98:99], s[6:7]
	s_add_u32 s16, s6, 0x100000
	ds_read_b128 v[188:191], v165 offset:16384
	ds_read_b128 v[192:195], v165 offset:17408
	ds_read_b128 v[196:199], v165 offset:18432
	ds_read_b128 v[200:203], v165 offset:19456
	ds_read_b128 v[204:207], v165 offset:20480
	ds_read_b128 v[208:211], v165 offset:21504
	ds_read_b128 v[212:215], v165 offset:22528
	ds_read_b128 v[216:219], v165 offset:23552
	global_load_lds_dwordx4 v134, s[6:7]
	s_mov_b32 m0, s84
	s_addc_u32 s17, s7, 0
	global_load_lds_dwordx4 v130, s[6:7]
	s_mov_b32 m0, s85
	s_mov_b64 s[100:101], s[82:83]
	global_load_lds_dwordx4 v134, s[16:17]
	s_mov_b32 m0, s46
	s_nop 0
	global_load_lds_dwordx4 v130, s[16:17]
	s_mov_b32 m0, s86
	s_nop 0
	global_load_lds_dwordx4 v136, s[82:83]
	s_mov_b32 m0, s93
	s_nop 0
	global_load_lds_dwordx4 v132, s[82:83]
	s_waitcnt vmcnt(8)
	s_waitcnt lgkmcnt(0)
	s_barrier
	s_setprio 1
	s_waitcnt lgkmcnt(0)
	v_mfma_f32_16x16x32_bf16 v[54:57], v[150:153], v[188:191], v[54:57]
	v_mfma_f32_16x16x32_bf16 v[50:53], v[158:161], v[188:191], v[50:53]
	v_mfma_f32_16x16x32_bf16 v[38:41], v[150:153], v[196:199], v[38:41]
	v_mfma_f32_16x16x32_bf16 v[34:37], v[158:161], v[196:199], v[34:37]
	v_mfma_f32_16x16x32_bf16 v[22:25], v[150:153], v[204:207], v[22:25]
	v_mfma_f32_16x16x32_bf16 v[18:21], v[158:161], v[204:207], v[18:21]
	v_mfma_f32_16x16x32_bf16 v[6:9], v[150:153], v[212:215], v[6:9]
	v_mfma_f32_16x16x32_bf16 v[2:5], v[158:161], v[212:215], v[2:5]
	v_mfma_f32_16x16x32_bf16 v[54:57], v[154:157], v[192:195], v[54:57]
	v_mfma_f32_16x16x32_bf16 v[50:53], v[168:171], v[192:195], v[50:53]
	v_mfma_f32_16x16x32_bf16 v[38:41], v[154:157], v[200:203], v[38:41]
	v_mfma_f32_16x16x32_bf16 v[34:37], v[168:171], v[200:203], v[34:37]
	v_mfma_f32_16x16x32_bf16 v[22:25], v[154:157], v[208:211], v[22:25]
	v_mfma_f32_16x16x32_bf16 v[18:21], v[168:171], v[208:211], v[18:21]
	v_mfma_f32_16x16x32_bf16 v[6:9], v[154:157], v[216:219], v[6:9]
	v_mfma_f32_16x16x32_bf16 v[2:5], v[168:171], v[216:219], v[2:5]
	s_setprio 0
	s_setprio 1
	v_mfma_f32_16x16x32_bf16 v[62:65], v[172:175], v[188:191], v[62:65]
	v_mfma_f32_16x16x32_bf16 v[58:61], v[180:183], v[188:191], v[58:61]
	v_mfma_f32_16x16x32_bf16 v[46:49], v[172:175], v[196:199], v[46:49]
	v_mfma_f32_16x16x32_bf16 v[42:45], v[180:183], v[196:199], v[42:45]
	v_mfma_f32_16x16x32_bf16 v[30:33], v[172:175], v[204:207], v[30:33]
	v_mfma_f32_16x16x32_bf16 v[26:29], v[180:183], v[204:207], v[26:29]
	v_mfma_f32_16x16x32_bf16 v[14:17], v[172:175], v[212:215], v[14:17]
	v_mfma_f32_16x16x32_bf16 v[10:13], v[180:183], v[212:215], v[10:13]
	v_mfma_f32_16x16x32_bf16 v[62:65], v[176:179], v[192:195], v[62:65]
	v_mfma_f32_16x16x32_bf16 v[58:61], v[184:187], v[192:195], v[58:61]
	v_mfma_f32_16x16x32_bf16 v[46:49], v[176:179], v[200:203], v[46:49]
	v_mfma_f32_16x16x32_bf16 v[42:45], v[184:187], v[200:203], v[42:45]
	v_mfma_f32_16x16x32_bf16 v[30:33], v[176:179], v[208:211], v[30:33]
	v_mfma_f32_16x16x32_bf16 v[26:29], v[184:187], v[208:211], v[26:29]
	v_mfma_f32_16x16x32_bf16 v[14:17], v[176:179], v[216:219], v[14:17]
	v_mfma_f32_16x16x32_bf16 v[10:13], v[184:187], v[216:219], v[10:13]
	s_setprio 0
	s_barrier
	ds_read_b128 v[150:153], v138
	ds_read_b128 v[154:157], v138 offset:1024
	ds_read_b128 v[158:161], v138 offset:2048
	ds_read_b128 v[168:171], v138 offset:3072
	ds_read_b128 v[172:175], v148
	ds_read_b128 v[176:179], v148 offset:1024
	ds_read_b128 v[180:183], v148 offset:2048
	ds_read_b128 v[184:187], v148 offset:3072
	s_add_u32 s16, s82, 0x100000
	s_addc_u32 s17, s83, 0
	s_mov_b32 m0, s94
	ds_read_b128 v[188:191], v165 offset:32768
	ds_read_b128 v[192:195], v165 offset:33792
	ds_read_b128 v[196:199], v165 offset:34816
	ds_read_b128 v[200:203], v165 offset:35840
	ds_read_b128 v[204:207], v165 offset:36864
	ds_read_b128 v[208:211], v165 offset:37888
	ds_read_b128 v[212:215], v165 offset:38912
	ds_read_b128 v[216:219], v165 offset:39936
	global_load_lds_dwordx4 v136, s[16:17]
	s_mov_b32 m0, s95
	s_nop 0
	global_load_lds_dwordx4 v132, s[16:17]
	s_waitcnt vmcnt(8)
	s_waitcnt lgkmcnt(0)
	s_barrier
	s_setprio 1
	s_waitcnt lgkmcnt(0)
	v_mfma_f32_16x16x32_bf16 v[118:121], v[150:153], v[188:191], v[118:121]
	v_mfma_f32_16x16x32_bf16 v[114:117], v[158:161], v[188:191], v[114:117]
	v_mfma_f32_16x16x32_bf16 v[102:105], v[150:153], v[196:199], v[102:105]
	v_mfma_f32_16x16x32_bf16 v[98:101], v[158:161], v[196:199], v[98:101]
	v_mfma_f32_16x16x32_bf16 v[86:89], v[150:153], v[204:207], v[86:89]
	v_mfma_f32_16x16x32_bf16 v[82:85], v[158:161], v[204:207], v[82:85]
	v_mfma_f32_16x16x32_bf16 v[70:73], v[150:153], v[212:215], v[70:73]
	v_mfma_f32_16x16x32_bf16 v[66:69], v[158:161], v[212:215], v[66:69]
	v_mfma_f32_16x16x32_bf16 v[118:121], v[154:157], v[192:195], v[118:121]
	v_mfma_f32_16x16x32_bf16 v[114:117], v[168:171], v[192:195], v[114:117]
	v_mfma_f32_16x16x32_bf16 v[102:105], v[154:157], v[200:203], v[102:105]
	v_mfma_f32_16x16x32_bf16 v[98:101], v[168:171], v[200:203], v[98:101]
	v_mfma_f32_16x16x32_bf16 v[86:89], v[154:157], v[208:211], v[86:89]
	v_mfma_f32_16x16x32_bf16 v[82:85], v[168:171], v[208:211], v[82:85]
	v_mfma_f32_16x16x32_bf16 v[70:73], v[154:157], v[216:219], v[70:73]
	v_mfma_f32_16x16x32_bf16 v[66:69], v[168:171], v[216:219], v[66:69]
	s_setprio 0
	s_setprio 1
	v_mfma_f32_16x16x32_bf16 v[126:129], v[172:175], v[188:191], v[126:129]
	v_mfma_f32_16x16x32_bf16 v[122:125], v[180:183], v[188:191], v[122:125]
	v_mfma_f32_16x16x32_bf16 v[110:113], v[172:175], v[196:199], v[110:113]
	v_mfma_f32_16x16x32_bf16 v[106:109], v[180:183], v[196:199], v[106:109]
	v_mfma_f32_16x16x32_bf16 v[94:97], v[172:175], v[204:207], v[94:97]
	v_mfma_f32_16x16x32_bf16 v[90:93], v[180:183], v[204:207], v[90:93]
	v_mfma_f32_16x16x32_bf16 v[78:81], v[172:175], v[212:215], v[78:81]
	v_mfma_f32_16x16x32_bf16 v[74:77], v[180:183], v[212:215], v[74:77]
	v_mfma_f32_16x16x32_bf16 v[126:129], v[176:179], v[192:195], v[126:129]
	v_mfma_f32_16x16x32_bf16 v[122:125], v[184:187], v[192:195], v[122:125]
	v_mfma_f32_16x16x32_bf16 v[110:113], v[176:179], v[200:203], v[110:113]
	v_mfma_f32_16x16x32_bf16 v[106:109], v[184:187], v[200:203], v[106:109]
	v_mfma_f32_16x16x32_bf16 v[94:97], v[176:179], v[208:211], v[94:97]
	v_mfma_f32_16x16x32_bf16 v[90:93], v[184:187], v[208:211], v[90:93]
	v_mfma_f32_16x16x32_bf16 v[78:81], v[176:179], v[216:219], v[78:81]
	v_mfma_f32_16x16x32_bf16 v[74:77], v[184:187], v[216:219], v[74:77]
	s_setprio 0
	s_barrier
	s_mov_b32 m0, s47
	s_add_u32 s98, s98, 0x80
	s_addc_u32 s99, s99, 0
	s_add_u32 s100, s100, 0x80
	s_addc_u32 s101, s101, 0
	s_add_u32 s6, s6, 0x100080
	ds_read_b128 v[188:191], v165 offset:49152
	ds_read_b128 v[192:195], v165 offset:50176
	ds_read_b128 v[196:199], v165 offset:51200
	ds_read_b128 v[200:203], v165 offset:52224
	ds_read_b128 v[204:207], v165 offset:53248
	ds_read_b128 v[208:211], v165 offset:54272
	ds_read_b128 v[212:215], v165 offset:55296
	ds_read_b128 v[216:219], v165 offset:56320
	global_load_lds_dwordx4 v134, s[98:99]
	s_mov_b32 m0, s91
	s_addc_u32 s7, s7, 0
	global_load_lds_dwordx4 v130, s[98:99]
	s_mov_b32 m0, s56
	s_nop 0
	global_load_lds_dwordx4 v134, s[6:7]
	s_mov_b32 m0, s57
	s_nop 0
	global_load_lds_dwordx4 v130, s[6:7]
	s_mov_b32 m0, s96
	s_nop 0
	global_load_lds_dwordx4 v136, s[100:101]
	s_mov_b32 m0, s97
	s_nop 0
	global_load_lds_dwordx4 v132, s[100:101]
	s_waitcnt vmcnt(8)
	s_waitcnt lgkmcnt(0)
	s_barrier
	s_setprio 1
	s_waitcnt lgkmcnt(0)
	v_mfma_f32_16x16x32_bf16 v[54:57], v[150:153], v[188:191], v[54:57]
	v_mfma_f32_16x16x32_bf16 v[50:53], v[158:161], v[188:191], v[50:53]
	v_mfma_f32_16x16x32_bf16 v[38:41], v[150:153], v[196:199], v[38:41]
	v_mfma_f32_16x16x32_bf16 v[34:37], v[158:161], v[196:199], v[34:37]
	v_mfma_f32_16x16x32_bf16 v[22:25], v[150:153], v[204:207], v[22:25]
	v_mfma_f32_16x16x32_bf16 v[18:21], v[158:161], v[204:207], v[18:21]
	v_mfma_f32_16x16x32_bf16 v[6:9], v[150:153], v[212:215], v[6:9]
	v_mfma_f32_16x16x32_bf16 v[2:5], v[158:161], v[212:215], v[2:5]
	v_mfma_f32_16x16x32_bf16 v[54:57], v[154:157], v[192:195], v[54:57]
	v_mfma_f32_16x16x32_bf16 v[50:53], v[168:171], v[192:195], v[50:53]
	v_mfma_f32_16x16x32_bf16 v[38:41], v[154:157], v[200:203], v[38:41]
	v_mfma_f32_16x16x32_bf16 v[34:37], v[168:171], v[200:203], v[34:37]
	v_mfma_f32_16x16x32_bf16 v[22:25], v[154:157], v[208:211], v[22:25]
	v_mfma_f32_16x16x32_bf16 v[18:21], v[168:171], v[208:211], v[18:21]
	v_mfma_f32_16x16x32_bf16 v[6:9], v[154:157], v[216:219], v[6:9]
	v_mfma_f32_16x16x32_bf16 v[2:5], v[168:171], v[216:219], v[2:5]
	s_setprio 0
	s_setprio 1
	v_mfma_f32_16x16x32_bf16 v[62:65], v[172:175], v[188:191], v[62:65]
	v_mfma_f32_16x16x32_bf16 v[58:61], v[180:183], v[188:191], v[58:61]
	v_mfma_f32_16x16x32_bf16 v[46:49], v[172:175], v[196:199], v[46:49]
	v_mfma_f32_16x16x32_bf16 v[42:45], v[180:183], v[196:199], v[42:45]
	v_mfma_f32_16x16x32_bf16 v[30:33], v[172:175], v[204:207], v[30:33]
	v_mfma_f32_16x16x32_bf16 v[26:29], v[180:183], v[204:207], v[26:29]
	v_mfma_f32_16x16x32_bf16 v[14:17], v[172:175], v[212:215], v[14:17]
	v_mfma_f32_16x16x32_bf16 v[10:13], v[180:183], v[212:215], v[10:13]
	v_mfma_f32_16x16x32_bf16 v[62:65], v[176:179], v[192:195], v[62:65]
	v_mfma_f32_16x16x32_bf16 v[58:61], v[184:187], v[192:195], v[58:61]
	v_mfma_f32_16x16x32_bf16 v[46:49], v[176:179], v[200:203], v[46:49]
	v_mfma_f32_16x16x32_bf16 v[42:45], v[184:187], v[200:203], v[42:45]
	v_mfma_f32_16x16x32_bf16 v[30:33], v[176:179], v[208:211], v[30:33]
	v_mfma_f32_16x16x32_bf16 v[26:29], v[184:187], v[208:211], v[26:29]
	v_mfma_f32_16x16x32_bf16 v[14:17], v[176:179], v[216:219], v[14:17]
	v_mfma_f32_16x16x32_bf16 v[10:13], v[184:187], v[216:219], v[10:13]
	s_setprio 0
	s_barrier
	s_add_i32 s15, s15, 2
	s_add_u32 s80, s80, 0x100
	s_addc_u32 s81, s81, 0
	s_add_u32 s30, s30, 0x100
	s_addc_u32 s14, s14, 0
	s_cmp_gt_u32 s15, 61
	s_cbranch_scc0 .LBB0_415
	s_and_b64 vcc, exec, s[64:65]
	s_cbranch_vccz .LBB0_418
	s_barrier

.LBB0_435:
	ds_read_b128 v[146:149], v141
	ds_read_b128 v[150:153], v141 offset:1024
	ds_read_b128 v[154:157], v141 offset:2048
	ds_read_b128 v[158:161], v141 offset:3072
	ds_read_b128 v[162:165], v142
	ds_read_b128 v[166:169], v142 offset:1024
	ds_read_b128 v[170:173], v142 offset:2048
	ds_read_b128 v[174:177], v142 offset:3072
	s_add_u32 s17, s78, 0xfff00080
	s_addc_u32 s20, s79, -1
	s_cmp_eq_u32 s16, 60
	s_cselect_b32 s81, s9, s20
	s_cselect_b32 s80, s67, s17
	s_cselect_b32 s77, s18, s15
	s_cselect_b32 s76, s95, s14
	s_mov_b32 m0, s96
	ds_read_b128 v[178:181], v143
	ds_read_b128 v[182:185], v143 offset:1024
	ds_read_b128 v[186:189], v143 offset:2048
	ds_read_b128 v[190:193], v143 offset:3072
	ds_read_b128 v[194:197], v143 offset:4096
	ds_read_b128 v[198:201], v143 offset:5120
	ds_read_b128 v[202:205], v143 offset:6144
	ds_read_b128 v[206:209], v143 offset:7168
	global_load_lds_dwordx4 v136, s[78:79]
	s_mov_b32 m0, s97
	s_nop 0
	global_load_lds_dwordx4 v138, s[78:79]
	s_waitcnt vmcnt(8)
	s_waitcnt lgkmcnt(0)
	s_barrier
	s_setprio 1
	s_waitcnt lgkmcnt(0)
	v_mfma_f32_16x16x32_bf16 v[34:37], v[146:149], v[178:181], v[34:37]
	v_mfma_f32_16x16x32_bf16 v[38:41], v[154:157], v[178:181], v[38:41]
	v_mfma_f32_16x16x32_bf16 v[18:21], v[146:149], v[186:189], v[18:21]
	v_mfma_f32_16x16x32_bf16 v[22:25], v[154:157], v[186:189], v[22:25]
	v_mfma_f32_16x16x32_bf16 v[10:13], v[146:149], v[194:197], v[10:13]
	v_mfma_f32_16x16x32_bf16 v[14:17], v[154:157], v[194:197], v[14:17]
	v_mfma_f32_16x16x32_bf16 v[2:5], v[146:149], v[202:205], v[2:5]
	v_mfma_f32_16x16x32_bf16 v[6:9], v[154:157], v[202:205], v[6:9]
	v_mfma_f32_16x16x32_bf16 v[34:37], v[150:153], v[182:185], v[34:37]
	v_mfma_f32_16x16x32_bf16 v[38:41], v[158:161], v[182:185], v[38:41]
	v_mfma_f32_16x16x32_bf16 v[18:21], v[150:153], v[190:193], v[18:21]
	v_mfma_f32_16x16x32_bf16 v[22:25], v[158:161], v[190:193], v[22:25]
	v_mfma_f32_16x16x32_bf16 v[10:13], v[150:153], v[198:201], v[10:13]
	v_mfma_f32_16x16x32_bf16 v[14:17], v[158:161], v[198:201], v[14:17]
	v_mfma_f32_16x16x32_bf16 v[2:5], v[150:153], v[206:209], v[2:5]
	v_mfma_f32_16x16x32_bf16 v[6:9], v[158:161], v[206:209], v[6:9]
	s_setprio 0
	s_setprio 1
	v_mfma_f32_16x16x32_bf16 v[66:69], v[162:165], v[178:181], v[66:69]
	v_mfma_f32_16x16x32_bf16 v[70:73], v[170:173], v[178:181], v[70:73]
	v_mfma_f32_16x16x32_bf16 v[54:57], v[162:165], v[186:189], v[54:57]
	v_mfma_f32_16x16x32_bf16 v[62:65], v[170:173], v[186:189], v[62:65]
	v_mfma_f32_16x16x32_bf16 v[42:45], v[162:165], v[194:197], v[42:45]
	v_mfma_f32_16x16x32_bf16 v[46:49], v[170:173], v[194:197], v[46:49]
	v_mfma_f32_16x16x32_bf16 v[26:29], v[162:165], v[202:205], v[26:29]
	v_mfma_f32_16x16x32_bf16 v[30:33], v[170:173], v[202:205], v[30:33]
	v_mfma_f32_16x16x32_bf16 v[66:69], v[166:169], v[182:185], v[66:69]
	v_mfma_f32_16x16x32_bf16 v[70:73], v[174:177], v[182:185], v[70:73]
	v_mfma_f32_16x16x32_bf16 v[54:57], v[166:169], v[190:193], v[54:57]
	v_mfma_f32_16x16x32_bf16 v[62:65], v[174:177], v[190:193], v[62:65]
	v_mfma_f32_16x16x32_bf16 v[42:45], v[166:169], v[198:201], v[42:45]
	v_mfma_f32_16x16x32_bf16 v[46:49], v[174:177], v[198:201], v[46:49]
	v_mfma_f32_16x16x32_bf16 v[26:29], v[166:169], v[206:209], v[26:29]
	v_mfma_f32_16x16x32_bf16 v[30:33], v[174:177], v[206:209], v[30:33]
	s_setprio 0
	s_barrier
	s_mov_b32 m0, vcc_lo
	s_mov_b64 s[98:99], s[76:77]
	s_add_u32 s20, s76, 0x100000
	ds_read_b128 v[178:181], v143 offset:16384
	ds_read_b128 v[182:185], v143 offset:17408
	ds_read_b128 v[186:189], v143 offset:18432
	ds_read_b128 v[190:193], v143 offset:19456
	ds_read_b128 v[194:197], v143 offset:20480
	ds_read_b128 v[198:201], v143 offset:21504
	ds_read_b128 v[202:205], v143 offset:22528
	ds_read_b128 v[206:209], v143 offset:23552
	global_load_lds_dwordx4 v132, s[76:77]
	s_mov_b32 m0, s84
	s_addc_u32 s21, s77, 0
	global_load_lds_dwordx4 v130, s[76:77]
	s_mov_b32 m0, s85
	s_mov_b64 s[100:101], s[80:81]
	global_load_lds_dwordx4 v132, s[20:21]
	s_mov_b32 m0, s46
	s_nop 0
	global_load_lds_dwordx4 v130, s[20:21]
	s_mov_b32 m0, s59
	s_nop 0
	global_load_lds_dwordx4 v132, s[80:81]
	s_mov_b32 m0, s82
	s_nop 0
	global_load_lds_dwordx4 v130, s[80:81]
	s_waitcnt vmcnt(8)
	s_waitcnt lgkmcnt(0)
	s_barrier
	s_setprio 1
	s_waitcnt lgkmcnt(0)
	v_mfma_f32_16x16x32_bf16 v[102:105], v[146:149], v[178:181], v[102:105]
	v_mfma_f32_16x16x32_bf16 v[110:113], v[154:157], v[178:181], v[110:113]
	v_mfma_f32_16x16x32_bf16 v[90:93], v[146:149], v[186:189], v[90:93]
	v_mfma_f32_16x16x32_bf16 v[94:97], v[154:157], v[186:189], v[94:97]
	v_mfma_f32_16x16x32_bf16 v[74:77], v[146:149], v[194:197], v[74:77]
	v_mfma_f32_16x16x32_bf16 v[78:81], v[154:157], v[194:197], v[78:81]
	v_mfma_f32_16x16x32_bf16 v[50:53], v[146:149], v[202:205], v[50:53]
	v_mfma_f32_16x16x32_bf16 v[58:61], v[154:157], v[202:205], v[58:61]
	v_mfma_f32_16x16x32_bf16 v[102:105], v[150:153], v[182:185], v[102:105]
	v_mfma_f32_16x16x32_bf16 v[110:113], v[158:161], v[182:185], v[110:113]
	v_mfma_f32_16x16x32_bf16 v[90:93], v[150:153], v[190:193], v[90:93]
	v_mfma_f32_16x16x32_bf16 v[94:97], v[158:161], v[190:193], v[94:97]
	v_mfma_f32_16x16x32_bf16 v[74:77], v[150:153], v[198:201], v[74:77]
	v_mfma_f32_16x16x32_bf16 v[78:81], v[158:161], v[198:201], v[78:81]
	v_mfma_f32_16x16x32_bf16 v[50:53], v[150:153], v[206:209], v[50:53]
	v_mfma_f32_16x16x32_bf16 v[58:61], v[158:161], v[206:209], v[58:61]
	s_setprio 0
	s_setprio 1
	v_mfma_f32_16x16x32_bf16 v[122:125], v[162:165], v[178:181], v[122:125]
	v_mfma_f32_16x16x32_bf16 v[126:129], v[170:173], v[178:181], v[126:129]
	v_mfma_f32_16x16x32_bf16 v[114:117], v[162:165], v[186:189], v[114:117]
	v_mfma_f32_16x16x32_bf16 v[118:121], v[170:173], v[186:189], v[118:121]
	v_mfma_f32_16x16x32_bf16 v[98:101], v[162:165], v[194:197], v[98:101]
	v_mfma_f32_16x16x32_bf16 v[106:109], v[170:173], v[194:197], v[106:109]
	v_mfma_f32_16x16x32_bf16 v[82:85], v[162:165], v[202:205], v[82:85]
	v_mfma_f32_16x16x32_bf16 v[86:89], v[170:173], v[202:205], v[86:89]
	v_mfma_f32_16x16x32_bf16 v[122:125], v[166:169], v[182:185], v[122:125]
	v_mfma_f32_16x16x32_bf16 v[126:129], v[174:177], v[182:185], v[126:129]
	v_mfma_f32_16x16x32_bf16 v[114:117], v[166:169], v[190:193], v[114:117]
	v_mfma_f32_16x16x32_bf16 v[118:121], v[174:177], v[190:193], v[118:121]
	v_mfma_f32_16x16x32_bf16 v[98:101], v[166:169], v[198:201], v[98:101]
	v_mfma_f32_16x16x32_bf16 v[106:109], v[174:177], v[198:201], v[106:109]
	v_mfma_f32_16x16x32_bf16 v[82:85], v[166:169], v[206:209], v[82:85]
	v_mfma_f32_16x16x32_bf16 v[86:89], v[174:177], v[206:209], v[86:89]
	s_setprio 0
	s_barrier
	ds_read_b128 v[146:149], v134
	ds_read_b128 v[150:153], v134 offset:1024
	ds_read_b128 v[154:157], v134 offset:2048
	ds_read_b128 v[158:161], v134 offset:3072
	ds_read_b128 v[162:165], v144
	ds_read_b128 v[166:169], v144 offset:1024
	ds_read_b128 v[170:173], v144 offset:2048
	ds_read_b128 v[174:177], v144 offset:3072
	s_add_u32 s20, s80, 0x100000
	s_addc_u32 s21, s81, 0
	s_mov_b32 m0, s83
	ds_read_b128 v[178:181], v143 offset:32768
	ds_read_b128 v[182:185], v143 offset:33792
	ds_read_b128 v[186:189], v143 offset:34816
	ds_read_b128 v[190:193], v143 offset:35840
	ds_read_b128 v[194:197], v143 offset:36864
	ds_read_b128 v[198:201], v143 offset:37888
	ds_read_b128 v[202:205], v143 offset:38912
	ds_read_b128 v[206:209], v143 offset:39936
	global_load_lds_dwordx4 v132, s[20:21]
	s_mov_b32 m0, s86
	s_nop 0
	global_load_lds_dwordx4 v130, s[20:21]
	s_waitcnt vmcnt(8)
	s_waitcnt lgkmcnt(0)
	s_barrier
	s_setprio 1
	s_waitcnt lgkmcnt(0)
	v_mfma_f32_16x16x32_bf16 v[34:37], v[146:149], v[178:181], v[34:37]
	v_mfma_f32_16x16x32_bf16 v[38:41], v[154:157], v[178:181], v[38:41]
	v_mfma_f32_16x16x32_bf16 v[18:21], v[146:149], v[186:189], v[18:21]
	v_mfma_f32_16x16x32_bf16 v[22:25], v[154:157], v[186:189], v[22:25]
	v_mfma_f32_16x16x32_bf16 v[10:13], v[146:149], v[194:197], v[10:13]
	v_mfma_f32_16x16x32_bf16 v[14:17], v[154:157], v[194:197], v[14:17]
	v_mfma_f32_16x16x32_bf16 v[2:5], v[146:149], v[202:205], v[2:5]
	v_mfma_f32_16x16x32_bf16 v[6:9], v[154:157], v[202:205], v[6:9]
	v_mfma_f32_16x16x32_bf16 v[34:37], v[150:153], v[182:185], v[34:37]
	v_mfma_f32_16x16x32_bf16 v[38:41], v[158:161], v[182:185], v[38:41]
	v_mfma_f32_16x16x32_bf16 v[18:21], v[150:153], v[190:193], v[18:21]
	v_mfma_f32_16x16x32_bf16 v[22:25], v[158:161], v[190:193], v[22:25]
	v_mfma_f32_16x16x32_bf16 v[10:13], v[150:153], v[198:201], v[10:13]
	v_mfma_f32_16x16x32_bf16 v[14:17], v[158:161], v[198:201], v[14:17]
	v_mfma_f32_16x16x32_bf16 v[2:5], v[150:153], v[206:209], v[2:5]
	v_mfma_f32_16x16x32_bf16 v[6:9], v[158:161], v[206:209], v[6:9]
	s_setprio 0
	s_setprio 1
	v_mfma_f32_16x16x32_bf16 v[66:69], v[162:165], v[178:181], v[66:69]
	v_mfma_f32_16x16x32_bf16 v[70:73], v[170:173], v[178:181], v[70:73]
	v_mfma_f32_16x16x32_bf16 v[54:57], v[162:165], v[186:189], v[54:57]
	v_mfma_f32_16x16x32_bf16 v[62:65], v[170:173], v[186:189], v[62:65]
	v_mfma_f32_16x16x32_bf16 v[42:45], v[162:165], v[194:197], v[42:45]
	v_mfma_f32_16x16x32_bf16 v[46:49], v[170:173], v[194:197], v[46:49]
	v_mfma_f32_16x16x32_bf16 v[26:29], v[162:165], v[202:205], v[26:29]
	v_mfma_f32_16x16x32_bf16 v[30:33], v[170:173], v[202:205], v[30:33]
	v_mfma_f32_16x16x32_bf16 v[66:69], v[166:169], v[182:185], v[66:69]
	v_mfma_f32_16x16x32_bf16 v[70:73], v[174:177], v[182:185], v[70:73]
	v_mfma_f32_16x16x32_bf16 v[54:57], v[166:169], v[190:193], v[54:57]
	v_mfma_f32_16x16x32_bf16 v[62:65], v[174:177], v[190:193], v[62:65]
	v_mfma_f32_16x16x32_bf16 v[42:45], v[166:169], v[198:201], v[42:45]
	v_mfma_f32_16x16x32_bf16 v[46:49], v[174:177], v[198:201], v[46:49]
	v_mfma_f32_16x16x32_bf16 v[26:29], v[166:169], v[206:209], v[26:29]
	v_mfma_f32_16x16x32_bf16 v[30:33], v[174:177], v[206:209], v[30:33]
	s_setprio 0
	s_barrier
	s_mov_b32 m0, s47
	s_add_u32 s98, s98, 0x80
	s_addc_u32 s99, s99, 0
	s_add_u32 s100, s100, 0x80
	s_addc_u32 s101, s101, 0
	s_add_u32 s20, s76, 0x100080
	ds_read_b128 v[178:181], v143 offset:49152
	ds_read_b128 v[182:185], v143 offset:50176
	ds_read_b128 v[186:189], v143 offset:51200
	ds_read_b128 v[190:193], v143 offset:52224
	ds_read_b128 v[194:197], v143 offset:53248
	ds_read_b128 v[198:201], v143 offset:54272
	ds_read_b128 v[202:205], v143 offset:55296
	ds_read_b128 v[206:209], v143 offset:56320
	global_load_lds_dwordx4 v132, s[98:99]
	s_mov_b32 m0, vcc_hi
	s_addc_u32 s21, s77, 0
	global_load_lds_dwordx4 v130, s[98:99]
	s_mov_b32 m0, s56
	s_nop 0
	global_load_lds_dwordx4 v132, s[20:21]
	s_mov_b32 m0, s57
	s_nop 0
	global_load_lds_dwordx4 v130, s[20:21]
	s_mov_b32 m0, s88
	s_nop 0
	global_load_lds_dwordx4 v132, s[100:101]
	s_mov_b32 m0, s89
	s_nop 0
	global_load_lds_dwordx4 v130, s[100:101]
	s_waitcnt vmcnt(8)
	s_waitcnt lgkmcnt(0)
	s_barrier
	s_setprio 1
	s_waitcnt lgkmcnt(0)
	v_mfma_f32_16x16x32_bf16 v[102:105], v[146:149], v[178:181], v[102:105]
	v_mfma_f32_16x16x32_bf16 v[110:113], v[154:157], v[178:181], v[110:113]
	v_mfma_f32_16x16x32_bf16 v[90:93], v[146:149], v[186:189], v[90:93]
	v_mfma_f32_16x16x32_bf16 v[94:97], v[154:157], v[186:189], v[94:97]
	v_mfma_f32_16x16x32_bf16 v[74:77], v[146:149], v[194:197], v[74:77]
	v_mfma_f32_16x16x32_bf16 v[78:81], v[154:157], v[194:197], v[78:81]
	v_mfma_f32_16x16x32_bf16 v[50:53], v[146:149], v[202:205], v[50:53]
	v_mfma_f32_16x16x32_bf16 v[58:61], v[154:157], v[202:205], v[58:61]
	v_mfma_f32_16x16x32_bf16 v[102:105], v[150:153], v[182:185], v[102:105]
	v_mfma_f32_16x16x32_bf16 v[110:113], v[158:161], v[182:185], v[110:113]
	v_mfma_f32_16x16x32_bf16 v[90:93], v[150:153], v[190:193], v[90:93]
	v_mfma_f32_16x16x32_bf16 v[94:97], v[158:161], v[190:193], v[94:97]
	v_mfma_f32_16x16x32_bf16 v[74:77], v[150:153], v[198:201], v[74:77]
	v_mfma_f32_16x16x32_bf16 v[78:81], v[158:161], v[198:201], v[78:81]
	v_mfma_f32_16x16x32_bf16 v[50:53], v[150:153], v[206:209], v[50:53]
	v_mfma_f32_16x16x32_bf16 v[58:61], v[158:161], v[206:209], v[58:61]
	s_setprio 0
	s_setprio 1
	v_mfma_f32_16x16x32_bf16 v[122:125], v[162:165], v[178:181], v[122:125]
	v_mfma_f32_16x16x32_bf16 v[126:129], v[170:173], v[178:181], v[126:129]
	v_mfma_f32_16x16x32_bf16 v[114:117], v[162:165], v[186:189], v[114:117]
	v_mfma_f32_16x16x32_bf16 v[118:121], v[170:173], v[186:189], v[118:121]
	v_mfma_f32_16x16x32_bf16 v[98:101], v[162:165], v[194:197], v[98:101]
	v_mfma_f32_16x16x32_bf16 v[106:109], v[170:173], v[194:197], v[106:109]
	v_mfma_f32_16x16x32_bf16 v[82:85], v[162:165], v[202:205], v[82:85]
	v_mfma_f32_16x16x32_bf16 v[86:89], v[170:173], v[202:205], v[86:89]
	v_mfma_f32_16x16x32_bf16 v[122:125], v[166:169], v[182:185], v[122:125]
	v_mfma_f32_16x16x32_bf16 v[126:129], v[174:177], v[182:185], v[126:129]
	v_mfma_f32_16x16x32_bf16 v[114:117], v[166:169], v[190:193], v[114:117]
	v_mfma_f32_16x16x32_bf16 v[118:121], v[174:177], v[190:193], v[118:121]
	v_mfma_f32_16x16x32_bf16 v[98:101], v[166:169], v[198:201], v[98:101]
	v_mfma_f32_16x16x32_bf16 v[106:109], v[174:177], v[198:201], v[106:109]
	v_mfma_f32_16x16x32_bf16 v[82:85], v[166:169], v[206:209], v[82:85]
	v_mfma_f32_16x16x32_bf16 v[86:89], v[174:177], v[206:209], v[86:89]
	s_setprio 0
	s_barrier
	s_add_i32 s16, s16, 2
	s_add_u32 s78, s78, 0x100
	s_addc_u32 s79, s79, 0
	s_add_u32 s14, s14, 0x100
	s_addc_u32 s15, s15, 0
	s_cmp_gt_u32 s16, 61
	s_cbranch_scc0 .LBB0_435
	s_and_b64 vcc, exec, s[30:31]
	s_cbranch_vccz .LBB0_438
	s_barrier

.LBB0_644:
	ds_read_b128 v[146:149], v1
	ds_read_b128 v[154:157], v1 offset:1024
	ds_read_b128 v[158:161], v1 offset:2048
	ds_read_b128 v[162:165], v1 offset:3072
	ds_read_b128 v[166:169], v150
	ds_read_b128 v[170:173], v150 offset:1024
	ds_read_b128 v[174:177], v150 offset:2048
	ds_read_b128 v[178:181], v150 offset:3072
	s_add_u32 s27, s62, 0xfffc0080
	s_addc_u32 s46, s63, -1
	s_cmp_eq_u32 s26, 12
	s_cselect_b32 s65, s23, s46
	s_cselect_b32 s64, s83, s27
	s_cselect_b32 s55, s0, s15
	s_cselect_b32 s54, s86, s14
	s_mov_b32 m0, s69
	ds_read_b128 v[182:185], v151
	ds_read_b128 v[186:189], v151 offset:1024
	ds_read_b128 v[190:193], v151 offset:2048
	ds_read_b128 v[194:197], v151 offset:3072
	ds_read_b128 v[198:201], v151 offset:4096
	ds_read_b128 v[202:205], v151 offset:5120
	ds_read_b128 v[206:209], v151 offset:6144
	ds_read_b128 v[210:213], v151 offset:7168
	global_load_lds_dwordx4 v138, s[62:63]
	s_mov_b32 m0, s70
	s_nop 0
	global_load_lds_dwordx4 v140, s[62:63]
	s_waitcnt vmcnt(8)
	s_waitcnt lgkmcnt(0)
	s_barrier
	s_setprio 1
	s_waitcnt lgkmcnt(0)
	v_mfma_f32_16x16x32_bf16 v[122:125], v[146:149], v[182:185], v[122:125]
	v_mfma_f32_16x16x32_bf16 v[114:117], v[158:161], v[182:185], v[114:117]
	v_mfma_f32_16x16x32_bf16 v[106:109], v[146:149], v[190:193], v[106:109]
	v_mfma_f32_16x16x32_bf16 v[98:101], v[158:161], v[190:193], v[98:101]
	v_mfma_f32_16x16x32_bf16 v[90:93], v[146:149], v[198:201], v[90:93]
	v_mfma_f32_16x16x32_bf16 v[82:85], v[158:161], v[198:201], v[82:85]
	v_mfma_f32_16x16x32_bf16 v[58:61], v[146:149], v[206:209], v[58:61]
	v_mfma_f32_16x16x32_bf16 v[50:53], v[158:161], v[206:209], v[50:53]
	v_mfma_f32_16x16x32_bf16 v[122:125], v[154:157], v[186:189], v[122:125]
	v_mfma_f32_16x16x32_bf16 v[114:117], v[162:165], v[186:189], v[114:117]
	v_mfma_f32_16x16x32_bf16 v[106:109], v[154:157], v[194:197], v[106:109]
	v_mfma_f32_16x16x32_bf16 v[98:101], v[162:165], v[194:197], v[98:101]
	v_mfma_f32_16x16x32_bf16 v[90:93], v[154:157], v[202:205], v[90:93]
	v_mfma_f32_16x16x32_bf16 v[82:85], v[162:165], v[202:205], v[82:85]
	v_mfma_f32_16x16x32_bf16 v[58:61], v[154:157], v[210:213], v[58:61]
	v_mfma_f32_16x16x32_bf16 v[50:53], v[162:165], v[210:213], v[50:53]
	s_setprio 0
	s_setprio 1
	v_mfma_f32_16x16x32_bf16 v[126:129], v[166:169], v[182:185], v[126:129]
	v_mfma_f32_16x16x32_bf16 v[118:121], v[174:177], v[182:185], v[118:121]
	v_mfma_f32_16x16x32_bf16 v[110:113], v[166:169], v[190:193], v[110:113]
	v_mfma_f32_16x16x32_bf16 v[102:105], v[174:177], v[190:193], v[102:105]
	v_mfma_f32_16x16x32_bf16 v[94:97], v[166:169], v[198:201], v[94:97]
	v_mfma_f32_16x16x32_bf16 v[86:89], v[174:177], v[198:201], v[86:89]
	v_mfma_f32_16x16x32_bf16 v[62:65], v[166:169], v[206:209], v[62:65]
	v_mfma_f32_16x16x32_bf16 v[54:57], v[174:177], v[206:209], v[54:57]
	v_mfma_f32_16x16x32_bf16 v[126:129], v[170:173], v[186:189], v[126:129]
	v_mfma_f32_16x16x32_bf16 v[118:121], v[178:181], v[186:189], v[118:121]
	v_mfma_f32_16x16x32_bf16 v[110:113], v[170:173], v[194:197], v[110:113]
	v_mfma_f32_16x16x32_bf16 v[102:105], v[178:181], v[194:197], v[102:105]
	v_mfma_f32_16x16x32_bf16 v[94:97], v[170:173], v[202:205], v[94:97]
	v_mfma_f32_16x16x32_bf16 v[86:89], v[178:181], v[202:205], v[86:89]
	v_mfma_f32_16x16x32_bf16 v[62:65], v[170:173], v[210:213], v[62:65]
	v_mfma_f32_16x16x32_bf16 v[54:57], v[178:181], v[210:213], v[54:57]
	s_setprio 0
	s_barrier
	s_mov_b32 m0, s72
	s_mov_b64 s[98:99], s[54:55]
	s_add_u32 s46, s54, 0x40000
	ds_read_b128 v[182:185], v151 offset:16384
	ds_read_b128 v[186:189], v151 offset:17408
	ds_read_b128 v[190:193], v151 offset:18432
	ds_read_b128 v[194:197], v151 offset:19456
	ds_read_b128 v[198:201], v151 offset:20480
	ds_read_b128 v[202:205], v151 offset:21504
	ds_read_b128 v[206:209], v151 offset:22528
	ds_read_b128 v[210:213], v151 offset:23552
	global_load_lds_dwordx4 v134, s[54:55]
	s_mov_b32 m0, s73
	s_addc_u32 s47, s55, 0
	global_load_lds_dwordx4 v130, s[54:55]
	s_mov_b32 m0, s74
	s_mov_b64 s[100:101], s[64:65]
	global_load_lds_dwordx4 v134, s[46:47]
	s_mov_b32 m0, s75
	s_nop 0
	global_load_lds_dwordx4 v130, s[46:47]
	s_mov_b32 m0, s33
	s_nop 0
	global_load_lds_dwordx4 v136, s[64:65]
	s_mov_b32 m0, s41
	s_nop 0
	global_load_lds_dwordx4 v132, s[64:65]
	s_waitcnt vmcnt(8)
	s_waitcnt lgkmcnt(0)
	s_barrier
	s_setprio 1
	s_waitcnt lgkmcnt(0)
	v_mfma_f32_16x16x32_bf16 v[74:77], v[146:149], v[182:185], v[74:77]
	v_mfma_f32_16x16x32_bf16 v[66:69], v[158:161], v[182:185], v[66:69]
	v_mfma_f32_16x16x32_bf16 v[42:45], v[146:149], v[190:193], v[42:45]
	v_mfma_f32_16x16x32_bf16 v[34:37], v[158:161], v[190:193], v[34:37]
	v_mfma_f32_16x16x32_bf16 v[26:29], v[146:149], v[198:201], v[26:29]
	v_mfma_f32_16x16x32_bf16 v[18:21], v[158:161], v[198:201], v[18:21]
	v_mfma_f32_16x16x32_bf16 v[10:13], v[146:149], v[206:209], v[10:13]
	v_mfma_f32_16x16x32_bf16 v[2:5], v[158:161], v[206:209], v[2:5]
	v_mfma_f32_16x16x32_bf16 v[74:77], v[154:157], v[186:189], v[74:77]
	v_mfma_f32_16x16x32_bf16 v[66:69], v[162:165], v[186:189], v[66:69]
	v_mfma_f32_16x16x32_bf16 v[42:45], v[154:157], v[194:197], v[42:45]
	v_mfma_f32_16x16x32_bf16 v[34:37], v[162:165], v[194:197], v[34:37]
	v_mfma_f32_16x16x32_bf16 v[26:29], v[154:157], v[202:205], v[26:29]
	v_mfma_f32_16x16x32_bf16 v[18:21], v[162:165], v[202:205], v[18:21]
	v_mfma_f32_16x16x32_bf16 v[10:13], v[154:157], v[210:213], v[10:13]
	v_mfma_f32_16x16x32_bf16 v[2:5], v[162:165], v[210:213], v[2:5]
	s_setprio 0
	s_setprio 1
	v_mfma_f32_16x16x32_bf16 v[78:81], v[166:169], v[182:185], v[78:81]
	v_mfma_f32_16x16x32_bf16 v[70:73], v[174:177], v[182:185], v[70:73]
	v_mfma_f32_16x16x32_bf16 v[46:49], v[166:169], v[190:193], v[46:49]
	v_mfma_f32_16x16x32_bf16 v[38:41], v[174:177], v[190:193], v[38:41]
	v_mfma_f32_16x16x32_bf16 v[30:33], v[166:169], v[198:201], v[30:33]
	v_mfma_f32_16x16x32_bf16 v[22:25], v[174:177], v[198:201], v[22:25]
	v_mfma_f32_16x16x32_bf16 v[14:17], v[166:169], v[206:209], v[14:17]
	v_mfma_f32_16x16x32_bf16 v[6:9], v[174:177], v[206:209], v[6:9]
	v_mfma_f32_16x16x32_bf16 v[78:81], v[170:173], v[186:189], v[78:81]
	v_mfma_f32_16x16x32_bf16 v[70:73], v[178:181], v[186:189], v[70:73]
	v_mfma_f32_16x16x32_bf16 v[46:49], v[170:173], v[194:197], v[46:49]
	v_mfma_f32_16x16x32_bf16 v[38:41], v[178:181], v[194:197], v[38:41]
	v_mfma_f32_16x16x32_bf16 v[30:33], v[170:173], v[202:205], v[30:33]
	v_mfma_f32_16x16x32_bf16 v[22:25], v[178:181], v[202:205], v[22:25]
	v_mfma_f32_16x16x32_bf16 v[14:17], v[170:173], v[210:213], v[14:17]
	v_mfma_f32_16x16x32_bf16 v[6:9], v[178:181], v[210:213], v[6:9]
	s_setprio 0
	s_barrier
	ds_read_b128 v[146:149], v152
	ds_read_b128 v[154:157], v152 offset:1024
	ds_read_b128 v[158:161], v152 offset:2048
	ds_read_b128 v[162:165], v152 offset:3072
	ds_read_b128 v[166:169], v153
	ds_read_b128 v[170:173], v153 offset:1024
	ds_read_b128 v[174:177], v153 offset:2048
	ds_read_b128 v[178:181], v153 offset:3072
	s_add_u32 s46, s64, 0x40000
	s_addc_u32 s47, s65, 0
	s_mov_b32 m0, s58
	ds_read_b128 v[182:185], v151 offset:32768
	ds_read_b128 v[186:189], v151 offset:33792
	ds_read_b128 v[190:193], v151 offset:34816
	ds_read_b128 v[194:197], v151 offset:35840
	ds_read_b128 v[198:201], v151 offset:36864
	ds_read_b128 v[202:205], v151 offset:37888
	ds_read_b128 v[206:209], v151 offset:38912
	ds_read_b128 v[210:213], v151 offset:39936
	global_load_lds_dwordx4 v136, s[46:47]
	s_mov_b32 m0, s59
	s_nop 0
	global_load_lds_dwordx4 v132, s[46:47]
	s_waitcnt vmcnt(8)
	s_waitcnt lgkmcnt(0)
	s_barrier
	s_setprio 1
	s_waitcnt lgkmcnt(0)
	v_mfma_f32_16x16x32_bf16 v[122:125], v[146:149], v[182:185], v[122:125]
	v_mfma_f32_16x16x32_bf16 v[114:117], v[158:161], v[182:185], v[114:117]
	v_mfma_f32_16x16x32_bf16 v[106:109], v[146:149], v[190:193], v[106:109]
	v_mfma_f32_16x16x32_bf16 v[98:101], v[158:161], v[190:193], v[98:101]
	v_mfma_f32_16x16x32_bf16 v[90:93], v[146:149], v[198:201], v[90:93]
	v_mfma_f32_16x16x32_bf16 v[82:85], v[158:161], v[198:201], v[82:85]
	v_mfma_f32_16x16x32_bf16 v[58:61], v[146:149], v[206:209], v[58:61]
	v_mfma_f32_16x16x32_bf16 v[50:53], v[158:161], v[206:209], v[50:53]
	v_mfma_f32_16x16x32_bf16 v[122:125], v[154:157], v[186:189], v[122:125]
	v_mfma_f32_16x16x32_bf16 v[114:117], v[162:165], v[186:189], v[114:117]
	v_mfma_f32_16x16x32_bf16 v[106:109], v[154:157], v[194:197], v[106:109]
	v_mfma_f32_16x16x32_bf16 v[98:101], v[162:165], v[194:197], v[98:101]
	v_mfma_f32_16x16x32_bf16 v[90:93], v[154:157], v[202:205], v[90:93]
	v_mfma_f32_16x16x32_bf16 v[82:85], v[162:165], v[202:205], v[82:85]
	v_mfma_f32_16x16x32_bf16 v[58:61], v[154:157], v[210:213], v[58:61]
	v_mfma_f32_16x16x32_bf16 v[50:53], v[162:165], v[210:213], v[50:53]
	s_setprio 0
	s_setprio 1
	v_mfma_f32_16x16x32_bf16 v[126:129], v[166:169], v[182:185], v[126:129]
	v_mfma_f32_16x16x32_bf16 v[118:121], v[174:177], v[182:185], v[118:121]
	v_mfma_f32_16x16x32_bf16 v[110:113], v[166:169], v[190:193], v[110:113]
	v_mfma_f32_16x16x32_bf16 v[102:105], v[174:177], v[190:193], v[102:105]
	v_mfma_f32_16x16x32_bf16 v[94:97], v[166:169], v[198:201], v[94:97]
	v_mfma_f32_16x16x32_bf16 v[86:89], v[174:177], v[198:201], v[86:89]
	v_mfma_f32_16x16x32_bf16 v[62:65], v[166:169], v[206:209], v[62:65]
	v_mfma_f32_16x16x32_bf16 v[54:57], v[174:177], v[206:209], v[54:57]
	v_mfma_f32_16x16x32_bf16 v[126:129], v[170:173], v[186:189], v[126:129]
	v_mfma_f32_16x16x32_bf16 v[118:121], v[178:181], v[186:189], v[118:121]
	v_mfma_f32_16x16x32_bf16 v[110:113], v[170:173], v[194:197], v[110:113]
	v_mfma_f32_16x16x32_bf16 v[102:105], v[178:181], v[194:197], v[102:105]
	v_mfma_f32_16x16x32_bf16 v[94:97], v[170:173], v[202:205], v[94:97]
	v_mfma_f32_16x16x32_bf16 v[86:89], v[178:181], v[202:205], v[86:89]
	v_mfma_f32_16x16x32_bf16 v[62:65], v[170:173], v[210:213], v[62:65]
	v_mfma_f32_16x16x32_bf16 v[54:57], v[178:181], v[210:213], v[54:57]
	s_setprio 0
	s_barrier
	s_mov_b32 m0, s76
	s_add_u32 s98, s98, 0x80
	s_addc_u32 s99, s99, 0
	s_add_u32 s100, s100, 0x80
	s_addc_u32 s101, s101, 0
	s_add_u32 s46, s54, 0x40080
	ds_read_b128 v[182:185], v151 offset:49152
	ds_read_b128 v[186:189], v151 offset:50176
	ds_read_b128 v[190:193], v151 offset:51200
	ds_read_b128 v[194:197], v151 offset:52224
	ds_read_b128 v[198:201], v151 offset:53248
	ds_read_b128 v[202:205], v151 offset:54272
	ds_read_b128 v[206:209], v151 offset:55296
	ds_read_b128 v[210:213], v151 offset:56320
	global_load_lds_dwordx4 v134, s[98:99]
	s_mov_b32 m0, s77
	s_addc_u32 s47, s55, 0
	global_load_lds_dwordx4 v130, s[98:99]
	s_mov_b32 m0, s78
	s_nop 0
	global_load_lds_dwordx4 v134, s[46:47]
	s_mov_b32 m0, s79
	s_nop 0
	global_load_lds_dwordx4 v130, s[46:47]
	s_mov_b32 m0, s66
	s_nop 0
	global_load_lds_dwordx4 v136, s[100:101]
	s_mov_b32 m0, s67
	s_nop 0
	global_load_lds_dwordx4 v132, s[100:101]
	s_waitcnt vmcnt(8)
	s_waitcnt lgkmcnt(0)
	s_barrier
	s_setprio 1
	s_waitcnt lgkmcnt(0)
	v_mfma_f32_16x16x32_bf16 v[74:77], v[146:149], v[182:185], v[74:77]
	v_mfma_f32_16x16x32_bf16 v[66:69], v[158:161], v[182:185], v[66:69]
	v_mfma_f32_16x16x32_bf16 v[42:45], v[146:149], v[190:193], v[42:45]
	v_mfma_f32_16x16x32_bf16 v[34:37], v[158:161], v[190:193], v[34:37]
	v_mfma_f32_16x16x32_bf16 v[26:29], v[146:149], v[198:201], v[26:29]
	v_mfma_f32_16x16x32_bf16 v[18:21], v[158:161], v[198:201], v[18:21]
	v_mfma_f32_16x16x32_bf16 v[10:13], v[146:149], v[206:209], v[10:13]
	v_mfma_f32_16x16x32_bf16 v[2:5], v[158:161], v[206:209], v[2:5]
	v_mfma_f32_16x16x32_bf16 v[74:77], v[154:157], v[186:189], v[74:77]
	v_mfma_f32_16x16x32_bf16 v[66:69], v[162:165], v[186:189], v[66:69]
	v_mfma_f32_16x16x32_bf16 v[42:45], v[154:157], v[194:197], v[42:45]
	v_mfma_f32_16x16x32_bf16 v[34:37], v[162:165], v[194:197], v[34:37]
	v_mfma_f32_16x16x32_bf16 v[26:29], v[154:157], v[202:205], v[26:29]
	v_mfma_f32_16x16x32_bf16 v[18:21], v[162:165], v[202:205], v[18:21]
	v_mfma_f32_16x16x32_bf16 v[10:13], v[154:157], v[210:213], v[10:13]
	v_mfma_f32_16x16x32_bf16 v[2:5], v[162:165], v[210:213], v[2:5]
	s_setprio 0
	s_setprio 1
	v_mfma_f32_16x16x32_bf16 v[78:81], v[166:169], v[182:185], v[78:81]
	v_mfma_f32_16x16x32_bf16 v[70:73], v[174:177], v[182:185], v[70:73]
	v_mfma_f32_16x16x32_bf16 v[46:49], v[166:169], v[190:193], v[46:49]
	v_mfma_f32_16x16x32_bf16 v[38:41], v[174:177], v[190:193], v[38:41]
	v_mfma_f32_16x16x32_bf16 v[30:33], v[166:169], v[198:201], v[30:33]
	v_mfma_f32_16x16x32_bf16 v[22:25], v[174:177], v[198:201], v[22:25]
	v_mfma_f32_16x16x32_bf16 v[14:17], v[166:169], v[206:209], v[14:17]
	v_mfma_f32_16x16x32_bf16 v[6:9], v[174:177], v[206:209], v[6:9]
	v_mfma_f32_16x16x32_bf16 v[78:81], v[170:173], v[186:189], v[78:81]
	v_mfma_f32_16x16x32_bf16 v[70:73], v[178:181], v[186:189], v[70:73]
	v_mfma_f32_16x16x32_bf16 v[46:49], v[170:173], v[194:197], v[46:49]
	v_mfma_f32_16x16x32_bf16 v[38:41], v[178:181], v[194:197], v[38:41]
	v_mfma_f32_16x16x32_bf16 v[30:33], v[170:173], v[202:205], v[30:33]
	v_mfma_f32_16x16x32_bf16 v[22:25], v[178:181], v[202:205], v[22:25]
	v_mfma_f32_16x16x32_bf16 v[14:17], v[170:173], v[210:213], v[14:17]
	v_mfma_f32_16x16x32_bf16 v[6:9], v[178:181], v[210:213], v[6:9]
	s_setprio 0
	s_barrier
	s_add_i32 s26, s26, 2
	s_add_u32 s62, s62, 0x100
	s_addc_u32 s63, s63, 0
	s_add_u32 s14, s14, 0x100
	s_addc_u32 s15, s15, 0
	s_cmp_gt_u32 s26, 13
	s_cbranch_scc0 .LBB0_644
	s_and_b64 vcc, exec, s[16:17]
	s_cbranch_vccz .LBB0_647
	s_barrier

.LBB0_670:
	ds_read_b128 v[132:135], v158
	ds_read_b128 v[154:157], v158 offset:1024
	ds_read_b128 v[162:165], v158 offset:2048
	ds_read_b128 v[166:169], v158 offset:3072
	ds_read_b128 v[170:173], v159
	ds_read_b128 v[174:177], v159 offset:1024
	ds_read_b128 v[178:181], v159 offset:2048
	ds_read_b128 v[182:185], v159 offset:3072
	s_add_u32 s6, s64, 0xfffe0080
	s_addc_u32 s7, s65, -1
	s_cmp_eq_u32 s26, 4
	s_cselect_b32 s67, s29, s7
	s_cselect_b32 s66, s79, s6
	s_cselect_b32 s7, s0, s15
	s_cselect_b32 s6, s80, s14
	s_mov_b32 m0, s81
	ds_read_b128 v[186:189], v160
	ds_read_b128 v[190:193], v160 offset:1024
	ds_read_b128 v[194:197], v160 offset:2048
	ds_read_b128 v[198:201], v160 offset:3072
	ds_read_b128 v[202:205], v160 offset:4096
	ds_read_b128 v[206:209], v160 offset:5120
	ds_read_b128 v[210:213], v160 offset:6144
	ds_read_b128 v[214:217], v160 offset:7168
	global_load_lds_dwordx4 v146, s[64:65]
	s_mov_b32 m0, s82
	s_nop 0
	global_load_lds_dwordx4 v148, s[64:65]
	s_waitcnt vmcnt(8)
	s_waitcnt lgkmcnt(0)
	s_barrier
	s_setprio 1
	s_waitcnt lgkmcnt(0)
	v_mfma_f32_16x16x32_bf16 v[118:121], v[132:135], v[186:189], v[118:121]
	v_mfma_f32_16x16x32_bf16 v[114:117], v[162:165], v[186:189], v[114:117]
	v_mfma_f32_16x16x32_bf16 v[110:113], v[132:135], v[194:197], v[110:113]
	v_mfma_f32_16x16x32_bf16 v[98:101], v[162:165], v[194:197], v[98:101]
	v_mfma_f32_16x16x32_bf16 v[94:97], v[132:135], v[202:205], v[94:97]
	v_mfma_f32_16x16x32_bf16 v[90:93], v[162:165], v[202:205], v[90:93]
	v_mfma_f32_16x16x32_bf16 v[78:81], v[132:135], v[210:213], v[78:81]
	v_mfma_f32_16x16x32_bf16 v[70:73], v[162:165], v[210:213], v[70:73]
	v_mfma_f32_16x16x32_bf16 v[118:121], v[154:157], v[190:193], v[118:121]
	v_mfma_f32_16x16x32_bf16 v[114:117], v[166:169], v[190:193], v[114:117]
	v_mfma_f32_16x16x32_bf16 v[110:113], v[154:157], v[198:201], v[110:113]
	v_mfma_f32_16x16x32_bf16 v[98:101], v[166:169], v[198:201], v[98:101]
	v_mfma_f32_16x16x32_bf16 v[94:97], v[154:157], v[206:209], v[94:97]
	v_mfma_f32_16x16x32_bf16 v[90:93], v[166:169], v[206:209], v[90:93]
	v_mfma_f32_16x16x32_bf16 v[78:81], v[154:157], v[214:217], v[78:81]
	v_mfma_f32_16x16x32_bf16 v[70:73], v[166:169], v[214:217], v[70:73]
	s_setprio 0
	s_setprio 1
	v_mfma_f32_16x16x32_bf16 v[126:129], v[170:173], v[186:189], v[126:129]
	v_mfma_f32_16x16x32_bf16 v[122:125], v[178:181], v[186:189], v[122:125]
	v_mfma_f32_16x16x32_bf16 v[106:109], v[170:173], v[194:197], v[106:109]
	v_mfma_f32_16x16x32_bf16 v[102:105], v[178:181], v[194:197], v[102:105]
	v_mfma_f32_16x16x32_bf16 v[86:89], v[170:173], v[202:205], v[86:89]
	v_mfma_f32_16x16x32_bf16 v[82:85], v[178:181], v[202:205], v[82:85]
	v_mfma_f32_16x16x32_bf16 v[62:65], v[170:173], v[210:213], v[62:65]
	v_mfma_f32_16x16x32_bf16 v[58:61], v[178:181], v[210:213], v[58:61]
	v_mfma_f32_16x16x32_bf16 v[126:129], v[174:177], v[190:193], v[126:129]
	v_mfma_f32_16x16x32_bf16 v[122:125], v[182:185], v[190:193], v[122:125]
	v_mfma_f32_16x16x32_bf16 v[106:109], v[174:177], v[198:201], v[106:109]
	v_mfma_f32_16x16x32_bf16 v[102:105], v[182:185], v[198:201], v[102:105]
	v_mfma_f32_16x16x32_bf16 v[86:89], v[174:177], v[206:209], v[86:89]
	v_mfma_f32_16x16x32_bf16 v[82:85], v[182:185], v[206:209], v[82:85]
	v_mfma_f32_16x16x32_bf16 v[62:65], v[174:177], v[214:217], v[62:65]
	v_mfma_f32_16x16x32_bf16 v[58:61], v[182:185], v[214:217], v[58:61]
	s_setprio 0
	s_barrier
	s_mov_b32 m0, s83
	s_mov_b64 s[98:99], s[6:7]
	s_add_u32 s88, s6, 0x20000
	ds_read_b128 v[186:189], v160 offset:16384
	ds_read_b128 v[190:193], v160 offset:17408
	ds_read_b128 v[194:197], v160 offset:18432
	ds_read_b128 v[198:201], v160 offset:19456
	ds_read_b128 v[202:205], v160 offset:20480
	ds_read_b128 v[206:209], v160 offset:21504
	ds_read_b128 v[210:213], v160 offset:22528
	ds_read_b128 v[214:217], v160 offset:23552
	global_load_lds_dwordx4 v140, s[6:7]
	s_mov_b32 m0, s84
	s_addc_u32 s89, s7, 0
	global_load_lds_dwordx4 v144, s[6:7]
	s_mov_b32 m0, s85
	s_mov_b64 s[100:101], s[66:67]
	global_load_lds_dwordx4 v140, s[88:89]
	s_mov_b32 m0, s46
	s_nop 0
	global_load_lds_dwordx4 v144, s[88:89]
	s_mov_b32 m0, s58
	s_nop 0
	global_load_lds_dwordx4 v138, s[66:67]
	s_mov_b32 m0, s59
	s_nop 0
	global_load_lds_dwordx4 v142, s[66:67]
	s_waitcnt vmcnt(8)
	s_waitcnt lgkmcnt(0)
	s_barrier
	s_setprio 1
	s_waitcnt lgkmcnt(0)
	v_mfma_f32_16x16x32_bf16 v[74:77], v[132:135], v[186:189], v[74:77]
	v_mfma_f32_16x16x32_bf16 v[66:69], v[162:165], v[186:189], v[66:69]
	v_mfma_f32_16x16x32_bf16 v[46:49], v[132:135], v[194:197], v[46:49]
	v_mfma_f32_16x16x32_bf16 v[42:45], v[162:165], v[194:197], v[42:45]
	v_mfma_f32_16x16x32_bf16 v[30:33], v[132:135], v[202:205], v[30:33]
	v_mfma_f32_16x16x32_bf16 v[26:29], v[162:165], v[202:205], v[26:29]
	v_mfma_f32_16x16x32_bf16 v[14:17], v[132:135], v[210:213], v[14:17]
	v_mfma_f32_16x16x32_bf16 v[10:13], v[162:165], v[210:213], v[10:13]
	v_mfma_f32_16x16x32_bf16 v[74:77], v[154:157], v[190:193], v[74:77]
	v_mfma_f32_16x16x32_bf16 v[66:69], v[166:169], v[190:193], v[66:69]
	v_mfma_f32_16x16x32_bf16 v[46:49], v[154:157], v[198:201], v[46:49]
	v_mfma_f32_16x16x32_bf16 v[42:45], v[166:169], v[198:201], v[42:45]
	v_mfma_f32_16x16x32_bf16 v[30:33], v[154:157], v[206:209], v[30:33]
	v_mfma_f32_16x16x32_bf16 v[26:29], v[166:169], v[206:209], v[26:29]
	v_mfma_f32_16x16x32_bf16 v[14:17], v[154:157], v[214:217], v[14:17]
	v_mfma_f32_16x16x32_bf16 v[10:13], v[166:169], v[214:217], v[10:13]
	s_setprio 0
	s_setprio 1
	v_mfma_f32_16x16x32_bf16 v[54:57], v[170:173], v[186:189], v[54:57]
	v_mfma_f32_16x16x32_bf16 v[50:53], v[178:181], v[186:189], v[50:53]
	v_mfma_f32_16x16x32_bf16 v[38:41], v[170:173], v[194:197], v[38:41]
	v_mfma_f32_16x16x32_bf16 v[34:37], v[178:181], v[194:197], v[34:37]
	v_mfma_f32_16x16x32_bf16 v[22:25], v[170:173], v[202:205], v[22:25]
	v_mfma_f32_16x16x32_bf16 v[18:21], v[178:181], v[202:205], v[18:21]
	v_mfma_f32_16x16x32_bf16 v[6:9], v[170:173], v[210:213], v[6:9]
	v_mfma_f32_16x16x32_bf16 v[2:5], v[178:181], v[210:213], v[2:5]
	v_mfma_f32_16x16x32_bf16 v[54:57], v[174:177], v[190:193], v[54:57]
	v_mfma_f32_16x16x32_bf16 v[50:53], v[182:185], v[190:193], v[50:53]
	v_mfma_f32_16x16x32_bf16 v[38:41], v[174:177], v[198:201], v[38:41]
	v_mfma_f32_16x16x32_bf16 v[34:37], v[182:185], v[198:201], v[34:37]
	v_mfma_f32_16x16x32_bf16 v[22:25], v[174:177], v[206:209], v[22:25]
	v_mfma_f32_16x16x32_bf16 v[18:21], v[182:185], v[206:209], v[18:21]
	v_mfma_f32_16x16x32_bf16 v[6:9], v[174:177], v[214:217], v[6:9]
	v_mfma_f32_16x16x32_bf16 v[2:5], v[182:185], v[214:217], v[2:5]
	s_setprio 0
	s_barrier
	ds_read_b128 v[132:135], v130
	ds_read_b128 v[154:157], v130 offset:1024
	ds_read_b128 v[162:165], v130 offset:2048
	ds_read_b128 v[166:169], v130 offset:3072
	ds_read_b128 v[170:173], v131
	ds_read_b128 v[174:177], v131 offset:1024
	ds_read_b128 v[178:181], v131 offset:2048
	ds_read_b128 v[182:185], v131 offset:3072
	s_add_u32 s66, s66, 0x20000
	s_addc_u32 s67, s67, 0
	s_mov_b32 m0, s63
	ds_read_b128 v[186:189], v160 offset:32768
	ds_read_b128 v[190:193], v160 offset:33792
	ds_read_b128 v[194:197], v160 offset:34816
	ds_read_b128 v[198:201], v160 offset:35840
	ds_read_b128 v[202:205], v160 offset:36864
	ds_read_b128 v[206:209], v160 offset:37888
	ds_read_b128 v[210:213], v160 offset:38912
	ds_read_b128 v[214:217], v160 offset:39936
	global_load_lds_dwordx4 v138, s[66:67]
	s_mov_b32 m0, s68
	s_nop 0
	global_load_lds_dwordx4 v142, s[66:67]
	s_waitcnt vmcnt(8)
	s_waitcnt lgkmcnt(0)
	s_barrier
	s_setprio 1
	s_waitcnt lgkmcnt(0)
	v_mfma_f32_16x16x32_bf16 v[118:121], v[132:135], v[186:189], v[118:121]
	v_mfma_f32_16x16x32_bf16 v[114:117], v[162:165], v[186:189], v[114:117]
	v_mfma_f32_16x16x32_bf16 v[110:113], v[132:135], v[194:197], v[110:113]
	v_mfma_f32_16x16x32_bf16 v[98:101], v[162:165], v[194:197], v[98:101]
	v_mfma_f32_16x16x32_bf16 v[94:97], v[132:135], v[202:205], v[94:97]
	v_mfma_f32_16x16x32_bf16 v[90:93], v[162:165], v[202:205], v[90:93]
	v_mfma_f32_16x16x32_bf16 v[78:81], v[132:135], v[210:213], v[78:81]
	v_mfma_f32_16x16x32_bf16 v[70:73], v[162:165], v[210:213], v[70:73]
	v_mfma_f32_16x16x32_bf16 v[118:121], v[154:157], v[190:193], v[118:121]
	v_mfma_f32_16x16x32_bf16 v[114:117], v[166:169], v[190:193], v[114:117]
	v_mfma_f32_16x16x32_bf16 v[110:113], v[154:157], v[198:201], v[110:113]
	v_mfma_f32_16x16x32_bf16 v[98:101], v[166:169], v[198:201], v[98:101]
	v_mfma_f32_16x16x32_bf16 v[94:97], v[154:157], v[206:209], v[94:97]
	v_mfma_f32_16x16x32_bf16 v[90:93], v[166:169], v[206:209], v[90:93]
	v_mfma_f32_16x16x32_bf16 v[78:81], v[154:157], v[214:217], v[78:81]
	v_mfma_f32_16x16x32_bf16 v[70:73], v[166:169], v[214:217], v[70:73]
	s_setprio 0
	s_setprio 1
	v_mfma_f32_16x16x32_bf16 v[126:129], v[170:173], v[186:189], v[126:129]
	v_mfma_f32_16x16x32_bf16 v[122:125], v[178:181], v[186:189], v[122:125]
	v_mfma_f32_16x16x32_bf16 v[106:109], v[170:173], v[194:197], v[106:109]
	v_mfma_f32_16x16x32_bf16 v[102:105], v[178:181], v[194:197], v[102:105]
	v_mfma_f32_16x16x32_bf16 v[86:89], v[170:173], v[202:205], v[86:89]
	v_mfma_f32_16x16x32_bf16 v[82:85], v[178:181], v[202:205], v[82:85]
	v_mfma_f32_16x16x32_bf16 v[62:65], v[170:173], v[210:213], v[62:65]
	v_mfma_f32_16x16x32_bf16 v[58:61], v[178:181], v[210:213], v[58:61]
	v_mfma_f32_16x16x32_bf16 v[126:129], v[174:177], v[190:193], v[126:129]
	v_mfma_f32_16x16x32_bf16 v[122:125], v[182:185], v[190:193], v[122:125]
	v_mfma_f32_16x16x32_bf16 v[106:109], v[174:177], v[198:201], v[106:109]
	v_mfma_f32_16x16x32_bf16 v[102:105], v[182:185], v[198:201], v[102:105]
	v_mfma_f32_16x16x32_bf16 v[86:89], v[174:177], v[206:209], v[86:89]
	v_mfma_f32_16x16x32_bf16 v[82:85], v[182:185], v[206:209], v[82:85]
	v_mfma_f32_16x16x32_bf16 v[62:65], v[174:177], v[214:217], v[62:65]
	v_mfma_f32_16x16x32_bf16 v[58:61], v[182:185], v[214:217], v[58:61]
	s_setprio 0
	s_barrier
	s_mov_b32 m0, s47
	s_add_u32 s98, s98, 0x80
	s_addc_u32 s99, s99, 0
	s_add_u32 s100, s100, 0x80
	s_addc_u32 s101, s101, 0
	s_add_u32 s6, s6, 0x20080
	ds_read_b128 v[186:189], v160 offset:49152
	ds_read_b128 v[190:193], v160 offset:50176
	ds_read_b128 v[194:197], v160 offset:51200
	ds_read_b128 v[198:201], v160 offset:52224
	ds_read_b128 v[202:205], v160 offset:53248
	ds_read_b128 v[206:209], v160 offset:54272
	ds_read_b128 v[210:213], v160 offset:55296
	ds_read_b128 v[214:217], v160 offset:56320
	global_load_lds_dwordx4 v140, s[98:99]
	s_mov_b32 m0, s86
	s_addc_u32 s7, s7, 0
	global_load_lds_dwordx4 v144, s[98:99]
	s_mov_b32 m0, s56
	s_nop 0
	global_load_lds_dwordx4 v140, s[6:7]
	s_mov_b32 m0, s57
	s_nop 0
	global_load_lds_dwordx4 v144, s[6:7]
	s_mov_b32 m0, s69
	s_nop 0
	global_load_lds_dwordx4 v138, s[100:101]
	s_mov_b32 m0, s70
	s_nop 0
	global_load_lds_dwordx4 v142, s[100:101]
	s_waitcnt vmcnt(8)
	s_waitcnt lgkmcnt(0)
	s_barrier
	s_setprio 1
	s_waitcnt lgkmcnt(0)
	v_mfma_f32_16x16x32_bf16 v[74:77], v[132:135], v[186:189], v[74:77]
	v_mfma_f32_16x16x32_bf16 v[66:69], v[162:165], v[186:189], v[66:69]
	v_mfma_f32_16x16x32_bf16 v[46:49], v[132:135], v[194:197], v[46:49]
	v_mfma_f32_16x16x32_bf16 v[42:45], v[162:165], v[194:197], v[42:45]
	v_mfma_f32_16x16x32_bf16 v[30:33], v[132:135], v[202:205], v[30:33]
	v_mfma_f32_16x16x32_bf16 v[26:29], v[162:165], v[202:205], v[26:29]
	v_mfma_f32_16x16x32_bf16 v[14:17], v[132:135], v[210:213], v[14:17]
	v_mfma_f32_16x16x32_bf16 v[10:13], v[162:165], v[210:213], v[10:13]
	v_mfma_f32_16x16x32_bf16 v[74:77], v[154:157], v[190:193], v[74:77]
	v_mfma_f32_16x16x32_bf16 v[66:69], v[166:169], v[190:193], v[66:69]
	v_mfma_f32_16x16x32_bf16 v[46:49], v[154:157], v[198:201], v[46:49]
	v_mfma_f32_16x16x32_bf16 v[42:45], v[166:169], v[198:201], v[42:45]
	v_mfma_f32_16x16x32_bf16 v[30:33], v[154:157], v[206:209], v[30:33]
	v_mfma_f32_16x16x32_bf16 v[26:29], v[166:169], v[206:209], v[26:29]
	v_mfma_f32_16x16x32_bf16 v[14:17], v[154:157], v[214:217], v[14:17]
	v_mfma_f32_16x16x32_bf16 v[10:13], v[166:169], v[214:217], v[10:13]
	s_setprio 0
	s_setprio 1
	v_mfma_f32_16x16x32_bf16 v[54:57], v[170:173], v[186:189], v[54:57]
	v_mfma_f32_16x16x32_bf16 v[50:53], v[178:181], v[186:189], v[50:53]
	v_mfma_f32_16x16x32_bf16 v[38:41], v[170:173], v[194:197], v[38:41]
	v_mfma_f32_16x16x32_bf16 v[34:37], v[178:181], v[194:197], v[34:37]
	v_mfma_f32_16x16x32_bf16 v[22:25], v[170:173], v[202:205], v[22:25]
	v_mfma_f32_16x16x32_bf16 v[18:21], v[178:181], v[202:205], v[18:21]
	v_mfma_f32_16x16x32_bf16 v[6:9], v[170:173], v[210:213], v[6:9]
	v_mfma_f32_16x16x32_bf16 v[2:5], v[178:181], v[210:213], v[2:5]
	v_mfma_f32_16x16x32_bf16 v[54:57], v[174:177], v[190:193], v[54:57]
	v_mfma_f32_16x16x32_bf16 v[50:53], v[182:185], v[190:193], v[50:53]
	v_mfma_f32_16x16x32_bf16 v[38:41], v[174:177], v[198:201], v[38:41]
	v_mfma_f32_16x16x32_bf16 v[34:37], v[182:185], v[198:201], v[34:37]
	v_mfma_f32_16x16x32_bf16 v[22:25], v[174:177], v[206:209], v[22:25]
	v_mfma_f32_16x16x32_bf16 v[18:21], v[182:185], v[206:209], v[18:21]
	v_mfma_f32_16x16x32_bf16 v[6:9], v[174:177], v[214:217], v[6:9]
	v_mfma_f32_16x16x32_bf16 v[2:5], v[182:185], v[214:217], v[2:5]
	s_setprio 0
	s_barrier
	s_add_i32 s26, s26, 2
	s_add_u32 s64, s64, 0x100
	s_addc_u32 s65, s65, 0
	s_add_u32 s14, s14, 0x100
	s_addc_u32 s15, s15, 0
	s_cmp_gt_u32 s26, 5
	s_cbranch_scc0 .LBB0_670
	s_and_b64 vcc, exec, s[18:19]
	s_cbranch_vccz .LBB0_673
	s_barrier

.LBB0_716:
	ds_read_b128 v[132:135], v164
	ds_read_b128 v[136:139], v164 offset:1024
	ds_read_b128 v[140:143], v164 offset:2048
	ds_read_b128 v[168:171], v164 offset:3072
	ds_read_b128 v[172:175], v165
	ds_read_b128 v[176:179], v165 offset:1024
	ds_read_b128 v[180:183], v165 offset:2048
	ds_read_b128 v[184:187], v165 offset:3072
	s_add_u32 s27, s62, 0xfff80080
	s_addc_u32 s50, s63, -1
	s_cmp_eq_u32 s26, 4
	s_cselect_b32 s65, s1, s50
	s_cselect_b32 s64, s0, s27
	s_cselect_b32 s51, s29, s15
	s_cselect_b32 s50, s28, s14
	s_mov_b32 m0, s23
	ds_read_b128 v[188:191], v166
	ds_read_b128 v[192:195], v166 offset:1024
	ds_read_b128 v[196:199], v166 offset:2048
	ds_read_b128 v[200:203], v166 offset:3072
	ds_read_b128 v[204:207], v166 offset:4096
	ds_read_b128 v[208:211], v166 offset:5120
	ds_read_b128 v[212:215], v166 offset:6144
	ds_read_b128 v[216:219], v166 offset:7168
	global_load_lds_dwordx4 v154, s[62:63]
	s_mov_b32 m0, s77
	s_nop 0
	global_load_lds_dwordx4 v156, s[62:63]
	s_waitcnt vmcnt(8)
	s_waitcnt lgkmcnt(0)
	s_barrier
	s_setprio 1
	s_waitcnt lgkmcnt(0)
	v_mfma_f32_16x16x32_bf16 v[102:105], v[132:135], v[188:191], v[102:105]
	v_mfma_f32_16x16x32_bf16 v[98:101], v[140:143], v[188:191], v[98:101]
	v_mfma_f32_16x16x32_bf16 v[94:97], v[132:135], v[196:199], v[94:97]
	v_mfma_f32_16x16x32_bf16 v[90:93], v[140:143], v[196:199], v[90:93]
	v_mfma_f32_16x16x32_bf16 v[86:89], v[132:135], v[204:207], v[86:89]
	v_mfma_f32_16x16x32_bf16 v[82:85], v[140:143], v[204:207], v[82:85]
	v_mfma_f32_16x16x32_bf16 v[78:81], v[132:135], v[212:215], v[78:81]
	v_mfma_f32_16x16x32_bf16 v[62:65], v[140:143], v[212:215], v[62:65]
	v_mfma_f32_16x16x32_bf16 v[102:105], v[136:139], v[192:195], v[102:105]
	v_mfma_f32_16x16x32_bf16 v[98:101], v[168:171], v[192:195], v[98:101]
	v_mfma_f32_16x16x32_bf16 v[94:97], v[136:139], v[200:203], v[94:97]
	v_mfma_f32_16x16x32_bf16 v[90:93], v[168:171], v[200:203], v[90:93]
	v_mfma_f32_16x16x32_bf16 v[86:89], v[136:139], v[208:211], v[86:89]
	v_mfma_f32_16x16x32_bf16 v[82:85], v[168:171], v[208:211], v[82:85]
	v_mfma_f32_16x16x32_bf16 v[78:81], v[136:139], v[216:219], v[78:81]
	v_mfma_f32_16x16x32_bf16 v[62:65], v[168:171], v[216:219], v[62:65]
	s_setprio 0
	s_setprio 1
	v_mfma_f32_16x16x32_bf16 v[126:129], v[172:175], v[188:191], v[126:129]
	v_mfma_f32_16x16x32_bf16 v[122:125], v[180:183], v[188:191], v[122:125]
	v_mfma_f32_16x16x32_bf16 v[118:121], v[172:175], v[196:199], v[118:121]
	v_mfma_f32_16x16x32_bf16 v[114:117], v[180:183], v[196:199], v[114:117]
	v_mfma_f32_16x16x32_bf16 v[110:113], v[172:175], v[204:207], v[110:113]
	v_mfma_f32_16x16x32_bf16 v[106:109], v[180:183], v[204:207], v[106:109]
	v_mfma_f32_16x16x32_bf16 v[54:57], v[172:175], v[212:215], v[54:57]
	v_mfma_f32_16x16x32_bf16 v[50:53], v[180:183], v[212:215], v[50:53]
	v_mfma_f32_16x16x32_bf16 v[126:129], v[176:179], v[192:195], v[126:129]
	v_mfma_f32_16x16x32_bf16 v[122:125], v[184:187], v[192:195], v[122:125]
	v_mfma_f32_16x16x32_bf16 v[118:121], v[176:179], v[200:203], v[118:121]
	v_mfma_f32_16x16x32_bf16 v[114:117], v[184:187], v[200:203], v[114:117]
	v_mfma_f32_16x16x32_bf16 v[110:113], v[176:179], v[208:211], v[110:113]
	v_mfma_f32_16x16x32_bf16 v[106:109], v[184:187], v[208:211], v[106:109]
	v_mfma_f32_16x16x32_bf16 v[54:57], v[176:179], v[216:219], v[54:57]
	v_mfma_f32_16x16x32_bf16 v[50:53], v[184:187], v[216:219], v[50:53]
	s_setprio 0
	s_barrier
	s_mov_b32 m0, s78
	s_mov_b64 s[98:99], s[50:51]
	s_add_u32 s82, s50, 0x80000
	ds_read_b128 v[188:191], v166 offset:16384
	ds_read_b128 v[192:195], v166 offset:17408
	ds_read_b128 v[196:199], v166 offset:18432
	ds_read_b128 v[200:203], v166 offset:19456
	ds_read_b128 v[204:207], v166 offset:20480
	ds_read_b128 v[208:211], v166 offset:21504
	ds_read_b128 v[212:215], v166 offset:22528
	ds_read_b128 v[216:219], v166 offset:23552
	global_load_lds_dwordx4 v148, s[50:51]
	s_mov_b32 m0, s79
	s_addc_u32 s83, s51, 0
	global_load_lds_dwordx4 v152, s[50:51]
	s_mov_b32 m0, s80
	s_mov_b64 s[100:101], s[64:65]
	global_load_lds_dwordx4 v148, s[82:83]
	s_mov_b32 m0, s46
	s_nop 0
	global_load_lds_dwordx4 v152, s[82:83]
	s_mov_b32 m0, s59
	s_nop 0
	global_load_lds_dwordx4 v146, s[64:65]
	s_mov_b32 m0, s31
	s_nop 0
	global_load_lds_dwordx4 v150, s[64:65]
	s_waitcnt vmcnt(8)
	s_waitcnt lgkmcnt(0)
	s_barrier
	s_setprio 1
	s_waitcnt lgkmcnt(0)
	v_mfma_f32_16x16x32_bf16 v[74:77], v[132:135], v[188:191], v[74:77]
	v_mfma_f32_16x16x32_bf16 v[70:73], v[140:143], v[188:191], v[70:73]
	v_mfma_f32_16x16x32_bf16 v[46:49], v[132:135], v[196:199], v[46:49]
	v_mfma_f32_16x16x32_bf16 v[42:45], v[140:143], v[196:199], v[42:45]
	v_mfma_f32_16x16x32_bf16 v[30:33], v[132:135], v[204:207], v[30:33]
	v_mfma_f32_16x16x32_bf16 v[26:29], v[140:143], v[204:207], v[26:29]
	v_mfma_f32_16x16x32_bf16 v[14:17], v[132:135], v[212:215], v[14:17]
	v_mfma_f32_16x16x32_bf16 v[10:13], v[140:143], v[212:215], v[10:13]
	v_mfma_f32_16x16x32_bf16 v[74:77], v[136:139], v[192:195], v[74:77]
	v_mfma_f32_16x16x32_bf16 v[70:73], v[168:171], v[192:195], v[70:73]
	v_mfma_f32_16x16x32_bf16 v[46:49], v[136:139], v[200:203], v[46:49]
	v_mfma_f32_16x16x32_bf16 v[42:45], v[168:171], v[200:203], v[42:45]
	v_mfma_f32_16x16x32_bf16 v[30:33], v[136:139], v[208:211], v[30:33]
	v_mfma_f32_16x16x32_bf16 v[26:29], v[168:171], v[208:211], v[26:29]
	v_mfma_f32_16x16x32_bf16 v[14:17], v[136:139], v[216:219], v[14:17]
	v_mfma_f32_16x16x32_bf16 v[10:13], v[168:171], v[216:219], v[10:13]
	s_setprio 0
	s_setprio 1
	v_mfma_f32_16x16x32_bf16 v[66:69], v[172:175], v[188:191], v[66:69]
	v_mfma_f32_16x16x32_bf16 v[58:61], v[180:183], v[188:191], v[58:61]
	v_mfma_f32_16x16x32_bf16 v[38:41], v[172:175], v[196:199], v[38:41]
	v_mfma_f32_16x16x32_bf16 v[34:37], v[180:183], v[196:199], v[34:37]
	v_mfma_f32_16x16x32_bf16 v[22:25], v[172:175], v[204:207], v[22:25]
	v_mfma_f32_16x16x32_bf16 v[18:21], v[180:183], v[204:207], v[18:21]
	v_mfma_f32_16x16x32_bf16 v[6:9], v[172:175], v[212:215], v[6:9]
	v_mfma_f32_16x16x32_bf16 v[2:5], v[180:183], v[212:215], v[2:5]
	v_mfma_f32_16x16x32_bf16 v[66:69], v[176:179], v[192:195], v[66:69]
	v_mfma_f32_16x16x32_bf16 v[58:61], v[184:187], v[192:195], v[58:61]
	v_mfma_f32_16x16x32_bf16 v[38:41], v[176:179], v[200:203], v[38:41]
	v_mfma_f32_16x16x32_bf16 v[34:37], v[184:187], v[200:203], v[34:37]
	v_mfma_f32_16x16x32_bf16 v[22:25], v[176:179], v[208:211], v[22:25]
	v_mfma_f32_16x16x32_bf16 v[18:21], v[184:187], v[208:211], v[18:21]
	v_mfma_f32_16x16x32_bf16 v[6:9], v[176:179], v[216:219], v[6:9]
	v_mfma_f32_16x16x32_bf16 v[2:5], v[184:187], v[216:219], v[2:5]
	s_setprio 0
	s_barrier
	ds_read_b128 v[132:135], v130
	ds_read_b128 v[136:139], v130 offset:1024
	ds_read_b128 v[140:143], v130 offset:2048
	ds_read_b128 v[168:171], v130 offset:3072
	ds_read_b128 v[172:175], v131
	ds_read_b128 v[176:179], v131 offset:1024
	ds_read_b128 v[180:183], v131 offset:2048
	ds_read_b128 v[184:187], v131 offset:3072
	s_add_u32 s64, s64, 0x80000
	s_addc_u32 s65, s65, 0
	s_mov_b32 m0, s66
	ds_read_b128 v[188:191], v166 offset:32768
	ds_read_b128 v[192:195], v166 offset:33792
	ds_read_b128 v[196:199], v166 offset:34816
	ds_read_b128 v[200:203], v166 offset:35840
	ds_read_b128 v[204:207], v166 offset:36864
	ds_read_b128 v[208:211], v166 offset:37888
	ds_read_b128 v[212:215], v166 offset:38912
	ds_read_b128 v[216:219], v166 offset:39936
	global_load_lds_dwordx4 v146, s[64:65]
	s_mov_b32 m0, s67
	s_nop 0
	global_load_lds_dwordx4 v150, s[64:65]
	s_waitcnt vmcnt(8)
	s_waitcnt lgkmcnt(0)
	s_barrier
	s_setprio 1
	s_waitcnt lgkmcnt(0)
	v_mfma_f32_16x16x32_bf16 v[102:105], v[132:135], v[188:191], v[102:105]
	v_mfma_f32_16x16x32_bf16 v[98:101], v[140:143], v[188:191], v[98:101]
	v_mfma_f32_16x16x32_bf16 v[94:97], v[132:135], v[196:199], v[94:97]
	v_mfma_f32_16x16x32_bf16 v[90:93], v[140:143], v[196:199], v[90:93]
	v_mfma_f32_16x16x32_bf16 v[86:89], v[132:135], v[204:207], v[86:89]
	v_mfma_f32_16x16x32_bf16 v[82:85], v[140:143], v[204:207], v[82:85]
	v_mfma_f32_16x16x32_bf16 v[78:81], v[132:135], v[212:215], v[78:81]
	v_mfma_f32_16x16x32_bf16 v[62:65], v[140:143], v[212:215], v[62:65]
	v_mfma_f32_16x16x32_bf16 v[102:105], v[136:139], v[192:195], v[102:105]
	v_mfma_f32_16x16x32_bf16 v[98:101], v[168:171], v[192:195], v[98:101]
	v_mfma_f32_16x16x32_bf16 v[94:97], v[136:139], v[200:203], v[94:97]
	v_mfma_f32_16x16x32_bf16 v[90:93], v[168:171], v[200:203], v[90:93]
	v_mfma_f32_16x16x32_bf16 v[86:89], v[136:139], v[208:211], v[86:89]
	v_mfma_f32_16x16x32_bf16 v[82:85], v[168:171], v[208:211], v[82:85]
	v_mfma_f32_16x16x32_bf16 v[78:81], v[136:139], v[216:219], v[78:81]
	v_mfma_f32_16x16x32_bf16 v[62:65], v[168:171], v[216:219], v[62:65]
	s_setprio 0
	s_setprio 1
	v_mfma_f32_16x16x32_bf16 v[126:129], v[172:175], v[188:191], v[126:129]
	v_mfma_f32_16x16x32_bf16 v[122:125], v[180:183], v[188:191], v[122:125]
	v_mfma_f32_16x16x32_bf16 v[118:121], v[172:175], v[196:199], v[118:121]
	v_mfma_f32_16x16x32_bf16 v[114:117], v[180:183], v[196:199], v[114:117]
	v_mfma_f32_16x16x32_bf16 v[110:113], v[172:175], v[204:207], v[110:113]
	v_mfma_f32_16x16x32_bf16 v[106:109], v[180:183], v[204:207], v[106:109]
	v_mfma_f32_16x16x32_bf16 v[54:57], v[172:175], v[212:215], v[54:57]
	v_mfma_f32_16x16x32_bf16 v[50:53], v[180:183], v[212:215], v[50:53]
	v_mfma_f32_16x16x32_bf16 v[126:129], v[176:179], v[192:195], v[126:129]
	v_mfma_f32_16x16x32_bf16 v[122:125], v[184:187], v[192:195], v[122:125]
	v_mfma_f32_16x16x32_bf16 v[118:121], v[176:179], v[200:203], v[118:121]
	v_mfma_f32_16x16x32_bf16 v[114:117], v[184:187], v[200:203], v[114:117]
	v_mfma_f32_16x16x32_bf16 v[110:113], v[176:179], v[208:211], v[110:113]
	v_mfma_f32_16x16x32_bf16 v[106:109], v[184:187], v[208:211], v[106:109]
	v_mfma_f32_16x16x32_bf16 v[54:57], v[176:179], v[216:219], v[54:57]
	v_mfma_f32_16x16x32_bf16 v[50:53], v[184:187], v[216:219], v[50:53]
	s_setprio 0
	s_barrier
	s_mov_b32 m0, s47
	s_add_u32 s98, s98, 0x80
	s_addc_u32 s99, s99, 0
	s_add_u32 s100, s100, 0x80
	s_addc_u32 s101, s101, 0
	s_add_u32 s50, s50, 0x80080
	ds_read_b128 v[188:191], v166 offset:49152
	ds_read_b128 v[192:195], v166 offset:50176
	ds_read_b128 v[196:199], v166 offset:51200
	ds_read_b128 v[200:203], v166 offset:52224
	ds_read_b128 v[204:207], v166 offset:53248
	ds_read_b128 v[208:211], v166 offset:54272
	ds_read_b128 v[212:215], v166 offset:55296
	ds_read_b128 v[216:219], v166 offset:56320
	global_load_lds_dwordx4 v148, s[98:99]
	s_mov_b32 m0, s81
	s_addc_u32 s51, s51, 0
	global_load_lds_dwordx4 v152, s[98:99]
	s_mov_b32 m0, s56
	s_nop 0
	global_load_lds_dwordx4 v148, s[50:51]
	s_mov_b32 m0, s57
	s_nop 0
	global_load_lds_dwordx4 v152, s[50:51]
	s_mov_b32 m0, s69
	s_nop 0
	global_load_lds_dwordx4 v146, s[100:101]
	s_mov_b32 m0, s70
	s_nop 0
	global_load_lds_dwordx4 v150, s[100:101]
	s_waitcnt vmcnt(8)
	s_waitcnt lgkmcnt(0)
	s_barrier
	s_setprio 1
	s_waitcnt lgkmcnt(0)
	v_mfma_f32_16x16x32_bf16 v[74:77], v[132:135], v[188:191], v[74:77]
	v_mfma_f32_16x16x32_bf16 v[70:73], v[140:143], v[188:191], v[70:73]
	v_mfma_f32_16x16x32_bf16 v[46:49], v[132:135], v[196:199], v[46:49]
	v_mfma_f32_16x16x32_bf16 v[42:45], v[140:143], v[196:199], v[42:45]
	v_mfma_f32_16x16x32_bf16 v[30:33], v[132:135], v[204:207], v[30:33]
	v_mfma_f32_16x16x32_bf16 v[26:29], v[140:143], v[204:207], v[26:29]
	v_mfma_f32_16x16x32_bf16 v[14:17], v[132:135], v[212:215], v[14:17]
	v_mfma_f32_16x16x32_bf16 v[10:13], v[140:143], v[212:215], v[10:13]
	v_mfma_f32_16x16x32_bf16 v[74:77], v[136:139], v[192:195], v[74:77]
	v_mfma_f32_16x16x32_bf16 v[70:73], v[168:171], v[192:195], v[70:73]
	v_mfma_f32_16x16x32_bf16 v[46:49], v[136:139], v[200:203], v[46:49]
	v_mfma_f32_16x16x32_bf16 v[42:45], v[168:171], v[200:203], v[42:45]
	v_mfma_f32_16x16x32_bf16 v[30:33], v[136:139], v[208:211], v[30:33]
	v_mfma_f32_16x16x32_bf16 v[26:29], v[168:171], v[208:211], v[26:29]
	v_mfma_f32_16x16x32_bf16 v[14:17], v[136:139], v[216:219], v[14:17]
	v_mfma_f32_16x16x32_bf16 v[10:13], v[168:171], v[216:219], v[10:13]
	s_setprio 0
	s_setprio 1
	v_mfma_f32_16x16x32_bf16 v[66:69], v[172:175], v[188:191], v[66:69]
	v_mfma_f32_16x16x32_bf16 v[58:61], v[180:183], v[188:191], v[58:61]
	v_mfma_f32_16x16x32_bf16 v[38:41], v[172:175], v[196:199], v[38:41]
	v_mfma_f32_16x16x32_bf16 v[34:37], v[180:183], v[196:199], v[34:37]
	v_mfma_f32_16x16x32_bf16 v[22:25], v[172:175], v[204:207], v[22:25]
	v_mfma_f32_16x16x32_bf16 v[18:21], v[180:183], v[204:207], v[18:21]
	v_mfma_f32_16x16x32_bf16 v[6:9], v[172:175], v[212:215], v[6:9]
	v_mfma_f32_16x16x32_bf16 v[2:5], v[180:183], v[212:215], v[2:5]
	v_mfma_f32_16x16x32_bf16 v[66:69], v[176:179], v[192:195], v[66:69]
	v_mfma_f32_16x16x32_bf16 v[58:61], v[184:187], v[192:195], v[58:61]
	v_mfma_f32_16x16x32_bf16 v[38:41], v[176:179], v[200:203], v[38:41]
	v_mfma_f32_16x16x32_bf16 v[34:37], v[184:187], v[200:203], v[34:37]
	v_mfma_f32_16x16x32_bf16 v[22:25], v[176:179], v[208:211], v[22:25]
	v_mfma_f32_16x16x32_bf16 v[18:21], v[184:187], v[208:211], v[18:21]
	v_mfma_f32_16x16x32_bf16 v[6:9], v[176:179], v[216:219], v[6:9]
	v_mfma_f32_16x16x32_bf16 v[2:5], v[184:187], v[216:219], v[2:5]
	s_setprio 0
	s_barrier
	s_add_i32 s26, s26, 2
	s_add_u32 s62, s62, 0x100
	s_addc_u32 s63, s63, 0
	s_add_u32 s14, s14, 0x100
	s_addc_u32 s15, s15, 0
	s_cmp_gt_u32 s26, 5
	s_cbranch_scc0 .LBB0_716
	s_and_b64 vcc, exec, s[16:17]
	s_cbranch_vccz .LBB0_719
	s_barrier

.LBB0_930:
	ds_read_b128 v[134:137], v130
	ds_read_b128 v[138:141], v130 offset:1024
	ds_read_b128 v[142:145], v130 offset:2048
	ds_read_b128 v[146:149], v130 offset:3072
	ds_read_b128 v[168:171], v131
	ds_read_b128 v[174:177], v131 offset:1024
	ds_read_b128 v[178:181], v131 offset:2048
	ds_read_b128 v[182:185], v131 offset:3072
	s_add_u32 s27, s62, 0xfff80080
	s_addc_u32 s50, s63, -1
	s_cmp_eq_u32 s26, 28
	s_cselect_b32 s65, s7, s50
	s_cselect_b32 s64, s6, s27
	s_cselect_b32 s51, s49, s15
	s_cselect_b32 s50, s48, s14
	s_mov_b32 m0, s0
	ds_read_b128 v[186:189], v172
	ds_read_b128 v[190:193], v172 offset:1024
	ds_read_b128 v[194:197], v172 offset:2048
	ds_read_b128 v[198:201], v172 offset:3072
	ds_read_b128 v[202:205], v172 offset:4096
	ds_read_b128 v[206:209], v172 offset:5120
	ds_read_b128 v[210:213], v172 offset:6144
	ds_read_b128 v[214:217], v172 offset:7168
	global_load_lds_dwordx4 v160, s[62:63]
	s_mov_b32 m0, s11
	s_nop 0
	global_load_lds_dwordx4 v162, s[62:63]
	s_waitcnt vmcnt(8)
	s_waitcnt lgkmcnt(0)
	s_barrier
	s_setprio 1
	s_waitcnt lgkmcnt(0)
	v_mfma_f32_16x16x32_bf16 v[126:129], v[134:137], v[186:189], v[126:129]
	v_mfma_f32_16x16x32_bf16 v[122:125], v[142:145], v[186:189], v[122:125]
	v_mfma_f32_16x16x32_bf16 v[118:121], v[134:137], v[194:197], v[118:121]
	v_mfma_f32_16x16x32_bf16 v[114:117], v[142:145], v[194:197], v[114:117]
	v_mfma_f32_16x16x32_bf16 v[110:113], v[134:137], v[202:205], v[110:113]
	v_mfma_f32_16x16x32_bf16 v[106:109], v[142:145], v[202:205], v[106:109]
	v_mfma_f32_16x16x32_bf16 v[102:105], v[134:137], v[210:213], v[102:105]
	v_mfma_f32_16x16x32_bf16 v[98:101], v[142:145], v[210:213], v[98:101]
	v_mfma_f32_16x16x32_bf16 v[126:129], v[138:141], v[190:193], v[126:129]
	v_mfma_f32_16x16x32_bf16 v[122:125], v[146:149], v[190:193], v[122:125]
	v_mfma_f32_16x16x32_bf16 v[118:121], v[138:141], v[198:201], v[118:121]
	v_mfma_f32_16x16x32_bf16 v[114:117], v[146:149], v[198:201], v[114:117]
	v_mfma_f32_16x16x32_bf16 v[110:113], v[138:141], v[206:209], v[110:113]
	v_mfma_f32_16x16x32_bf16 v[106:109], v[146:149], v[206:209], v[106:109]
	v_mfma_f32_16x16x32_bf16 v[102:105], v[138:141], v[214:217], v[102:105]
	v_mfma_f32_16x16x32_bf16 v[98:101], v[146:149], v[214:217], v[98:101]
	s_setprio 0
	s_setprio 1
	v_mfma_f32_16x16x32_bf16 v[94:97], v[168:171], v[186:189], v[94:97]
	v_mfma_f32_16x16x32_bf16 v[90:93], v[178:181], v[186:189], v[90:93]
	v_mfma_f32_16x16x32_bf16 v[86:89], v[168:171], v[194:197], v[86:89]
	v_mfma_f32_16x16x32_bf16 v[82:85], v[178:181], v[194:197], v[82:85]
	v_mfma_f32_16x16x32_bf16 v[78:81], v[168:171], v[202:205], v[78:81]
	v_mfma_f32_16x16x32_bf16 v[74:77], v[178:181], v[202:205], v[74:77]
	v_mfma_f32_16x16x32_bf16 v[70:73], v[168:171], v[210:213], v[70:73]
	v_mfma_f32_16x16x32_bf16 v[66:69], v[178:181], v[210:213], v[66:69]
	v_mfma_f32_16x16x32_bf16 v[94:97], v[174:177], v[190:193], v[94:97]
	v_mfma_f32_16x16x32_bf16 v[90:93], v[182:185], v[190:193], v[90:93]
	v_mfma_f32_16x16x32_bf16 v[86:89], v[174:177], v[198:201], v[86:89]
	v_mfma_f32_16x16x32_bf16 v[82:85], v[182:185], v[198:201], v[82:85]
	v_mfma_f32_16x16x32_bf16 v[78:81], v[174:177], v[206:209], v[78:81]
	v_mfma_f32_16x16x32_bf16 v[74:77], v[182:185], v[206:209], v[74:77]
	v_mfma_f32_16x16x32_bf16 v[70:73], v[174:177], v[214:217], v[70:73]
	v_mfma_f32_16x16x32_bf16 v[66:69], v[182:185], v[214:217], v[66:69]
	s_setprio 0
	s_barrier
	s_mov_b32 m0, s12
	s_mov_b64 s[98:99], s[50:51]
	s_add_u32 s58, s50, 0x80000
	ds_read_b128 v[186:189], v172 offset:16384
	ds_read_b128 v[190:193], v172 offset:17408
	ds_read_b128 v[194:197], v172 offset:18432
	ds_read_b128 v[198:201], v172 offset:19456
	ds_read_b128 v[202:205], v172 offset:20480
	ds_read_b128 v[206:209], v172 offset:21504
	ds_read_b128 v[210:213], v172 offset:22528
	ds_read_b128 v[214:217], v172 offset:23552
	global_load_lds_dwordx4 v152, s[50:51]
	s_mov_b32 m0, s13
	s_addc_u32 s59, s51, 0
	global_load_lds_dwordx4 v156, s[50:51]
	s_mov_b32 m0, s43
	s_mov_b64 s[100:101], s[64:65]
	global_load_lds_dwordx4 v152, s[58:59]
	s_mov_b32 m0, s46
	s_nop 0
	global_load_lds_dwordx4 v156, s[58:59]
	s_mov_b32 m0, s69
	s_nop 0
	global_load_lds_dwordx4 v150, s[64:65]
	s_mov_b32 m0, s70
	s_nop 0
	global_load_lds_dwordx4 v154, s[64:65]
	s_waitcnt vmcnt(8)
	s_waitcnt lgkmcnt(0)
	s_barrier
	s_setprio 1
	s_waitcnt lgkmcnt(0)
	v_mfma_f32_16x16x32_bf16 v[62:65], v[134:137], v[186:189], v[62:65]
	v_mfma_f32_16x16x32_bf16 v[58:61], v[142:145], v[186:189], v[58:61]
	v_mfma_f32_16x16x32_bf16 v[54:57], v[134:137], v[194:197], v[54:57]
	v_mfma_f32_16x16x32_bf16 v[50:53], v[142:145], v[194:197], v[50:53]
	v_mfma_f32_16x16x32_bf16 v[46:49], v[134:137], v[202:205], v[46:49]
	v_mfma_f32_16x16x32_bf16 v[42:45], v[142:145], v[202:205], v[42:45]
	v_mfma_f32_16x16x32_bf16 v[38:41], v[134:137], v[210:213], v[38:41]
	v_mfma_f32_16x16x32_bf16 v[34:37], v[142:145], v[210:213], v[34:37]
	v_mfma_f32_16x16x32_bf16 v[62:65], v[138:141], v[190:193], v[62:65]
	v_mfma_f32_16x16x32_bf16 v[58:61], v[146:149], v[190:193], v[58:61]
	v_mfma_f32_16x16x32_bf16 v[54:57], v[138:141], v[198:201], v[54:57]
	v_mfma_f32_16x16x32_bf16 v[50:53], v[146:149], v[198:201], v[50:53]
	v_mfma_f32_16x16x32_bf16 v[46:49], v[138:141], v[206:209], v[46:49]
	v_mfma_f32_16x16x32_bf16 v[42:45], v[146:149], v[206:209], v[42:45]
	v_mfma_f32_16x16x32_bf16 v[38:41], v[138:141], v[214:217], v[38:41]
	v_mfma_f32_16x16x32_bf16 v[34:37], v[146:149], v[214:217], v[34:37]
	s_setprio 0
	s_setprio 1
	v_mfma_f32_16x16x32_bf16 v[30:33], v[168:171], v[186:189], v[30:33]
	v_mfma_f32_16x16x32_bf16 v[26:29], v[178:181], v[186:189], v[26:29]
	v_mfma_f32_16x16x32_bf16 v[22:25], v[168:171], v[194:197], v[22:25]
	v_mfma_f32_16x16x32_bf16 v[18:21], v[178:181], v[194:197], v[18:21]
	v_mfma_f32_16x16x32_bf16 v[14:17], v[168:171], v[202:205], v[14:17]
	v_mfma_f32_16x16x32_bf16 v[10:13], v[178:181], v[202:205], v[10:13]
	v_mfma_f32_16x16x32_bf16 v[6:9], v[168:171], v[210:213], v[6:9]
	v_mfma_f32_16x16x32_bf16 v[2:5], v[178:181], v[210:213], v[2:5]
	v_mfma_f32_16x16x32_bf16 v[30:33], v[174:177], v[190:193], v[30:33]
	v_mfma_f32_16x16x32_bf16 v[26:29], v[182:185], v[190:193], v[26:29]
	v_mfma_f32_16x16x32_bf16 v[22:25], v[174:177], v[198:201], v[22:25]
	v_mfma_f32_16x16x32_bf16 v[18:21], v[182:185], v[198:201], v[18:21]
	v_mfma_f32_16x16x32_bf16 v[14:17], v[174:177], v[206:209], v[14:17]
	v_mfma_f32_16x16x32_bf16 v[10:13], v[182:185], v[206:209], v[10:13]
	v_mfma_f32_16x16x32_bf16 v[6:9], v[174:177], v[214:217], v[6:9]
	v_mfma_f32_16x16x32_bf16 v[2:5], v[182:185], v[214:217], v[2:5]
	s_setprio 0
	s_barrier
	ds_read_b128 v[134:137], v132
	ds_read_b128 v[138:141], v132 offset:1024
	ds_read_b128 v[142:145], v132 offset:2048
	ds_read_b128 v[146:149], v132 offset:3072
	ds_read_b128 v[168:171], v133
	ds_read_b128 v[174:177], v133 offset:1024
	ds_read_b128 v[178:181], v133 offset:2048
	ds_read_b128 v[182:185], v133 offset:3072
	s_add_u32 s58, s64, 0x80000
	s_addc_u32 s59, s65, 0
	s_mov_b32 m0, s71
	ds_read_b128 v[186:189], v172 offset:32768
	ds_read_b128 v[190:193], v172 offset:33792
	ds_read_b128 v[194:197], v172 offset:34816
	ds_read_b128 v[198:201], v172 offset:35840
	ds_read_b128 v[202:205], v172 offset:36864
	ds_read_b128 v[206:209], v172 offset:37888
	ds_read_b128 v[210:213], v172 offset:38912
	ds_read_b128 v[214:217], v172 offset:39936
	global_load_lds_dwordx4 v150, s[58:59]
	s_mov_b32 m0, s72
	s_nop 0
	global_load_lds_dwordx4 v154, s[58:59]
	s_waitcnt vmcnt(8)
	s_waitcnt lgkmcnt(0)
	s_barrier
	s_setprio 1
	s_waitcnt lgkmcnt(0)
	v_mfma_f32_16x16x32_bf16 v[126:129], v[134:137], v[186:189], v[126:129]
	v_mfma_f32_16x16x32_bf16 v[122:125], v[142:145], v[186:189], v[122:125]
	v_mfma_f32_16x16x32_bf16 v[118:121], v[134:137], v[194:197], v[118:121]
	v_mfma_f32_16x16x32_bf16 v[114:117], v[142:145], v[194:197], v[114:117]
	v_mfma_f32_16x16x32_bf16 v[110:113], v[134:137], v[202:205], v[110:113]
	v_mfma_f32_16x16x32_bf16 v[106:109], v[142:145], v[202:205], v[106:109]
	v_mfma_f32_16x16x32_bf16 v[102:105], v[134:137], v[210:213], v[102:105]
	v_mfma_f32_16x16x32_bf16 v[98:101], v[142:145], v[210:213], v[98:101]
	v_mfma_f32_16x16x32_bf16 v[126:129], v[138:141], v[190:193], v[126:129]
	v_mfma_f32_16x16x32_bf16 v[122:125], v[146:149], v[190:193], v[122:125]
	v_mfma_f32_16x16x32_bf16 v[118:121], v[138:141], v[198:201], v[118:121]
	v_mfma_f32_16x16x32_bf16 v[114:117], v[146:149], v[198:201], v[114:117]
	v_mfma_f32_16x16x32_bf16 v[110:113], v[138:141], v[206:209], v[110:113]
	v_mfma_f32_16x16x32_bf16 v[106:109], v[146:149], v[206:209], v[106:109]
	v_mfma_f32_16x16x32_bf16 v[102:105], v[138:141], v[214:217], v[102:105]
	v_mfma_f32_16x16x32_bf16 v[98:101], v[146:149], v[214:217], v[98:101]
	s_setprio 0
	s_setprio 1
	v_mfma_f32_16x16x32_bf16 v[94:97], v[168:171], v[186:189], v[94:97]
	v_mfma_f32_16x16x32_bf16 v[90:93], v[178:181], v[186:189], v[90:93]
	v_mfma_f32_16x16x32_bf16 v[86:89], v[168:171], v[194:197], v[86:89]
	v_mfma_f32_16x16x32_bf16 v[82:85], v[178:181], v[194:197], v[82:85]
	v_mfma_f32_16x16x32_bf16 v[78:81], v[168:171], v[202:205], v[78:81]
	v_mfma_f32_16x16x32_bf16 v[74:77], v[178:181], v[202:205], v[74:77]
	v_mfma_f32_16x16x32_bf16 v[70:73], v[168:171], v[210:213], v[70:73]
	v_mfma_f32_16x16x32_bf16 v[66:69], v[178:181], v[210:213], v[66:69]
	v_mfma_f32_16x16x32_bf16 v[94:97], v[174:177], v[190:193], v[94:97]
	v_mfma_f32_16x16x32_bf16 v[90:93], v[182:185], v[190:193], v[90:93]
	v_mfma_f32_16x16x32_bf16 v[86:89], v[174:177], v[198:201], v[86:89]
	v_mfma_f32_16x16x32_bf16 v[82:85], v[182:185], v[198:201], v[82:85]
	v_mfma_f32_16x16x32_bf16 v[78:81], v[174:177], v[206:209], v[78:81]
	v_mfma_f32_16x16x32_bf16 v[74:77], v[182:185], v[206:209], v[74:77]
	v_mfma_f32_16x16x32_bf16 v[70:73], v[174:177], v[214:217], v[70:73]
	v_mfma_f32_16x16x32_bf16 v[66:69], v[182:185], v[214:217], v[66:69]
	s_setprio 0
	s_barrier
	s_mov_b32 m0, s47
	s_add_u32 s98, s98, 0x80
	s_addc_u32 s99, s99, 0
	s_add_u32 s100, s100, 0x80
	s_addc_u32 s101, s101, 0
	s_add_u32 s50, s50, 0x80080
	ds_read_b128 v[186:189], v172 offset:49152
	ds_read_b128 v[190:193], v172 offset:50176
	ds_read_b128 v[194:197], v172 offset:51200
	ds_read_b128 v[198:201], v172 offset:52224
	ds_read_b128 v[202:205], v172 offset:53248
	ds_read_b128 v[206:209], v172 offset:54272
	ds_read_b128 v[210:213], v172 offset:55296
	ds_read_b128 v[214:217], v172 offset:56320
	global_load_lds_dwordx4 v152, s[98:99]
	s_mov_b32 m0, s53
	s_addc_u32 s51, s51, 0
	global_load_lds_dwordx4 v156, s[98:99]
	s_mov_b32 m0, s55
	s_nop 0
	global_load_lds_dwordx4 v152, s[50:51]
	s_mov_b32 m0, s56
	s_nop 0
	global_load_lds_dwordx4 v156, s[50:51]
	s_mov_b32 m0, s77
	s_nop 0
	global_load_lds_dwordx4 v150, s[100:101]
	s_mov_b32 m0, s78
	s_nop 0
	global_load_lds_dwordx4 v154, s[100:101]
	s_waitcnt vmcnt(8)
	s_waitcnt lgkmcnt(0)
	s_barrier
	s_setprio 1
	s_waitcnt lgkmcnt(0)
	v_mfma_f32_16x16x32_bf16 v[62:65], v[134:137], v[186:189], v[62:65]
	v_mfma_f32_16x16x32_bf16 v[58:61], v[142:145], v[186:189], v[58:61]
	v_mfma_f32_16x16x32_bf16 v[54:57], v[134:137], v[194:197], v[54:57]
	v_mfma_f32_16x16x32_bf16 v[50:53], v[142:145], v[194:197], v[50:53]
	v_mfma_f32_16x16x32_bf16 v[46:49], v[134:137], v[202:205], v[46:49]
	v_mfma_f32_16x16x32_bf16 v[42:45], v[142:145], v[202:205], v[42:45]
	v_mfma_f32_16x16x32_bf16 v[38:41], v[134:137], v[210:213], v[38:41]
	v_mfma_f32_16x16x32_bf16 v[34:37], v[142:145], v[210:213], v[34:37]
	v_mfma_f32_16x16x32_bf16 v[62:65], v[138:141], v[190:193], v[62:65]
	v_mfma_f32_16x16x32_bf16 v[58:61], v[146:149], v[190:193], v[58:61]
	v_mfma_f32_16x16x32_bf16 v[54:57], v[138:141], v[198:201], v[54:57]
	v_mfma_f32_16x16x32_bf16 v[50:53], v[146:149], v[198:201], v[50:53]
	v_mfma_f32_16x16x32_bf16 v[46:49], v[138:141], v[206:209], v[46:49]
	v_mfma_f32_16x16x32_bf16 v[42:45], v[146:149], v[206:209], v[42:45]
	v_mfma_f32_16x16x32_bf16 v[38:41], v[138:141], v[214:217], v[38:41]
	v_mfma_f32_16x16x32_bf16 v[34:37], v[146:149], v[214:217], v[34:37]
	s_setprio 0
	s_setprio 1
	v_mfma_f32_16x16x32_bf16 v[30:33], v[168:171], v[186:189], v[30:33]
	v_mfma_f32_16x16x32_bf16 v[26:29], v[178:181], v[186:189], v[26:29]
	v_mfma_f32_16x16x32_bf16 v[22:25], v[168:171], v[194:197], v[22:25]
	v_mfma_f32_16x16x32_bf16 v[18:21], v[178:181], v[194:197], v[18:21]
	v_mfma_f32_16x16x32_bf16 v[14:17], v[168:171], v[202:205], v[14:17]
	v_mfma_f32_16x16x32_bf16 v[10:13], v[178:181], v[202:205], v[10:13]
	v_mfma_f32_16x16x32_bf16 v[6:9], v[168:171], v[210:213], v[6:9]
	v_mfma_f32_16x16x32_bf16 v[2:5], v[178:181], v[210:213], v[2:5]
	v_mfma_f32_16x16x32_bf16 v[30:33], v[174:177], v[190:193], v[30:33]
	v_mfma_f32_16x16x32_bf16 v[26:29], v[182:185], v[190:193], v[26:29]
	v_mfma_f32_16x16x32_bf16 v[22:25], v[174:177], v[198:201], v[22:25]
	v_mfma_f32_16x16x32_bf16 v[18:21], v[182:185], v[198:201], v[18:21]
	v_mfma_f32_16x16x32_bf16 v[14:17], v[174:177], v[206:209], v[14:17]
	v_mfma_f32_16x16x32_bf16 v[10:13], v[182:185], v[206:209], v[10:13]
	v_mfma_f32_16x16x32_bf16 v[6:9], v[174:177], v[214:217], v[6:9]
	v_mfma_f32_16x16x32_bf16 v[2:5], v[182:185], v[214:217], v[2:5]
	s_setprio 0
	s_barrier
	s_add_i32 s26, s26, 2
	s_add_u32 s62, s62, 0x100
	s_addc_u32 s63, s63, 0
	s_add_u32 s14, s14, 0x100
	s_addc_u32 s15, s15, 0
	s_cmp_gt_u32 s26, 29
	s_cbranch_scc0 .LBB0_930
	s_and_b64 vcc, exec, s[18:19]
	s_cbranch_vccz .LBB0_933
	s_barrier

.LBB0_1014:
	ds_read_b128 v[132:135], v182
	ds_read_b128 v[136:139], v182 offset:1024
	ds_read_b128 v[140:143], v182 offset:2048
	ds_read_b128 v[144:147], v182 offset:3072
	ds_read_b128 v[148:151], v183
	ds_read_b128 v[170:173], v183 offset:1024
	ds_read_b128 v[174:177], v183 offset:2048
	ds_read_b128 v[178:181], v183 offset:3072
	s_add_u32 s27, s48, 0xfff00080
	s_addc_u32 s42, s49, -1
	s_cmp_eq_u32 s26, 60
	s_cselect_b32 s51, s29, s42
	s_cselect_b32 s50, s41, s27
	s_cselect_b32 s43, s0, s15
	s_cselect_b32 s42, s68, s14
	s_mov_b32 m0, s61
	ds_read_b128 v[186:189], v184
	ds_read_b128 v[190:193], v184 offset:1024
	ds_read_b128 v[194:197], v184 offset:2048
	ds_read_b128 v[198:201], v184 offset:3072
	ds_read_b128 v[202:205], v184 offset:4096
	ds_read_b128 v[206:209], v184 offset:5120
	ds_read_b128 v[210:213], v184 offset:6144
	ds_read_b128 v[214:217], v184 offset:7168
	global_load_lds_dwordx4 v162, s[48:49]
	s_mov_b32 m0, s62
	s_nop 0
	global_load_lds_dwordx4 v164, s[48:49]
	s_waitcnt vmcnt(8)
	s_waitcnt lgkmcnt(0)
	s_barrier
	s_setprio 1
	s_waitcnt lgkmcnt(0)
	v_mfma_f32_16x16x32_bf16 v[122:125], v[132:135], v[186:189], v[122:125]
	v_mfma_f32_16x16x32_bf16 v[118:121], v[140:143], v[186:189], v[118:121]
	v_mfma_f32_16x16x32_bf16 v[110:113], v[132:135], v[194:197], v[110:113]
	v_mfma_f32_16x16x32_bf16 v[106:109], v[140:143], v[194:197], v[106:109]
	v_mfma_f32_16x16x32_bf16 v[94:97], v[132:135], v[202:205], v[94:97]
	v_mfma_f32_16x16x32_bf16 v[90:93], v[140:143], v[202:205], v[90:93]
	v_mfma_f32_16x16x32_bf16 v[78:81], v[132:135], v[210:213], v[78:81]
	v_mfma_f32_16x16x32_bf16 v[74:77], v[140:143], v[210:213], v[74:77]
	v_mfma_f32_16x16x32_bf16 v[122:125], v[136:139], v[190:193], v[122:125]
	v_mfma_f32_16x16x32_bf16 v[118:121], v[144:147], v[190:193], v[118:121]
	v_mfma_f32_16x16x32_bf16 v[110:113], v[136:139], v[198:201], v[110:113]
	v_mfma_f32_16x16x32_bf16 v[106:109], v[144:147], v[198:201], v[106:109]
	v_mfma_f32_16x16x32_bf16 v[94:97], v[136:139], v[206:209], v[94:97]
	v_mfma_f32_16x16x32_bf16 v[90:93], v[144:147], v[206:209], v[90:93]
	v_mfma_f32_16x16x32_bf16 v[78:81], v[136:139], v[214:217], v[78:81]
	v_mfma_f32_16x16x32_bf16 v[74:77], v[144:147], v[214:217], v[74:77]
	s_setprio 0
	s_setprio 1
	v_mfma_f32_16x16x32_bf16 v[126:129], v[148:151], v[186:189], v[126:129]
	v_mfma_f32_16x16x32_bf16 v[114:117], v[174:177], v[186:189], v[114:117]
	v_mfma_f32_16x16x32_bf16 v[102:105], v[148:151], v[194:197], v[102:105]
	v_mfma_f32_16x16x32_bf16 v[98:101], v[174:177], v[194:197], v[98:101]
	v_mfma_f32_16x16x32_bf16 v[86:89], v[148:151], v[202:205], v[86:89]
	v_mfma_f32_16x16x32_bf16 v[82:85], v[174:177], v[202:205], v[82:85]
	v_mfma_f32_16x16x32_bf16 v[70:73], v[148:151], v[210:213], v[70:73]
	v_mfma_f32_16x16x32_bf16 v[66:69], v[174:177], v[210:213], v[66:69]
	v_mfma_f32_16x16x32_bf16 v[126:129], v[170:173], v[190:193], v[126:129]
	v_mfma_f32_16x16x32_bf16 v[114:117], v[178:181], v[190:193], v[114:117]
	v_mfma_f32_16x16x32_bf16 v[102:105], v[170:173], v[198:201], v[102:105]
	v_mfma_f32_16x16x32_bf16 v[98:101], v[178:181], v[198:201], v[98:101]
	v_mfma_f32_16x16x32_bf16 v[86:89], v[170:173], v[206:209], v[86:89]
	v_mfma_f32_16x16x32_bf16 v[82:85], v[178:181], v[206:209], v[82:85]
	v_mfma_f32_16x16x32_bf16 v[70:73], v[170:173], v[214:217], v[70:73]
	v_mfma_f32_16x16x32_bf16 v[66:69], v[178:181], v[214:217], v[66:69]
	s_setprio 0
	s_barrier
	s_mov_b32 m0, s63
	s_mov_b64 s[98:99], s[42:43]
	s_add_u32 s72, s42, 0x100000
	ds_read_b128 v[186:189], v184 offset:16384
	ds_read_b128 v[190:193], v184 offset:17408
	ds_read_b128 v[194:197], v184 offset:18432
	ds_read_b128 v[198:201], v184 offset:19456
	ds_read_b128 v[202:205], v184 offset:20480
	ds_read_b128 v[206:209], v184 offset:21504
	ds_read_b128 v[210:213], v184 offset:22528
	ds_read_b128 v[214:217], v184 offset:23552
	global_load_lds_dwordx4 v156, s[42:43]
	s_mov_b32 m0, s64
	s_addc_u32 s73, s43, 0
	global_load_lds_dwordx4 v160, s[42:43]
	s_mov_b32 m0, s69
	s_mov_b64 s[100:101], s[50:51]
	global_load_lds_dwordx4 v156, s[72:73]
	s_mov_b32 m0, s46
	s_nop 0
	global_load_lds_dwordx4 v160, s[72:73]
	s_mov_b32 m0, s13
	s_nop 0
	global_load_lds_dwordx4 v154, s[50:51]
	s_mov_b32 m0, s33
	s_nop 0
	global_load_lds_dwordx4 v158, s[50:51]
	s_waitcnt vmcnt(8)
	s_waitcnt lgkmcnt(0)
	s_barrier
	s_setprio 1
	s_waitcnt lgkmcnt(0)
	v_mfma_f32_16x16x32_bf16 v[58:61], v[132:135], v[186:189], v[58:61]
	v_mfma_f32_16x16x32_bf16 v[54:57], v[140:143], v[186:189], v[54:57]
	v_mfma_f32_16x16x32_bf16 v[46:49], v[132:135], v[194:197], v[46:49]
	v_mfma_f32_16x16x32_bf16 v[42:45], v[140:143], v[194:197], v[42:45]
	v_mfma_f32_16x16x32_bf16 v[30:33], v[132:135], v[202:205], v[30:33]
	v_mfma_f32_16x16x32_bf16 v[26:29], v[140:143], v[202:205], v[26:29]
	v_mfma_f32_16x16x32_bf16 v[14:17], v[132:135], v[210:213], v[14:17]
	v_mfma_f32_16x16x32_bf16 v[10:13], v[140:143], v[210:213], v[10:13]
	v_mfma_f32_16x16x32_bf16 v[58:61], v[136:139], v[190:193], v[58:61]
	v_mfma_f32_16x16x32_bf16 v[54:57], v[144:147], v[190:193], v[54:57]
	v_mfma_f32_16x16x32_bf16 v[46:49], v[136:139], v[198:201], v[46:49]
	v_mfma_f32_16x16x32_bf16 v[42:45], v[144:147], v[198:201], v[42:45]
	v_mfma_f32_16x16x32_bf16 v[30:33], v[136:139], v[206:209], v[30:33]
	v_mfma_f32_16x16x32_bf16 v[26:29], v[144:147], v[206:209], v[26:29]
	v_mfma_f32_16x16x32_bf16 v[14:17], v[136:139], v[214:217], v[14:17]
	v_mfma_f32_16x16x32_bf16 v[10:13], v[144:147], v[214:217], v[10:13]
	s_setprio 0
	s_setprio 1
	v_mfma_f32_16x16x32_bf16 v[62:65], v[148:151], v[186:189], v[62:65]
	v_mfma_f32_16x16x32_bf16 v[50:53], v[174:177], v[186:189], v[50:53]
	v_mfma_f32_16x16x32_bf16 v[38:41], v[148:151], v[194:197], v[38:41]
	v_mfma_f32_16x16x32_bf16 v[34:37], v[174:177], v[194:197], v[34:37]
	v_mfma_f32_16x16x32_bf16 v[22:25], v[148:151], v[202:205], v[22:25]
	v_mfma_f32_16x16x32_bf16 v[18:21], v[174:177], v[202:205], v[18:21]
	v_mfma_f32_16x16x32_bf16 v[6:9], v[148:151], v[210:213], v[6:9]
	v_mfma_f32_16x16x32_bf16 v[2:5], v[174:177], v[210:213], v[2:5]
	v_mfma_f32_16x16x32_bf16 v[62:65], v[170:173], v[190:193], v[62:65]
	v_mfma_f32_16x16x32_bf16 v[50:53], v[178:181], v[190:193], v[50:53]
	v_mfma_f32_16x16x32_bf16 v[38:41], v[170:173], v[198:201], v[38:41]
	v_mfma_f32_16x16x32_bf16 v[34:37], v[178:181], v[198:201], v[34:37]
	v_mfma_f32_16x16x32_bf16 v[22:25], v[170:173], v[206:209], v[22:25]
	v_mfma_f32_16x16x32_bf16 v[18:21], v[178:181], v[206:209], v[18:21]
	v_mfma_f32_16x16x32_bf16 v[6:9], v[170:173], v[214:217], v[6:9]
	v_mfma_f32_16x16x32_bf16 v[2:5], v[178:181], v[214:217], v[2:5]
	s_setprio 0
	s_barrier
	ds_read_b128 v[132:135], v130
	ds_read_b128 v[136:139], v130 offset:1024
	ds_read_b128 v[140:143], v130 offset:2048
	ds_read_b128 v[144:147], v130 offset:3072
	ds_read_b128 v[148:151], v131
	ds_read_b128 v[170:173], v131 offset:1024
	ds_read_b128 v[174:177], v131 offset:2048
	ds_read_b128 v[178:181], v131 offset:3072
	s_add_u32 s50, s50, 0x100000
	s_addc_u32 s51, s51, 0
	s_mov_b32 m0, s52
	ds_read_b128 v[186:189], v184 offset:32768
	ds_read_b128 v[190:193], v184 offset:33792
	ds_read_b128 v[194:197], v184 offset:34816
	ds_read_b128 v[198:201], v184 offset:35840
	ds_read_b128 v[202:205], v184 offset:36864
	ds_read_b128 v[206:209], v184 offset:37888
	ds_read_b128 v[210:213], v184 offset:38912
	ds_read_b128 v[214:217], v184 offset:39936
	global_load_lds_dwordx4 v154, s[50:51]
	s_mov_b32 m0, s53
	s_nop 0
	global_load_lds_dwordx4 v158, s[50:51]
	s_waitcnt vmcnt(8)
	s_waitcnt lgkmcnt(0)
	s_barrier
	s_setprio 1
	s_waitcnt lgkmcnt(0)
	v_mfma_f32_16x16x32_bf16 v[122:125], v[132:135], v[186:189], v[122:125]
	v_mfma_f32_16x16x32_bf16 v[118:121], v[140:143], v[186:189], v[118:121]
	v_mfma_f32_16x16x32_bf16 v[110:113], v[132:135], v[194:197], v[110:113]
	v_mfma_f32_16x16x32_bf16 v[106:109], v[140:143], v[194:197], v[106:109]
	v_mfma_f32_16x16x32_bf16 v[94:97], v[132:135], v[202:205], v[94:97]
	v_mfma_f32_16x16x32_bf16 v[90:93], v[140:143], v[202:205], v[90:93]
	v_mfma_f32_16x16x32_bf16 v[78:81], v[132:135], v[210:213], v[78:81]
	v_mfma_f32_16x16x32_bf16 v[74:77], v[140:143], v[210:213], v[74:77]
	v_mfma_f32_16x16x32_bf16 v[122:125], v[136:139], v[190:193], v[122:125]
	v_mfma_f32_16x16x32_bf16 v[118:121], v[144:147], v[190:193], v[118:121]
	v_mfma_f32_16x16x32_bf16 v[110:113], v[136:139], v[198:201], v[110:113]
	v_mfma_f32_16x16x32_bf16 v[106:109], v[144:147], v[198:201], v[106:109]
	v_mfma_f32_16x16x32_bf16 v[94:97], v[136:139], v[206:209], v[94:97]
	v_mfma_f32_16x16x32_bf16 v[90:93], v[144:147], v[206:209], v[90:93]
	v_mfma_f32_16x16x32_bf16 v[78:81], v[136:139], v[214:217], v[78:81]
	v_mfma_f32_16x16x32_bf16 v[74:77], v[144:147], v[214:217], v[74:77]
	s_setprio 0
	s_setprio 1
	v_mfma_f32_16x16x32_bf16 v[126:129], v[148:151], v[186:189], v[126:129]
	v_mfma_f32_16x16x32_bf16 v[114:117], v[174:177], v[186:189], v[114:117]
	v_mfma_f32_16x16x32_bf16 v[102:105], v[148:151], v[194:197], v[102:105]
	v_mfma_f32_16x16x32_bf16 v[98:101], v[174:177], v[194:197], v[98:101]
	v_mfma_f32_16x16x32_bf16 v[86:89], v[148:151], v[202:205], v[86:89]
	v_mfma_f32_16x16x32_bf16 v[82:85], v[174:177], v[202:205], v[82:85]
	v_mfma_f32_16x16x32_bf16 v[70:73], v[148:151], v[210:213], v[70:73]
	v_mfma_f32_16x16x32_bf16 v[66:69], v[174:177], v[210:213], v[66:69]
	v_mfma_f32_16x16x32_bf16 v[126:129], v[170:173], v[190:193], v[126:129]
	v_mfma_f32_16x16x32_bf16 v[114:117], v[178:181], v[190:193], v[114:117]
	v_mfma_f32_16x16x32_bf16 v[102:105], v[170:173], v[198:201], v[102:105]
	v_mfma_f32_16x16x32_bf16 v[98:101], v[178:181], v[198:201], v[98:101]
	v_mfma_f32_16x16x32_bf16 v[86:89], v[170:173], v[206:209], v[86:89]
	v_mfma_f32_16x16x32_bf16 v[82:85], v[178:181], v[206:209], v[82:85]
	v_mfma_f32_16x16x32_bf16 v[70:73], v[170:173], v[214:217], v[70:73]
	v_mfma_f32_16x16x32_bf16 v[66:69], v[178:181], v[214:217], v[66:69]
	s_setprio 0
	s_barrier
	s_mov_b32 m0, s47
	s_add_u32 s98, s98, 0x80
	s_addc_u32 s99, s99, 0
	s_add_u32 s100, s100, 0x80
	s_addc_u32 s101, s101, 0
	s_add_u32 s42, s42, 0x100080
	ds_read_b128 v[186:189], v184 offset:49152
	ds_read_b128 v[190:193], v184 offset:50176
	ds_read_b128 v[194:197], v184 offset:51200
	ds_read_b128 v[198:201], v184 offset:52224
	ds_read_b128 v[202:205], v184 offset:53248
	ds_read_b128 v[206:209], v184 offset:54272
	ds_read_b128 v[210:213], v184 offset:55296
	ds_read_b128 v[214:217], v184 offset:56320
	global_load_lds_dwordx4 v156, s[98:99]
	s_mov_b32 m0, s70
	s_addc_u32 s43, s43, 0
	global_load_lds_dwordx4 v160, s[98:99]
	s_mov_b32 m0, s56
	s_nop 0
	global_load_lds_dwordx4 v156, s[42:43]
	s_mov_b32 m0, s57
	s_nop 0
	global_load_lds_dwordx4 v160, s[42:43]
	s_mov_b32 m0, s54
	s_nop 0
	global_load_lds_dwordx4 v154, s[100:101]
	s_mov_b32 m0, s55
	s_nop 0
	global_load_lds_dwordx4 v158, s[100:101]
	s_waitcnt vmcnt(8)
	s_waitcnt lgkmcnt(0)
	s_barrier
	s_setprio 1
	s_waitcnt lgkmcnt(0)
	v_mfma_f32_16x16x32_bf16 v[58:61], v[132:135], v[186:189], v[58:61]
	v_mfma_f32_16x16x32_bf16 v[54:57], v[140:143], v[186:189], v[54:57]
	v_mfma_f32_16x16x32_bf16 v[46:49], v[132:135], v[194:197], v[46:49]
	v_mfma_f32_16x16x32_bf16 v[42:45], v[140:143], v[194:197], v[42:45]
	v_mfma_f32_16x16x32_bf16 v[30:33], v[132:135], v[202:205], v[30:33]
	v_mfma_f32_16x16x32_bf16 v[26:29], v[140:143], v[202:205], v[26:29]
	v_mfma_f32_16x16x32_bf16 v[14:17], v[132:135], v[210:213], v[14:17]
	v_mfma_f32_16x16x32_bf16 v[10:13], v[140:143], v[210:213], v[10:13]
	v_mfma_f32_16x16x32_bf16 v[58:61], v[136:139], v[190:193], v[58:61]
	v_mfma_f32_16x16x32_bf16 v[54:57], v[144:147], v[190:193], v[54:57]
	v_mfma_f32_16x16x32_bf16 v[46:49], v[136:139], v[198:201], v[46:49]
	v_mfma_f32_16x16x32_bf16 v[42:45], v[144:147], v[198:201], v[42:45]
	v_mfma_f32_16x16x32_bf16 v[30:33], v[136:139], v[206:209], v[30:33]
	v_mfma_f32_16x16x32_bf16 v[26:29], v[144:147], v[206:209], v[26:29]
	v_mfma_f32_16x16x32_bf16 v[14:17], v[136:139], v[214:217], v[14:17]
	v_mfma_f32_16x16x32_bf16 v[10:13], v[144:147], v[214:217], v[10:13]
	s_setprio 0
	s_setprio 1
	v_mfma_f32_16x16x32_bf16 v[62:65], v[148:151], v[186:189], v[62:65]
	v_mfma_f32_16x16x32_bf16 v[50:53], v[174:177], v[186:189], v[50:53]
	v_mfma_f32_16x16x32_bf16 v[38:41], v[148:151], v[194:197], v[38:41]
	v_mfma_f32_16x16x32_bf16 v[34:37], v[174:177], v[194:197], v[34:37]
	v_mfma_f32_16x16x32_bf16 v[22:25], v[148:151], v[202:205], v[22:25]
	v_mfma_f32_16x16x32_bf16 v[18:21], v[174:177], v[202:205], v[18:21]
	v_mfma_f32_16x16x32_bf16 v[6:9], v[148:151], v[210:213], v[6:9]
	v_mfma_f32_16x16x32_bf16 v[2:5], v[174:177], v[210:213], v[2:5]
	v_mfma_f32_16x16x32_bf16 v[62:65], v[170:173], v[190:193], v[62:65]
	v_mfma_f32_16x16x32_bf16 v[50:53], v[178:181], v[190:193], v[50:53]
	v_mfma_f32_16x16x32_bf16 v[38:41], v[170:173], v[198:201], v[38:41]
	v_mfma_f32_16x16x32_bf16 v[34:37], v[178:181], v[198:201], v[34:37]
	v_mfma_f32_16x16x32_bf16 v[22:25], v[170:173], v[206:209], v[22:25]
	v_mfma_f32_16x16x32_bf16 v[18:21], v[178:181], v[206:209], v[18:21]
	v_mfma_f32_16x16x32_bf16 v[6:9], v[170:173], v[214:217], v[6:9]
	v_mfma_f32_16x16x32_bf16 v[2:5], v[178:181], v[214:217], v[2:5]
	s_setprio 0
	s_barrier
	s_add_i32 s26, s26, 2
	s_add_u32 s48, s48, 0x100
	s_addc_u32 s49, s49, 0
	s_add_u32 s14, s14, 0x100
	s_addc_u32 s15, s15, 0
	s_cmp_gt_u32 s26, 61
	s_cbranch_scc0 .LBB0_1014
	s_and_b64 vcc, exec, s[18:19]
	s_cbranch_vccz .LBB0_1017
	s_barrier

.LBB0_1110:
	ds_read_b128 v[152:155], v148
	ds_read_b128 v[156:159], v148 offset:1024
	ds_read_b128 v[160:163], v148 offset:2048
	ds_read_b128 v[164:167], v148 offset:3072
	ds_read_b128 v[168:171], v149
	ds_read_b128 v[172:175], v149 offset:1024
	ds_read_b128 v[176:179], v149 offset:2048
	ds_read_b128 v[180:183], v149 offset:3072
	s_add_u32 s27, s0, 0xfff00080
	s_addc_u32 s52, s1, -1
	s_cmp_eq_u32 s26, 28
	s_cselect_b32 s55, s43, s52
	s_cselect_b32 s54, s42, s27
	s_cselect_b32 s53, s49, s15
	s_cselect_b32 s52, s48, s14
	s_mov_b32 m0, s41
	ds_read_b128 v[184:187], v150
	ds_read_b128 v[188:191], v150 offset:1024
	ds_read_b128 v[192:195], v150 offset:2048
	ds_read_b128 v[196:199], v150 offset:3072
	ds_read_b128 v[200:203], v150 offset:4096
	ds_read_b128 v[204:207], v150 offset:5120
	ds_read_b128 v[208:211], v150 offset:6144
	ds_read_b128 v[212:215], v150 offset:7168
	global_load_lds_dwordx4 v136, s[0:1]
	s_mov_b32 m0, s73
	s_nop 0
	global_load_lds_dwordx4 v138, s[0:1]
	s_waitcnt vmcnt(8)
	s_waitcnt lgkmcnt(0)
	s_barrier
	s_setprio 1
	s_waitcnt lgkmcnt(0)
	v_mfma_f32_16x16x32_bf16 v[118:121], v[152:155], v[184:187], v[118:121]
	v_mfma_f32_16x16x32_bf16 v[114:117], v[160:163], v[184:187], v[114:117]
	v_mfma_f32_16x16x32_bf16 v[102:105], v[152:155], v[192:195], v[102:105]
	v_mfma_f32_16x16x32_bf16 v[98:101], v[160:163], v[192:195], v[98:101]
	v_mfma_f32_16x16x32_bf16 v[86:89], v[152:155], v[200:203], v[86:89]
	v_mfma_f32_16x16x32_bf16 v[82:85], v[160:163], v[200:203], v[82:85]
	v_mfma_f32_16x16x32_bf16 v[74:77], v[152:155], v[208:211], v[74:77]
	v_mfma_f32_16x16x32_bf16 v[54:57], v[160:163], v[208:211], v[54:57]
	v_mfma_f32_16x16x32_bf16 v[118:121], v[156:159], v[188:191], v[118:121]
	v_mfma_f32_16x16x32_bf16 v[114:117], v[164:167], v[188:191], v[114:117]
	v_mfma_f32_16x16x32_bf16 v[102:105], v[156:159], v[196:199], v[102:105]
	v_mfma_f32_16x16x32_bf16 v[98:101], v[164:167], v[196:199], v[98:101]
	v_mfma_f32_16x16x32_bf16 v[86:89], v[156:159], v[204:207], v[86:89]
	v_mfma_f32_16x16x32_bf16 v[82:85], v[164:167], v[204:207], v[82:85]
	v_mfma_f32_16x16x32_bf16 v[74:77], v[156:159], v[212:215], v[74:77]
	v_mfma_f32_16x16x32_bf16 v[54:57], v[164:167], v[212:215], v[54:57]
	s_setprio 0
	s_setprio 1
	v_mfma_f32_16x16x32_bf16 v[126:129], v[168:171], v[184:187], v[126:129]
	v_mfma_f32_16x16x32_bf16 v[122:125], v[176:179], v[184:187], v[122:125]
	v_mfma_f32_16x16x32_bf16 v[110:113], v[168:171], v[192:195], v[110:113]
	v_mfma_f32_16x16x32_bf16 v[106:109], v[176:179], v[192:195], v[106:109]
	v_mfma_f32_16x16x32_bf16 v[94:97], v[168:171], v[200:203], v[94:97]
	v_mfma_f32_16x16x32_bf16 v[90:93], v[176:179], v[200:203], v[90:93]
	v_mfma_f32_16x16x32_bf16 v[70:73], v[168:171], v[208:211], v[70:73]
	v_mfma_f32_16x16x32_bf16 v[50:53], v[176:179], v[208:211], v[50:53]
	v_mfma_f32_16x16x32_bf16 v[126:129], v[172:175], v[188:191], v[126:129]
	v_mfma_f32_16x16x32_bf16 v[122:125], v[180:183], v[188:191], v[122:125]
	v_mfma_f32_16x16x32_bf16 v[110:113], v[172:175], v[196:199], v[110:113]
	v_mfma_f32_16x16x32_bf16 v[106:109], v[180:183], v[196:199], v[106:109]
	v_mfma_f32_16x16x32_bf16 v[94:97], v[172:175], v[204:207], v[94:97]
	v_mfma_f32_16x16x32_bf16 v[90:93], v[180:183], v[204:207], v[90:93]
	v_mfma_f32_16x16x32_bf16 v[70:73], v[172:175], v[212:215], v[70:73]
	v_mfma_f32_16x16x32_bf16 v[50:53], v[180:183], v[212:215], v[50:53]
	s_setprio 0
	s_barrier
	s_mov_b32 m0, s74
	s_mov_b64 s[98:99], s[52:53]
	s_add_u32 s78, s52, 0x100000
	ds_read_b128 v[184:187], v150 offset:16384
	ds_read_b128 v[188:191], v150 offset:17408
	ds_read_b128 v[192:195], v150 offset:18432
	ds_read_b128 v[196:199], v150 offset:19456
	ds_read_b128 v[200:203], v150 offset:20480
	ds_read_b128 v[204:207], v150 offset:21504
	ds_read_b128 v[208:211], v150 offset:22528
	ds_read_b128 v[212:215], v150 offset:23552
	global_load_lds_dwordx4 v130, s[52:53]
	s_mov_b32 m0, s75
	s_addc_u32 s79, s53, 0
	global_load_lds_dwordx4 v132, s[52:53]
	s_mov_b32 m0, s76
	s_mov_b64 s[100:101], s[54:55]
	global_load_lds_dwordx4 v130, s[78:79]
	s_mov_b32 m0, s46
	s_nop 0
	global_load_lds_dwordx4 v132, s[78:79]
	s_mov_b32 m0, s33
	s_nop 0
	global_load_lds_dwordx4 v130, s[54:55]
	s_mov_b32 m0, s51
	s_nop 0
	global_load_lds_dwordx4 v132, s[54:55]
	s_waitcnt vmcnt(8)
	s_waitcnt lgkmcnt(0)
	s_barrier
	s_setprio 1
	s_waitcnt lgkmcnt(0)
	v_mfma_f32_16x16x32_bf16 v[66:69], v[152:155], v[184:187], v[66:69]
	v_mfma_f32_16x16x32_bf16 v[62:65], v[160:163], v[184:187], v[62:65]
	v_mfma_f32_16x16x32_bf16 v[42:45], v[152:155], v[192:195], v[42:45]
	v_mfma_f32_16x16x32_bf16 v[38:41], v[160:163], v[192:195], v[38:41]
	v_mfma_f32_16x16x32_bf16 v[26:29], v[152:155], v[200:203], v[26:29]
	v_mfma_f32_16x16x32_bf16 v[22:25], v[160:163], v[200:203], v[22:25]
	v_mfma_f32_16x16x32_bf16 v[6:9], v[152:155], v[208:211], v[6:9]
	v_mfma_f32_16x16x32_bf16 v[2:5], v[160:163], v[208:211], v[2:5]
	v_mfma_f32_16x16x32_bf16 v[66:69], v[156:159], v[188:191], v[66:69]
	v_mfma_f32_16x16x32_bf16 v[62:65], v[164:167], v[188:191], v[62:65]
	v_mfma_f32_16x16x32_bf16 v[42:45], v[156:159], v[196:199], v[42:45]
	v_mfma_f32_16x16x32_bf16 v[38:41], v[164:167], v[196:199], v[38:41]
	v_mfma_f32_16x16x32_bf16 v[26:29], v[156:159], v[204:207], v[26:29]
	v_mfma_f32_16x16x32_bf16 v[22:25], v[164:167], v[204:207], v[22:25]
	v_mfma_f32_16x16x32_bf16 v[6:9], v[156:159], v[212:215], v[6:9]
	v_mfma_f32_16x16x32_bf16 v[2:5], v[164:167], v[212:215], v[2:5]
	s_setprio 0
	s_setprio 1
	v_mfma_f32_16x16x32_bf16 v[78:81], v[168:171], v[184:187], v[78:81]
	v_mfma_f32_16x16x32_bf16 v[58:61], v[176:179], v[184:187], v[58:61]
	v_mfma_f32_16x16x32_bf16 v[46:49], v[168:171], v[192:195], v[46:49]
	v_mfma_f32_16x16x32_bf16 v[34:37], v[176:179], v[192:195], v[34:37]
	v_mfma_f32_16x16x32_bf16 v[30:33], v[168:171], v[200:203], v[30:33]
	v_mfma_f32_16x16x32_bf16 v[18:21], v[176:179], v[200:203], v[18:21]
	v_mfma_f32_16x16x32_bf16 v[14:17], v[168:171], v[208:211], v[14:17]
	v_mfma_f32_16x16x32_bf16 v[10:13], v[176:179], v[208:211], v[10:13]
	v_mfma_f32_16x16x32_bf16 v[78:81], v[172:175], v[188:191], v[78:81]
	v_mfma_f32_16x16x32_bf16 v[58:61], v[180:183], v[188:191], v[58:61]
	v_mfma_f32_16x16x32_bf16 v[46:49], v[172:175], v[196:199], v[46:49]
	v_mfma_f32_16x16x32_bf16 v[34:37], v[180:183], v[196:199], v[34:37]
	v_mfma_f32_16x16x32_bf16 v[30:33], v[172:175], v[204:207], v[30:33]
	v_mfma_f32_16x16x32_bf16 v[18:21], v[180:183], v[204:207], v[18:21]
	v_mfma_f32_16x16x32_bf16 v[14:17], v[172:175], v[212:215], v[14:17]
	v_mfma_f32_16x16x32_bf16 v[10:13], v[180:183], v[212:215], v[10:13]
	s_setprio 0
	s_barrier
	ds_read_b128 v[152:155], v134
	ds_read_b128 v[156:159], v134 offset:1024
	ds_read_b128 v[160:163], v134 offset:2048
	ds_read_b128 v[164:167], v134 offset:3072
	ds_read_b128 v[168:171], v144
	ds_read_b128 v[172:175], v144 offset:1024
	ds_read_b128 v[176:179], v144 offset:2048
	ds_read_b128 v[180:183], v144 offset:3072
	s_add_u32 s54, s54, 0x100000
	s_addc_u32 s55, s55, 0
	s_mov_b32 m0, s58
	ds_read_b128 v[184:187], v150 offset:32768
	ds_read_b128 v[188:191], v150 offset:33792
	ds_read_b128 v[192:195], v150 offset:34816
	ds_read_b128 v[196:199], v150 offset:35840
	ds_read_b128 v[200:203], v150 offset:36864
	ds_read_b128 v[204:207], v150 offset:37888
	ds_read_b128 v[208:211], v150 offset:38912
	ds_read_b128 v[212:215], v150 offset:39936
	global_load_lds_dwordx4 v130, s[54:55]
	s_mov_b32 m0, s59
	s_nop 0
	global_load_lds_dwordx4 v132, s[54:55]
	s_waitcnt vmcnt(8)
	s_waitcnt lgkmcnt(0)
	s_barrier
	s_setprio 1
	s_waitcnt lgkmcnt(0)
	v_mfma_f32_16x16x32_bf16 v[118:121], v[152:155], v[184:187], v[118:121]
	v_mfma_f32_16x16x32_bf16 v[114:117], v[160:163], v[184:187], v[114:117]
	v_mfma_f32_16x16x32_bf16 v[102:105], v[152:155], v[192:195], v[102:105]
	v_mfma_f32_16x16x32_bf16 v[98:101], v[160:163], v[192:195], v[98:101]
	v_mfma_f32_16x16x32_bf16 v[86:89], v[152:155], v[200:203], v[86:89]
	v_mfma_f32_16x16x32_bf16 v[82:85], v[160:163], v[200:203], v[82:85]
	v_mfma_f32_16x16x32_bf16 v[74:77], v[152:155], v[208:211], v[74:77]
	v_mfma_f32_16x16x32_bf16 v[54:57], v[160:163], v[208:211], v[54:57]
	v_mfma_f32_16x16x32_bf16 v[118:121], v[156:159], v[188:191], v[118:121]
	v_mfma_f32_16x16x32_bf16 v[114:117], v[164:167], v[188:191], v[114:117]
	v_mfma_f32_16x16x32_bf16 v[102:105], v[156:159], v[196:199], v[102:105]
	v_mfma_f32_16x16x32_bf16 v[98:101], v[164:167], v[196:199], v[98:101]
	v_mfma_f32_16x16x32_bf16 v[86:89], v[156:159], v[204:207], v[86:89]
	v_mfma_f32_16x16x32_bf16 v[82:85], v[164:167], v[204:207], v[82:85]
	v_mfma_f32_16x16x32_bf16 v[74:77], v[156:159], v[212:215], v[74:77]
	v_mfma_f32_16x16x32_bf16 v[54:57], v[164:167], v[212:215], v[54:57]
	s_setprio 0
	s_setprio 1
	v_mfma_f32_16x16x32_bf16 v[126:129], v[168:171], v[184:187], v[126:129]
	v_mfma_f32_16x16x32_bf16 v[122:125], v[176:179], v[184:187], v[122:125]
	v_mfma_f32_16x16x32_bf16 v[110:113], v[168:171], v[192:195], v[110:113]
	v_mfma_f32_16x16x32_bf16 v[106:109], v[176:179], v[192:195], v[106:109]
	v_mfma_f32_16x16x32_bf16 v[94:97], v[168:171], v[200:203], v[94:97]
	v_mfma_f32_16x16x32_bf16 v[90:93], v[176:179], v[200:203], v[90:93]
	v_mfma_f32_16x16x32_bf16 v[70:73], v[168:171], v[208:211], v[70:73]
	v_mfma_f32_16x16x32_bf16 v[50:53], v[176:179], v[208:211], v[50:53]
	v_mfma_f32_16x16x32_bf16 v[126:129], v[172:175], v[188:191], v[126:129]
	v_mfma_f32_16x16x32_bf16 v[122:125], v[180:183], v[188:191], v[122:125]
	v_mfma_f32_16x16x32_bf16 v[110:113], v[172:175], v[196:199], v[110:113]
	v_mfma_f32_16x16x32_bf16 v[106:109], v[180:183], v[196:199], v[106:109]
	v_mfma_f32_16x16x32_bf16 v[94:97], v[172:175], v[204:207], v[94:97]
	v_mfma_f32_16x16x32_bf16 v[90:93], v[180:183], v[204:207], v[90:93]
	v_mfma_f32_16x16x32_bf16 v[70:73], v[172:175], v[212:215], v[70:73]
	v_mfma_f32_16x16x32_bf16 v[50:53], v[180:183], v[212:215], v[50:53]
	s_setprio 0
	s_barrier
	s_mov_b32 m0, s47
	s_add_u32 s98, s98, 0x80
	s_addc_u32 s99, s99, 0
	s_add_u32 s100, s100, 0x80
	s_addc_u32 s101, s101, 0
	s_add_u32 s52, s52, 0x100080
	ds_read_b128 v[184:187], v150 offset:49152
	ds_read_b128 v[188:191], v150 offset:50176
	ds_read_b128 v[192:195], v150 offset:51200
	ds_read_b128 v[196:199], v150 offset:52224
	ds_read_b128 v[200:203], v150 offset:53248
	ds_read_b128 v[204:207], v150 offset:54272
	ds_read_b128 v[208:211], v150 offset:55296
	ds_read_b128 v[212:215], v150 offset:56320
	global_load_lds_dwordx4 v130, s[98:99]
	s_mov_b32 m0, s77
	s_addc_u32 s53, s53, 0
	global_load_lds_dwordx4 v132, s[98:99]
	s_mov_b32 m0, s56
	s_nop 0
	global_load_lds_dwordx4 v130, s[52:53]
	s_mov_b32 m0, s57
	s_nop 0
	global_load_lds_dwordx4 v132, s[52:53]
	s_mov_b32 m0, s61
	s_nop 0
	global_load_lds_dwordx4 v130, s[100:101]
	s_mov_b32 m0, s62
	s_nop 0
	global_load_lds_dwordx4 v132, s[100:101]
	s_waitcnt vmcnt(8)
	s_waitcnt lgkmcnt(0)
	s_barrier
	s_setprio 1
	s_waitcnt lgkmcnt(0)
	v_mfma_f32_16x16x32_bf16 v[66:69], v[152:155], v[184:187], v[66:69]
	v_mfma_f32_16x16x32_bf16 v[62:65], v[160:163], v[184:187], v[62:65]
	v_mfma_f32_16x16x32_bf16 v[42:45], v[152:155], v[192:195], v[42:45]
	v_mfma_f32_16x16x32_bf16 v[38:41], v[160:163], v[192:195], v[38:41]
	v_mfma_f32_16x16x32_bf16 v[26:29], v[152:155], v[200:203], v[26:29]
	v_mfma_f32_16x16x32_bf16 v[22:25], v[160:163], v[200:203], v[22:25]
	v_mfma_f32_16x16x32_bf16 v[6:9], v[152:155], v[208:211], v[6:9]
	v_mfma_f32_16x16x32_bf16 v[2:5], v[160:163], v[208:211], v[2:5]
	v_mfma_f32_16x16x32_bf16 v[66:69], v[156:159], v[188:191], v[66:69]
	v_mfma_f32_16x16x32_bf16 v[62:65], v[164:167], v[188:191], v[62:65]
	v_mfma_f32_16x16x32_bf16 v[42:45], v[156:159], v[196:199], v[42:45]
	v_mfma_f32_16x16x32_bf16 v[38:41], v[164:167], v[196:199], v[38:41]
	v_mfma_f32_16x16x32_bf16 v[26:29], v[156:159], v[204:207], v[26:29]
	v_mfma_f32_16x16x32_bf16 v[22:25], v[164:167], v[204:207], v[22:25]
	v_mfma_f32_16x16x32_bf16 v[6:9], v[156:159], v[212:215], v[6:9]
	v_mfma_f32_16x16x32_bf16 v[2:5], v[164:167], v[212:215], v[2:5]
	s_setprio 0
	s_setprio 1
	v_mfma_f32_16x16x32_bf16 v[78:81], v[168:171], v[184:187], v[78:81]
	v_mfma_f32_16x16x32_bf16 v[58:61], v[176:179], v[184:187], v[58:61]
	v_mfma_f32_16x16x32_bf16 v[46:49], v[168:171], v[192:195], v[46:49]
	v_mfma_f32_16x16x32_bf16 v[34:37], v[176:179], v[192:195], v[34:37]
	v_mfma_f32_16x16x32_bf16 v[30:33], v[168:171], v[200:203], v[30:33]
	v_mfma_f32_16x16x32_bf16 v[18:21], v[176:179], v[200:203], v[18:21]
	v_mfma_f32_16x16x32_bf16 v[14:17], v[168:171], v[208:211], v[14:17]
	v_mfma_f32_16x16x32_bf16 v[10:13], v[176:179], v[208:211], v[10:13]
	v_mfma_f32_16x16x32_bf16 v[78:81], v[172:175], v[188:191], v[78:81]
	v_mfma_f32_16x16x32_bf16 v[58:61], v[180:183], v[188:191], v[58:61]
	v_mfma_f32_16x16x32_bf16 v[46:49], v[172:175], v[196:199], v[46:49]
	v_mfma_f32_16x16x32_bf16 v[34:37], v[180:183], v[196:199], v[34:37]
	v_mfma_f32_16x16x32_bf16 v[30:33], v[172:175], v[204:207], v[30:33]
	v_mfma_f32_16x16x32_bf16 v[18:21], v[180:183], v[204:207], v[18:21]
	v_mfma_f32_16x16x32_bf16 v[14:17], v[172:175], v[212:215], v[14:17]
	v_mfma_f32_16x16x32_bf16 v[10:13], v[180:183], v[212:215], v[10:13]
	s_setprio 0
	s_barrier
	s_add_i32 s26, s26, 2
	s_add_u32 s0, s0, 0x100
	s_addc_u32 s1, s1, 0
	s_add_u32 s14, s14, 0x100
	s_addc_u32 s15, s15, 0
	s_cmp_gt_u32 s26, 29
	s_cbranch_scc0 .LBB0_1110
	s_and_b64 vcc, exec, s[18:19]
	s_cbranch_vccz .LBB0_1113
	s_barrier

.LBB0_1261:
	ds_read_b128 v[132:135], v182
	ds_read_b128 v[136:139], v182 offset:1024
	ds_read_b128 v[140:143], v182 offset:2048
	ds_read_b128 v[144:147], v182 offset:3072
	ds_read_b128 v[148:151], v183
	ds_read_b128 v[170:173], v183 offset:1024
	ds_read_b128 v[174:177], v183 offset:2048
	ds_read_b128 v[178:181], v183 offset:3072
	s_add_u32 s38, s40, 0xfffe0080
	s_addc_u32 s39, s41, -1
	s_cmp_eq_u32 s69, 4
	s_cselect_b32 s43, s23, s39
	s_cselect_b32 s42, s31, s38
	s_cselect_b32 s39, s0, s27
	s_cselect_b32 s38, s66, s26
	s_mov_b32 m0, s59
	ds_read_b128 v[186:189], v184
	ds_read_b128 v[190:193], v184 offset:1024
	ds_read_b128 v[194:197], v184 offset:2048
	ds_read_b128 v[198:201], v184 offset:3072
	ds_read_b128 v[202:205], v184 offset:4096
	ds_read_b128 v[206:209], v184 offset:5120
	ds_read_b128 v[210:213], v184 offset:6144
	ds_read_b128 v[214:217], v184 offset:7168
	global_load_lds_dwordx4 v162, s[40:41]
	s_mov_b32 m0, s60
	s_nop 0
	global_load_lds_dwordx4 v164, s[40:41]
	s_waitcnt vmcnt(8)
	s_waitcnt lgkmcnt(0)
	s_barrier
	s_setprio 1
	s_waitcnt lgkmcnt(0)
	v_mfma_f32_16x16x32_bf16 v[122:125], v[132:135], v[186:189], v[122:125]
	v_mfma_f32_16x16x32_bf16 v[118:121], v[140:143], v[186:189], v[118:121]
	v_mfma_f32_16x16x32_bf16 v[110:113], v[132:135], v[194:197], v[110:113]
	v_mfma_f32_16x16x32_bf16 v[106:109], v[140:143], v[194:197], v[106:109]
	v_mfma_f32_16x16x32_bf16 v[94:97], v[132:135], v[202:205], v[94:97]
	v_mfma_f32_16x16x32_bf16 v[90:93], v[140:143], v[202:205], v[90:93]
	v_mfma_f32_16x16x32_bf16 v[78:81], v[132:135], v[210:213], v[78:81]
	v_mfma_f32_16x16x32_bf16 v[74:77], v[140:143], v[210:213], v[74:77]
	v_mfma_f32_16x16x32_bf16 v[122:125], v[136:139], v[190:193], v[122:125]
	v_mfma_f32_16x16x32_bf16 v[118:121], v[144:147], v[190:193], v[118:121]
	v_mfma_f32_16x16x32_bf16 v[110:113], v[136:139], v[198:201], v[110:113]
	v_mfma_f32_16x16x32_bf16 v[106:109], v[144:147], v[198:201], v[106:109]
	v_mfma_f32_16x16x32_bf16 v[94:97], v[136:139], v[206:209], v[94:97]
	v_mfma_f32_16x16x32_bf16 v[90:93], v[144:147], v[206:209], v[90:93]
	v_mfma_f32_16x16x32_bf16 v[78:81], v[136:139], v[214:217], v[78:81]
	v_mfma_f32_16x16x32_bf16 v[74:77], v[144:147], v[214:217], v[74:77]
	s_setprio 0
	s_setprio 1
	v_mfma_f32_16x16x32_bf16 v[126:129], v[148:151], v[186:189], v[126:129]
	v_mfma_f32_16x16x32_bf16 v[114:117], v[174:177], v[186:189], v[114:117]
	v_mfma_f32_16x16x32_bf16 v[102:105], v[148:151], v[194:197], v[102:105]
	v_mfma_f32_16x16x32_bf16 v[98:101], v[174:177], v[194:197], v[98:101]
	v_mfma_f32_16x16x32_bf16 v[86:89], v[148:151], v[202:205], v[86:89]
	v_mfma_f32_16x16x32_bf16 v[82:85], v[174:177], v[202:205], v[82:85]
	v_mfma_f32_16x16x32_bf16 v[70:73], v[148:151], v[210:213], v[70:73]
	v_mfma_f32_16x16x32_bf16 v[66:69], v[174:177], v[210:213], v[66:69]
	v_mfma_f32_16x16x32_bf16 v[126:129], v[170:173], v[190:193], v[126:129]
	v_mfma_f32_16x16x32_bf16 v[114:117], v[178:181], v[190:193], v[114:117]
	v_mfma_f32_16x16x32_bf16 v[102:105], v[170:173], v[198:201], v[102:105]
	v_mfma_f32_16x16x32_bf16 v[98:101], v[178:181], v[198:201], v[98:101]
	v_mfma_f32_16x16x32_bf16 v[86:89], v[170:173], v[206:209], v[86:89]
	v_mfma_f32_16x16x32_bf16 v[82:85], v[178:181], v[206:209], v[82:85]
	v_mfma_f32_16x16x32_bf16 v[70:73], v[170:173], v[214:217], v[70:73]
	v_mfma_f32_16x16x32_bf16 v[66:69], v[178:181], v[214:217], v[66:69]
	s_setprio 0
	s_barrier
	s_mov_b32 m0, s61
	s_mov_b64 s[98:99], s[38:39]
	s_add_u32 s70, s38, 0x20000
	ds_read_b128 v[186:189], v184 offset:16384
	ds_read_b128 v[190:193], v184 offset:17408
	ds_read_b128 v[194:197], v184 offset:18432
	ds_read_b128 v[198:201], v184 offset:19456
	ds_read_b128 v[202:205], v184 offset:20480
	ds_read_b128 v[206:209], v184 offset:21504
	ds_read_b128 v[210:213], v184 offset:22528
	ds_read_b128 v[214:217], v184 offset:23552
	global_load_lds_dwordx4 v156, s[38:39]
	s_mov_b32 m0, s62
	s_addc_u32 s71, s39, 0
	global_load_lds_dwordx4 v160, s[38:39]
	s_mov_b32 m0, s67
	s_mov_b64 s[100:101], s[42:43]
	global_load_lds_dwordx4 v156, s[70:71]
	s_mov_b32 m0, s46
	s_nop 0
	global_load_lds_dwordx4 v160, s[70:71]
	s_mov_b32 m0, s48
	s_nop 0
	global_load_lds_dwordx4 v154, s[42:43]
	s_mov_b32 m0, s49
	s_nop 0
	global_load_lds_dwordx4 v158, s[42:43]
	s_waitcnt vmcnt(8)
	s_waitcnt lgkmcnt(0)
	s_barrier
	s_setprio 1
	s_waitcnt lgkmcnt(0)
	v_mfma_f32_16x16x32_bf16 v[58:61], v[132:135], v[186:189], v[58:61]
	v_mfma_f32_16x16x32_bf16 v[54:57], v[140:143], v[186:189], v[54:57]
	v_mfma_f32_16x16x32_bf16 v[46:49], v[132:135], v[194:197], v[46:49]
	v_mfma_f32_16x16x32_bf16 v[42:45], v[140:143], v[194:197], v[42:45]
	v_mfma_f32_16x16x32_bf16 v[30:33], v[132:135], v[202:205], v[30:33]
	v_mfma_f32_16x16x32_bf16 v[26:29], v[140:143], v[202:205], v[26:29]
	v_mfma_f32_16x16x32_bf16 v[14:17], v[132:135], v[210:213], v[14:17]
	v_mfma_f32_16x16x32_bf16 v[10:13], v[140:143], v[210:213], v[10:13]
	v_mfma_f32_16x16x32_bf16 v[58:61], v[136:139], v[190:193], v[58:61]
	v_mfma_f32_16x16x32_bf16 v[54:57], v[144:147], v[190:193], v[54:57]
	v_mfma_f32_16x16x32_bf16 v[46:49], v[136:139], v[198:201], v[46:49]
	v_mfma_f32_16x16x32_bf16 v[42:45], v[144:147], v[198:201], v[42:45]
	v_mfma_f32_16x16x32_bf16 v[30:33], v[136:139], v[206:209], v[30:33]
	v_mfma_f32_16x16x32_bf16 v[26:29], v[144:147], v[206:209], v[26:29]
	v_mfma_f32_16x16x32_bf16 v[14:17], v[136:139], v[214:217], v[14:17]
	v_mfma_f32_16x16x32_bf16 v[10:13], v[144:147], v[214:217], v[10:13]
	s_setprio 0
	s_setprio 1
	v_mfma_f32_16x16x32_bf16 v[62:65], v[148:151], v[186:189], v[62:65]
	v_mfma_f32_16x16x32_bf16 v[50:53], v[174:177], v[186:189], v[50:53]
	v_mfma_f32_16x16x32_bf16 v[38:41], v[148:151], v[194:197], v[38:41]
	v_mfma_f32_16x16x32_bf16 v[34:37], v[174:177], v[194:197], v[34:37]
	v_mfma_f32_16x16x32_bf16 v[22:25], v[148:151], v[202:205], v[22:25]
	v_mfma_f32_16x16x32_bf16 v[18:21], v[174:177], v[202:205], v[18:21]
	v_mfma_f32_16x16x32_bf16 v[6:9], v[148:151], v[210:213], v[6:9]
	v_mfma_f32_16x16x32_bf16 v[2:5], v[174:177], v[210:213], v[2:5]
	v_mfma_f32_16x16x32_bf16 v[62:65], v[170:173], v[190:193], v[62:65]
	v_mfma_f32_16x16x32_bf16 v[50:53], v[178:181], v[190:193], v[50:53]
	v_mfma_f32_16x16x32_bf16 v[38:41], v[170:173], v[198:201], v[38:41]
	v_mfma_f32_16x16x32_bf16 v[34:37], v[178:181], v[198:201], v[34:37]
	v_mfma_f32_16x16x32_bf16 v[22:25], v[170:173], v[206:209], v[22:25]
	v_mfma_f32_16x16x32_bf16 v[18:21], v[178:181], v[206:209], v[18:21]
	v_mfma_f32_16x16x32_bf16 v[6:9], v[170:173], v[214:217], v[6:9]
	v_mfma_f32_16x16x32_bf16 v[2:5], v[178:181], v[214:217], v[2:5]
	s_setprio 0
	s_barrier
	ds_read_b128 v[132:135], v130
	ds_read_b128 v[136:139], v130 offset:1024
	ds_read_b128 v[140:143], v130 offset:2048
	ds_read_b128 v[144:147], v130 offset:3072
	ds_read_b128 v[148:151], v131
	ds_read_b128 v[170:173], v131 offset:1024
	ds_read_b128 v[174:177], v131 offset:2048
	ds_read_b128 v[178:181], v131 offset:3072
	s_add_u32 s42, s42, 0x20000
	s_addc_u32 s43, s43, 0
	s_mov_b32 m0, s50
	ds_read_b128 v[186:189], v184 offset:32768
	ds_read_b128 v[190:193], v184 offset:33792
	ds_read_b128 v[194:197], v184 offset:34816
	ds_read_b128 v[198:201], v184 offset:35840
	ds_read_b128 v[202:205], v184 offset:36864
	ds_read_b128 v[206:209], v184 offset:37888
	ds_read_b128 v[210:213], v184 offset:38912
	ds_read_b128 v[214:217], v184 offset:39936
	global_load_lds_dwordx4 v154, s[42:43]
	s_mov_b32 m0, s51
	s_nop 0
	global_load_lds_dwordx4 v158, s[42:43]
	s_waitcnt vmcnt(8)
	s_waitcnt lgkmcnt(0)
	s_barrier
	s_setprio 1
	s_waitcnt lgkmcnt(0)
	v_mfma_f32_16x16x32_bf16 v[122:125], v[132:135], v[186:189], v[122:125]
	v_mfma_f32_16x16x32_bf16 v[118:121], v[140:143], v[186:189], v[118:121]
	v_mfma_f32_16x16x32_bf16 v[110:113], v[132:135], v[194:197], v[110:113]
	v_mfma_f32_16x16x32_bf16 v[106:109], v[140:143], v[194:197], v[106:109]
	v_mfma_f32_16x16x32_bf16 v[94:97], v[132:135], v[202:205], v[94:97]
	v_mfma_f32_16x16x32_bf16 v[90:93], v[140:143], v[202:205], v[90:93]
	v_mfma_f32_16x16x32_bf16 v[78:81], v[132:135], v[210:213], v[78:81]
	v_mfma_f32_16x16x32_bf16 v[74:77], v[140:143], v[210:213], v[74:77]
	v_mfma_f32_16x16x32_bf16 v[122:125], v[136:139], v[190:193], v[122:125]
	v_mfma_f32_16x16x32_bf16 v[118:121], v[144:147], v[190:193], v[118:121]
	v_mfma_f32_16x16x32_bf16 v[110:113], v[136:139], v[198:201], v[110:113]
	v_mfma_f32_16x16x32_bf16 v[106:109], v[144:147], v[198:201], v[106:109]
	v_mfma_f32_16x16x32_bf16 v[94:97], v[136:139], v[206:209], v[94:97]
	v_mfma_f32_16x16x32_bf16 v[90:93], v[144:147], v[206:209], v[90:93]
	v_mfma_f32_16x16x32_bf16 v[78:81], v[136:139], v[214:217], v[78:81]
	v_mfma_f32_16x16x32_bf16 v[74:77], v[144:147], v[214:217], v[74:77]
	s_setprio 0
	s_setprio 1
	v_mfma_f32_16x16x32_bf16 v[126:129], v[148:151], v[186:189], v[126:129]
	v_mfma_f32_16x16x32_bf16 v[114:117], v[174:177], v[186:189], v[114:117]
	v_mfma_f32_16x16x32_bf16 v[102:105], v[148:151], v[194:197], v[102:105]
	v_mfma_f32_16x16x32_bf16 v[98:101], v[174:177], v[194:197], v[98:101]
	v_mfma_f32_16x16x32_bf16 v[86:89], v[148:151], v[202:205], v[86:89]
	v_mfma_f32_16x16x32_bf16 v[82:85], v[174:177], v[202:205], v[82:85]
	v_mfma_f32_16x16x32_bf16 v[70:73], v[148:151], v[210:213], v[70:73]
	v_mfma_f32_16x16x32_bf16 v[66:69], v[174:177], v[210:213], v[66:69]
	v_mfma_f32_16x16x32_bf16 v[126:129], v[170:173], v[190:193], v[126:129]
	v_mfma_f32_16x16x32_bf16 v[114:117], v[178:181], v[190:193], v[114:117]
	v_mfma_f32_16x16x32_bf16 v[102:105], v[170:173], v[198:201], v[102:105]
	v_mfma_f32_16x16x32_bf16 v[98:101], v[178:181], v[198:201], v[98:101]
	v_mfma_f32_16x16x32_bf16 v[86:89], v[170:173], v[206:209], v[86:89]
	v_mfma_f32_16x16x32_bf16 v[82:85], v[178:181], v[206:209], v[82:85]
	v_mfma_f32_16x16x32_bf16 v[70:73], v[170:173], v[214:217], v[70:73]
	v_mfma_f32_16x16x32_bf16 v[66:69], v[178:181], v[214:217], v[66:69]
	s_setprio 0
	s_barrier
	s_mov_b32 m0, s47
	s_add_u32 s98, s98, 0x80
	s_addc_u32 s99, s99, 0
	s_add_u32 s100, s100, 0x80
	s_addc_u32 s101, s101, 0
	s_add_u32 s38, s38, 0x20080
	ds_read_b128 v[186:189], v184 offset:49152
	ds_read_b128 v[190:193], v184 offset:50176
	ds_read_b128 v[194:197], v184 offset:51200
	ds_read_b128 v[198:201], v184 offset:52224
	ds_read_b128 v[202:205], v184 offset:53248
	ds_read_b128 v[206:209], v184 offset:54272
	ds_read_b128 v[210:213], v184 offset:55296
	ds_read_b128 v[214:217], v184 offset:56320
	global_load_lds_dwordx4 v156, s[98:99]
	s_mov_b32 m0, s68
	s_addc_u32 s39, s39, 0
	global_load_lds_dwordx4 v160, s[98:99]
	s_mov_b32 m0, s56
	s_nop 0
	global_load_lds_dwordx4 v156, s[38:39]
	s_mov_b32 m0, s57
	s_nop 0
	global_load_lds_dwordx4 v160, s[38:39]
	s_mov_b32 m0, s52
	s_nop 0
	global_load_lds_dwordx4 v154, s[100:101]
	s_mov_b32 m0, s53
	s_nop 0
	global_load_lds_dwordx4 v158, s[100:101]
	s_waitcnt vmcnt(8)
	s_waitcnt lgkmcnt(0)
	s_barrier
	s_setprio 1
	s_waitcnt lgkmcnt(0)
	v_mfma_f32_16x16x32_bf16 v[58:61], v[132:135], v[186:189], v[58:61]
	v_mfma_f32_16x16x32_bf16 v[54:57], v[140:143], v[186:189], v[54:57]
	v_mfma_f32_16x16x32_bf16 v[46:49], v[132:135], v[194:197], v[46:49]
	v_mfma_f32_16x16x32_bf16 v[42:45], v[140:143], v[194:197], v[42:45]
	v_mfma_f32_16x16x32_bf16 v[30:33], v[132:135], v[202:205], v[30:33]
	v_mfma_f32_16x16x32_bf16 v[26:29], v[140:143], v[202:205], v[26:29]
	v_mfma_f32_16x16x32_bf16 v[14:17], v[132:135], v[210:213], v[14:17]
	v_mfma_f32_16x16x32_bf16 v[10:13], v[140:143], v[210:213], v[10:13]
	v_mfma_f32_16x16x32_bf16 v[58:61], v[136:139], v[190:193], v[58:61]
	v_mfma_f32_16x16x32_bf16 v[54:57], v[144:147], v[190:193], v[54:57]
	v_mfma_f32_16x16x32_bf16 v[46:49], v[136:139], v[198:201], v[46:49]
	v_mfma_f32_16x16x32_bf16 v[42:45], v[144:147], v[198:201], v[42:45]
	v_mfma_f32_16x16x32_bf16 v[30:33], v[136:139], v[206:209], v[30:33]
	v_mfma_f32_16x16x32_bf16 v[26:29], v[144:147], v[206:209], v[26:29]
	v_mfma_f32_16x16x32_bf16 v[14:17], v[136:139], v[214:217], v[14:17]
	v_mfma_f32_16x16x32_bf16 v[10:13], v[144:147], v[214:217], v[10:13]
	s_setprio 0
	s_setprio 1
	v_mfma_f32_16x16x32_bf16 v[62:65], v[148:151], v[186:189], v[62:65]
	v_mfma_f32_16x16x32_bf16 v[50:53], v[174:177], v[186:189], v[50:53]
	v_mfma_f32_16x16x32_bf16 v[38:41], v[148:151], v[194:197], v[38:41]
	v_mfma_f32_16x16x32_bf16 v[34:37], v[174:177], v[194:197], v[34:37]
	v_mfma_f32_16x16x32_bf16 v[22:25], v[148:151], v[202:205], v[22:25]
	v_mfma_f32_16x16x32_bf16 v[18:21], v[174:177], v[202:205], v[18:21]
	v_mfma_f32_16x16x32_bf16 v[6:9], v[148:151], v[210:213], v[6:9]
	v_mfma_f32_16x16x32_bf16 v[2:5], v[174:177], v[210:213], v[2:5]
	v_mfma_f32_16x16x32_bf16 v[62:65], v[170:173], v[190:193], v[62:65]
	v_mfma_f32_16x16x32_bf16 v[50:53], v[178:181], v[190:193], v[50:53]
	v_mfma_f32_16x16x32_bf16 v[38:41], v[170:173], v[198:201], v[38:41]
	v_mfma_f32_16x16x32_bf16 v[34:37], v[178:181], v[198:201], v[34:37]
	v_mfma_f32_16x16x32_bf16 v[22:25], v[170:173], v[206:209], v[22:25]
	v_mfma_f32_16x16x32_bf16 v[18:21], v[178:181], v[206:209], v[18:21]
	v_mfma_f32_16x16x32_bf16 v[6:9], v[170:173], v[214:217], v[6:9]
	v_mfma_f32_16x16x32_bf16 v[2:5], v[178:181], v[214:217], v[2:5]
	s_setprio 0
	s_barrier
	s_add_i32 s69, s69, 2
	s_add_u32 s40, s40, 0x100
	s_addc_u32 s41, s41, 0
	s_add_u32 s26, s26, 0x100
	s_addc_u32 s27, s27, 0
	s_cmp_gt_u32 s69, 5
	s_cbranch_scc0 .LBB0_1261
	s_and_b64 vcc, exec, s[16:17]
	s_cbranch_vccz .LBB0_1264
	s_barrier

.LBB0_1345:
	ds_read_b128 v[156:159], v150
	ds_read_b128 v[160:163], v150 offset:1024
	ds_read_b128 v[164:167], v150 offset:2048
	ds_read_b128 v[168:171], v150 offset:3072
	ds_read_b128 v[172:175], v151
	ds_read_b128 v[176:179], v151 offset:1024
	ds_read_b128 v[180:183], v151 offset:2048
	ds_read_b128 v[184:187], v151 offset:3072
	s_add_u32 s38, s40, 0xfff00080
	s_addc_u32 s39, s41, -1
	s_cmp_eq_u32 s68, 60
	s_cselect_b32 s43, s1, s39
	s_cselect_b32 s42, s25, s38
	s_cselect_b32 s39, s8, s27
	s_cselect_b32 s38, s67, s26
	s_mov_b32 m0, s53
	ds_read_b128 v[188:191], v152
	ds_read_b128 v[192:195], v152 offset:1024
	ds_read_b128 v[196:199], v152 offset:2048
	ds_read_b128 v[200:203], v152 offset:3072
	ds_read_b128 v[204:207], v152 offset:4096
	ds_read_b128 v[208:211], v152 offset:5120
	ds_read_b128 v[212:215], v152 offset:6144
	ds_read_b128 v[216:219], v152 offset:7168
	global_load_lds_dwordx4 v0, s[40:41]
	s_mov_b32 m0, s54
	s_nop 0
	global_load_lds_dwordx4 v140, s[40:41]
	s_waitcnt vmcnt(8)
	s_waitcnt lgkmcnt(0)
	s_barrier
	s_setprio 1
	s_waitcnt lgkmcnt(0)
	v_mfma_f32_16x16x32_bf16 v[118:121], v[156:159], v[188:191], v[118:121]
	v_mfma_f32_16x16x32_bf16 v[114:117], v[164:167], v[188:191], v[114:117]
	v_mfma_f32_16x16x32_bf16 v[102:105], v[156:159], v[196:199], v[102:105]
	v_mfma_f32_16x16x32_bf16 v[98:101], v[164:167], v[196:199], v[98:101]
	v_mfma_f32_16x16x32_bf16 v[86:89], v[156:159], v[204:207], v[86:89]
	v_mfma_f32_16x16x32_bf16 v[82:85], v[164:167], v[204:207], v[82:85]
	v_mfma_f32_16x16x32_bf16 v[66:69], v[156:159], v[212:215], v[66:69]
	v_mfma_f32_16x16x32_bf16 v[62:65], v[164:167], v[212:215], v[62:65]
	v_mfma_f32_16x16x32_bf16 v[118:121], v[160:163], v[192:195], v[118:121]
	v_mfma_f32_16x16x32_bf16 v[114:117], v[168:171], v[192:195], v[114:117]
	v_mfma_f32_16x16x32_bf16 v[102:105], v[160:163], v[200:203], v[102:105]
	v_mfma_f32_16x16x32_bf16 v[98:101], v[168:171], v[200:203], v[98:101]
	v_mfma_f32_16x16x32_bf16 v[86:89], v[160:163], v[208:211], v[86:89]
	v_mfma_f32_16x16x32_bf16 v[82:85], v[168:171], v[208:211], v[82:85]
	v_mfma_f32_16x16x32_bf16 v[66:69], v[160:163], v[216:219], v[66:69]
	v_mfma_f32_16x16x32_bf16 v[62:65], v[168:171], v[216:219], v[62:65]
	s_setprio 0
	s_setprio 1
	v_mfma_f32_16x16x32_bf16 v[126:129], v[172:175], v[188:191], v[126:129]
	v_mfma_f32_16x16x32_bf16 v[122:125], v[180:183], v[188:191], v[122:125]
	v_mfma_f32_16x16x32_bf16 v[110:113], v[172:175], v[196:199], v[110:113]
	v_mfma_f32_16x16x32_bf16 v[106:109], v[180:183], v[196:199], v[106:109]
	v_mfma_f32_16x16x32_bf16 v[94:97], v[172:175], v[204:207], v[94:97]
	v_mfma_f32_16x16x32_bf16 v[90:93], v[180:183], v[204:207], v[90:93]
	v_mfma_f32_16x16x32_bf16 v[78:81], v[172:175], v[212:215], v[78:81]
	v_mfma_f32_16x16x32_bf16 v[74:77], v[180:183], v[212:215], v[74:77]
	v_mfma_f32_16x16x32_bf16 v[126:129], v[176:179], v[192:195], v[126:129]
	v_mfma_f32_16x16x32_bf16 v[122:125], v[184:187], v[192:195], v[122:125]
	v_mfma_f32_16x16x32_bf16 v[110:113], v[176:179], v[200:203], v[110:113]
	v_mfma_f32_16x16x32_bf16 v[106:109], v[184:187], v[200:203], v[106:109]
	v_mfma_f32_16x16x32_bf16 v[94:97], v[176:179], v[208:211], v[94:97]
	v_mfma_f32_16x16x32_bf16 v[90:93], v[184:187], v[208:211], v[90:93]
	v_mfma_f32_16x16x32_bf16 v[78:81], v[176:179], v[216:219], v[78:81]
	v_mfma_f32_16x16x32_bf16 v[74:77], v[184:187], v[216:219], v[74:77]
	s_setprio 0
	s_barrier
	s_mov_b32 m0, s59
	s_mov_b64 s[98:99], s[38:39]
	s_add_u32 s70, s38, 0x100000
	ds_read_b128 v[188:191], v152 offset:16384
	ds_read_b128 v[192:195], v152 offset:17408
	ds_read_b128 v[196:199], v152 offset:18432
	ds_read_b128 v[200:203], v152 offset:19456
	ds_read_b128 v[204:207], v152 offset:20480
	ds_read_b128 v[208:211], v152 offset:21504
	ds_read_b128 v[212:215], v152 offset:22528
	ds_read_b128 v[216:219], v152 offset:23552
	global_load_lds_dwordx4 v134, s[38:39]
	s_mov_b32 m0, s60
	s_addc_u32 s71, s39, 0
	global_load_lds_dwordx4 v130, s[38:39]
	s_mov_b32 m0, s61
	s_mov_b64 s[100:101], s[42:43]
	global_load_lds_dwordx4 v134, s[70:71]
	s_mov_b32 m0, s62
	s_nop 0
	global_load_lds_dwordx4 v130, s[70:71]
	s_mov_b32 m0, s13
	s_nop 0
	global_load_lds_dwordx4 v136, s[42:43]
	s_mov_b32 m0, s33
	s_nop 0
	global_load_lds_dwordx4 v132, s[42:43]
	s_waitcnt vmcnt(8)
	s_waitcnt lgkmcnt(0)
	s_barrier
	s_setprio 1
	s_waitcnt lgkmcnt(0)
	v_mfma_f32_16x16x32_bf16 v[54:57], v[156:159], v[188:191], v[54:57]
	v_mfma_f32_16x16x32_bf16 v[50:53], v[164:167], v[188:191], v[50:53]
	v_mfma_f32_16x16x32_bf16 v[38:41], v[156:159], v[196:199], v[38:41]
	v_mfma_f32_16x16x32_bf16 v[34:37], v[164:167], v[196:199], v[34:37]
	v_mfma_f32_16x16x32_bf16 v[22:25], v[156:159], v[204:207], v[22:25]
	v_mfma_f32_16x16x32_bf16 v[18:21], v[164:167], v[204:207], v[18:21]
	v_mfma_f32_16x16x32_bf16 v[6:9], v[156:159], v[212:215], v[6:9]
	v_mfma_f32_16x16x32_bf16 v[2:5], v[164:167], v[212:215], v[2:5]
	v_mfma_f32_16x16x32_bf16 v[54:57], v[160:163], v[192:195], v[54:57]
	v_mfma_f32_16x16x32_bf16 v[50:53], v[168:171], v[192:195], v[50:53]
	v_mfma_f32_16x16x32_bf16 v[38:41], v[160:163], v[200:203], v[38:41]
	v_mfma_f32_16x16x32_bf16 v[34:37], v[168:171], v[200:203], v[34:37]
	v_mfma_f32_16x16x32_bf16 v[22:25], v[160:163], v[208:211], v[22:25]
	v_mfma_f32_16x16x32_bf16 v[18:21], v[168:171], v[208:211], v[18:21]
	v_mfma_f32_16x16x32_bf16 v[6:9], v[160:163], v[216:219], v[6:9]
	v_mfma_f32_16x16x32_bf16 v[2:5], v[168:171], v[216:219], v[2:5]
	s_setprio 0
	s_setprio 1
	v_mfma_f32_16x16x32_bf16 v[70:73], v[172:175], v[188:191], v[70:73]
	v_mfma_f32_16x16x32_bf16 v[58:61], v[180:183], v[188:191], v[58:61]
	v_mfma_f32_16x16x32_bf16 v[46:49], v[172:175], v[196:199], v[46:49]
	v_mfma_f32_16x16x32_bf16 v[42:45], v[180:183], v[196:199], v[42:45]
	v_mfma_f32_16x16x32_bf16 v[30:33], v[172:175], v[204:207], v[30:33]
	v_mfma_f32_16x16x32_bf16 v[26:29], v[180:183], v[204:207], v[26:29]
	v_mfma_f32_16x16x32_bf16 v[14:17], v[172:175], v[212:215], v[14:17]
	v_mfma_f32_16x16x32_bf16 v[10:13], v[180:183], v[212:215], v[10:13]
	v_mfma_f32_16x16x32_bf16 v[70:73], v[176:179], v[192:195], v[70:73]
	v_mfma_f32_16x16x32_bf16 v[58:61], v[184:187], v[192:195], v[58:61]
	v_mfma_f32_16x16x32_bf16 v[46:49], v[176:179], v[200:203], v[46:49]
	v_mfma_f32_16x16x32_bf16 v[42:45], v[184:187], v[200:203], v[42:45]
	v_mfma_f32_16x16x32_bf16 v[30:33], v[176:179], v[208:211], v[30:33]
	v_mfma_f32_16x16x32_bf16 v[26:29], v[184:187], v[208:211], v[26:29]
	v_mfma_f32_16x16x32_bf16 v[14:17], v[176:179], v[216:219], v[14:17]
	v_mfma_f32_16x16x32_bf16 v[10:13], v[184:187], v[216:219], v[10:13]
	s_setprio 0
	s_barrier
	ds_read_b128 v[156:159], v154
	ds_read_b128 v[160:163], v154 offset:1024
	ds_read_b128 v[164:167], v154 offset:2048
	ds_read_b128 v[168:171], v154 offset:3072
	ds_read_b128 v[172:175], v146
	ds_read_b128 v[176:179], v146 offset:1024
	ds_read_b128 v[180:183], v146 offset:2048
	ds_read_b128 v[184:187], v146 offset:3072
	s_add_u32 s42, s42, 0x100000
	s_addc_u32 s43, s43, 0
	s_mov_b32 m0, s48
	ds_read_b128 v[188:191], v152 offset:32768
	ds_read_b128 v[192:195], v152 offset:33792
	ds_read_b128 v[196:199], v152 offset:34816
	ds_read_b128 v[200:203], v152 offset:35840
	ds_read_b128 v[204:207], v152 offset:36864
	ds_read_b128 v[208:211], v152 offset:37888
	ds_read_b128 v[212:215], v152 offset:38912
	ds_read_b128 v[216:219], v152 offset:39936
	global_load_lds_dwordx4 v136, s[42:43]
	s_mov_b32 m0, s49
	s_nop 0
	global_load_lds_dwordx4 v132, s[42:43]
	s_waitcnt vmcnt(8)
	s_waitcnt lgkmcnt(0)
	s_barrier
	s_setprio 1
	s_waitcnt lgkmcnt(0)
	v_mfma_f32_16x16x32_bf16 v[118:121], v[156:159], v[188:191], v[118:121]
	v_mfma_f32_16x16x32_bf16 v[114:117], v[164:167], v[188:191], v[114:117]
	v_mfma_f32_16x16x32_bf16 v[102:105], v[156:159], v[196:199], v[102:105]
	v_mfma_f32_16x16x32_bf16 v[98:101], v[164:167], v[196:199], v[98:101]
	v_mfma_f32_16x16x32_bf16 v[86:89], v[156:159], v[204:207], v[86:89]
	v_mfma_f32_16x16x32_bf16 v[82:85], v[164:167], v[204:207], v[82:85]
	v_mfma_f32_16x16x32_bf16 v[66:69], v[156:159], v[212:215], v[66:69]
	v_mfma_f32_16x16x32_bf16 v[62:65], v[164:167], v[212:215], v[62:65]
	v_mfma_f32_16x16x32_bf16 v[118:121], v[160:163], v[192:195], v[118:121]
	v_mfma_f32_16x16x32_bf16 v[114:117], v[168:171], v[192:195], v[114:117]
	v_mfma_f32_16x16x32_bf16 v[102:105], v[160:163], v[200:203], v[102:105]
	v_mfma_f32_16x16x32_bf16 v[98:101], v[168:171], v[200:203], v[98:101]
	v_mfma_f32_16x16x32_bf16 v[86:89], v[160:163], v[208:211], v[86:89]
	v_mfma_f32_16x16x32_bf16 v[82:85], v[168:171], v[208:211], v[82:85]
	v_mfma_f32_16x16x32_bf16 v[66:69], v[160:163], v[216:219], v[66:69]
	v_mfma_f32_16x16x32_bf16 v[62:65], v[168:171], v[216:219], v[62:65]
	s_setprio 0
	s_setprio 1
	v_mfma_f32_16x16x32_bf16 v[126:129], v[172:175], v[188:191], v[126:129]
	v_mfma_f32_16x16x32_bf16 v[122:125], v[180:183], v[188:191], v[122:125]
	v_mfma_f32_16x16x32_bf16 v[110:113], v[172:175], v[196:199], v[110:113]
	v_mfma_f32_16x16x32_bf16 v[106:109], v[180:183], v[196:199], v[106:109]
	v_mfma_f32_16x16x32_bf16 v[94:97], v[172:175], v[204:207], v[94:97]
	v_mfma_f32_16x16x32_bf16 v[90:93], v[180:183], v[204:207], v[90:93]
	v_mfma_f32_16x16x32_bf16 v[78:81], v[172:175], v[212:215], v[78:81]
	v_mfma_f32_16x16x32_bf16 v[74:77], v[180:183], v[212:215], v[74:77]
	v_mfma_f32_16x16x32_bf16 v[126:129], v[176:179], v[192:195], v[126:129]
	v_mfma_f32_16x16x32_bf16 v[122:125], v[184:187], v[192:195], v[122:125]
	v_mfma_f32_16x16x32_bf16 v[110:113], v[176:179], v[200:203], v[110:113]
	v_mfma_f32_16x16x32_bf16 v[106:109], v[184:187], v[200:203], v[106:109]
	v_mfma_f32_16x16x32_bf16 v[94:97], v[176:179], v[208:211], v[94:97]
	v_mfma_f32_16x16x32_bf16 v[90:93], v[184:187], v[208:211], v[90:93]
	v_mfma_f32_16x16x32_bf16 v[78:81], v[176:179], v[216:219], v[78:81]
	v_mfma_f32_16x16x32_bf16 v[74:77], v[184:187], v[216:219], v[74:77]
	s_setprio 0
	s_barrier
	s_mov_b32 m0, s46
	s_add_u32 s98, s98, 0x80
	s_addc_u32 s99, s99, 0
	s_add_u32 s100, s100, 0x80
	s_addc_u32 s101, s101, 0
	s_add_u32 s38, s38, 0x100080
	ds_read_b128 v[188:191], v152 offset:49152
	ds_read_b128 v[192:195], v152 offset:50176
	ds_read_b128 v[196:199], v152 offset:51200
	ds_read_b128 v[200:203], v152 offset:52224
	ds_read_b128 v[204:207], v152 offset:53248
	ds_read_b128 v[208:211], v152 offset:54272
	ds_read_b128 v[212:215], v152 offset:55296
	ds_read_b128 v[216:219], v152 offset:56320
	global_load_lds_dwordx4 v134, s[98:99]
	s_mov_b32 m0, s47
	s_addc_u32 s39, s39, 0
	global_load_lds_dwordx4 v130, s[98:99]
	s_mov_b32 m0, s56
	s_nop 0
	global_load_lds_dwordx4 v134, s[38:39]
	s_mov_b32 m0, s57
	s_nop 0
	global_load_lds_dwordx4 v130, s[38:39]
	s_mov_b32 m0, s50
	s_nop 0
	global_load_lds_dwordx4 v136, s[100:101]
	s_mov_b32 m0, s51
	s_nop 0
	global_load_lds_dwordx4 v132, s[100:101]
	s_waitcnt vmcnt(8)
	s_waitcnt lgkmcnt(0)
	s_barrier
	s_setprio 1
	s_waitcnt lgkmcnt(0)
	v_mfma_f32_16x16x32_bf16 v[54:57], v[156:159], v[188:191], v[54:57]
	v_mfma_f32_16x16x32_bf16 v[50:53], v[164:167], v[188:191], v[50:53]
	v_mfma_f32_16x16x32_bf16 v[38:41], v[156:159], v[196:199], v[38:41]
	v_mfma_f32_16x16x32_bf16 v[34:37], v[164:167], v[196:199], v[34:37]
	v_mfma_f32_16x16x32_bf16 v[22:25], v[156:159], v[204:207], v[22:25]
	v_mfma_f32_16x16x32_bf16 v[18:21], v[164:167], v[204:207], v[18:21]
	v_mfma_f32_16x16x32_bf16 v[6:9], v[156:159], v[212:215], v[6:9]
	v_mfma_f32_16x16x32_bf16 v[2:5], v[164:167], v[212:215], v[2:5]
	v_mfma_f32_16x16x32_bf16 v[54:57], v[160:163], v[192:195], v[54:57]
	v_mfma_f32_16x16x32_bf16 v[50:53], v[168:171], v[192:195], v[50:53]
	v_mfma_f32_16x16x32_bf16 v[38:41], v[160:163], v[200:203], v[38:41]
	v_mfma_f32_16x16x32_bf16 v[34:37], v[168:171], v[200:203], v[34:37]
	v_mfma_f32_16x16x32_bf16 v[22:25], v[160:163], v[208:211], v[22:25]
	v_mfma_f32_16x16x32_bf16 v[18:21], v[168:171], v[208:211], v[18:21]
	v_mfma_f32_16x16x32_bf16 v[6:9], v[160:163], v[216:219], v[6:9]
	v_mfma_f32_16x16x32_bf16 v[2:5], v[168:171], v[216:219], v[2:5]
	s_setprio 0
	s_setprio 1
	v_mfma_f32_16x16x32_bf16 v[70:73], v[172:175], v[188:191], v[70:73]
	v_mfma_f32_16x16x32_bf16 v[58:61], v[180:183], v[188:191], v[58:61]
	v_mfma_f32_16x16x32_bf16 v[46:49], v[172:175], v[196:199], v[46:49]
	v_mfma_f32_16x16x32_bf16 v[42:45], v[180:183], v[196:199], v[42:45]
	v_mfma_f32_16x16x32_bf16 v[30:33], v[172:175], v[204:207], v[30:33]
	v_mfma_f32_16x16x32_bf16 v[26:29], v[180:183], v[204:207], v[26:29]
	v_mfma_f32_16x16x32_bf16 v[14:17], v[172:175], v[212:215], v[14:17]
	v_mfma_f32_16x16x32_bf16 v[10:13], v[180:183], v[212:215], v[10:13]
	v_mfma_f32_16x16x32_bf16 v[70:73], v[176:179], v[192:195], v[70:73]
	v_mfma_f32_16x16x32_bf16 v[58:61], v[184:187], v[192:195], v[58:61]
	v_mfma_f32_16x16x32_bf16 v[46:49], v[176:179], v[200:203], v[46:49]
	v_mfma_f32_16x16x32_bf16 v[42:45], v[184:187], v[200:203], v[42:45]
	v_mfma_f32_16x16x32_bf16 v[30:33], v[176:179], v[208:211], v[30:33]
	v_mfma_f32_16x16x32_bf16 v[26:29], v[184:187], v[208:211], v[26:29]
	v_mfma_f32_16x16x32_bf16 v[14:17], v[176:179], v[216:219], v[14:17]
	v_mfma_f32_16x16x32_bf16 v[10:13], v[184:187], v[216:219], v[10:13]
	s_setprio 0
	s_barrier
	s_add_i32 s68, s68, 2
	s_add_u32 s40, s40, 0x100
	s_addc_u32 s41, s41, 0
	s_add_u32 s26, s26, 0x100
	s_addc_u32 s27, s27, 0
	s_cmp_gt_u32 s68, 61
	s_cbranch_scc0 .LBB0_1345
	s_and_b64 vcc, exec, s[18:19]
	s_cbranch_vccz .LBB0_1348
	s_barrier

.LBB0_1425:
	ds_read_b128 v[148:151], v152
	ds_read_b128 v[156:159], v152 offset:1024
	ds_read_b128 v[160:163], v152 offset:2048
	ds_read_b128 v[164:167], v152 offset:3072
	ds_read_b128 v[168:171], v153
	ds_read_b128 v[172:175], v153 offset:1024
	ds_read_b128 v[176:179], v153 offset:2048
	ds_read_b128 v[180:183], v153 offset:3072
	s_add_u32 s20, s18, 0x200
	s_addc_u32 s21, s19, 0
	s_cmpk_eq_i32 s57, 0xa8
	s_cselect_b32 s23, s5, s21
	s_cselect_b32 s22, s4, s20
	s_cselect_b32 s21, s17, s27
	s_cselect_b32 s20, s16, s26
	s_mov_b32 m0, s49
	ds_read_b128 v[184:187], v154
	ds_read_b128 v[188:191], v154 offset:1024
	ds_read_b128 v[192:195], v154 offset:2048
	ds_read_b128 v[196:199], v154 offset:3072
	ds_read_b128 v[200:203], v154 offset:4096
	ds_read_b128 v[204:207], v154 offset:5120
	ds_read_b128 v[208:211], v154 offset:6144
	ds_read_b128 v[212:215], v154 offset:7168
	global_load_lds_dwordx4 v138, s[18:19]
	s_mov_b32 m0, s50
	s_nop 0
	global_load_lds_dwordx4 v140, s[18:19]
	s_waitcnt vmcnt(8)
	s_waitcnt lgkmcnt(0)
	s_barrier
	s_setprio 1
	s_waitcnt lgkmcnt(0)
	v_mfma_f32_16x16x32_bf16 v[126:129], v[148:151], v[184:187], v[126:129]
	v_mfma_f32_16x16x32_bf16 v[122:125], v[160:163], v[184:187], v[122:125]
	v_mfma_f32_16x16x32_bf16 v[110:113], v[148:151], v[192:195], v[110:113]
	v_mfma_f32_16x16x32_bf16 v[106:109], v[160:163], v[192:195], v[106:109]
	v_mfma_f32_16x16x32_bf16 v[94:97], v[148:151], v[200:203], v[94:97]
	v_mfma_f32_16x16x32_bf16 v[90:93], v[160:163], v[200:203], v[90:93]
	v_mfma_f32_16x16x32_bf16 v[78:81], v[148:151], v[208:211], v[78:81]
	v_mfma_f32_16x16x32_bf16 v[74:77], v[160:163], v[208:211], v[74:77]
	v_mfma_f32_16x16x32_bf16 v[126:129], v[156:159], v[188:191], v[126:129]
	v_mfma_f32_16x16x32_bf16 v[122:125], v[164:167], v[188:191], v[122:125]
	v_mfma_f32_16x16x32_bf16 v[110:113], v[156:159], v[196:199], v[110:113]
	v_mfma_f32_16x16x32_bf16 v[106:109], v[164:167], v[196:199], v[106:109]
	v_mfma_f32_16x16x32_bf16 v[94:97], v[156:159], v[204:207], v[94:97]
	v_mfma_f32_16x16x32_bf16 v[90:93], v[164:167], v[204:207], v[90:93]
	v_mfma_f32_16x16x32_bf16 v[78:81], v[156:159], v[212:215], v[78:81]
	v_mfma_f32_16x16x32_bf16 v[74:77], v[164:167], v[212:215], v[74:77]
	s_setprio 0
	s_setprio 1
	v_mfma_f32_16x16x32_bf16 v[118:121], v[168:171], v[184:187], v[118:121]
	v_mfma_f32_16x16x32_bf16 v[114:117], v[176:179], v[184:187], v[114:117]
	v_mfma_f32_16x16x32_bf16 v[102:105], v[168:171], v[192:195], v[102:105]
	v_mfma_f32_16x16x32_bf16 v[98:101], v[176:179], v[192:195], v[98:101]
	v_mfma_f32_16x16x32_bf16 v[86:89], v[168:171], v[200:203], v[86:89]
	v_mfma_f32_16x16x32_bf16 v[82:85], v[176:179], v[200:203], v[82:85]
	v_mfma_f32_16x16x32_bf16 v[70:73], v[168:171], v[208:211], v[70:73]
	v_mfma_f32_16x16x32_bf16 v[66:69], v[176:179], v[208:211], v[66:69]
	v_mfma_f32_16x16x32_bf16 v[118:121], v[172:175], v[188:191], v[118:121]
	v_mfma_f32_16x16x32_bf16 v[114:117], v[180:183], v[188:191], v[114:117]
	v_mfma_f32_16x16x32_bf16 v[102:105], v[172:175], v[196:199], v[102:105]
	v_mfma_f32_16x16x32_bf16 v[98:101], v[180:183], v[196:199], v[98:101]
	v_mfma_f32_16x16x32_bf16 v[86:89], v[172:175], v[204:207], v[86:89]
	v_mfma_f32_16x16x32_bf16 v[82:85], v[180:183], v[204:207], v[82:85]
	v_mfma_f32_16x16x32_bf16 v[70:73], v[172:175], v[212:215], v[70:73]
	v_mfma_f32_16x16x32_bf16 v[66:69], v[180:183], v[212:215], v[66:69]
	s_setprio 0
	s_barrier
	s_mov_b32 m0, s51
	s_mov_b64 s[98:99], s[20:21]
	s_add_u32 s58, s20, 0x2b0000
	ds_read_b128 v[184:187], v154 offset:16384
	ds_read_b128 v[188:191], v154 offset:17408
	ds_read_b128 v[192:195], v154 offset:18432
	ds_read_b128 v[196:199], v154 offset:19456
	ds_read_b128 v[200:203], v154 offset:20480
	ds_read_b128 v[204:207], v154 offset:21504
	ds_read_b128 v[208:211], v154 offset:22528
	ds_read_b128 v[212:215], v154 offset:23552
	global_load_lds_dwordx4 v132, s[20:21]
	s_mov_b32 m0, s52
	s_addc_u32 s59, s21, 0
	global_load_lds_dwordx4 v136, s[20:21]
	s_mov_b32 m0, s46
	s_mov_b64 s[100:101], s[22:23]
	global_load_lds_dwordx4 v132, s[58:59]
	s_mov_b32 m0, s47
	s_nop 0
	global_load_lds_dwordx4 v136, s[58:59]
	s_mov_b32 m0, s28
	s_nop 0
	global_load_lds_dwordx4 v130, s[22:23]
	s_mov_b32 m0, s29
	s_nop 0
	global_load_lds_dwordx4 v134, s[22:23]
	s_waitcnt vmcnt(8)
	s_waitcnt lgkmcnt(0)
	s_barrier
	s_setprio 1
	s_waitcnt lgkmcnt(0)
	v_mfma_f32_16x16x32_bf16 v[62:65], v[148:151], v[184:187], v[62:65]
	v_mfma_f32_16x16x32_bf16 v[58:61], v[160:163], v[184:187], v[58:61]
	v_mfma_f32_16x16x32_bf16 v[46:49], v[148:151], v[192:195], v[46:49]
	v_mfma_f32_16x16x32_bf16 v[42:45], v[160:163], v[192:195], v[42:45]
	v_mfma_f32_16x16x32_bf16 v[30:33], v[148:151], v[200:203], v[30:33]
	v_mfma_f32_16x16x32_bf16 v[26:29], v[160:163], v[200:203], v[26:29]
	v_mfma_f32_16x16x32_bf16 v[14:17], v[148:151], v[208:211], v[14:17]
	v_mfma_f32_16x16x32_bf16 v[10:13], v[160:163], v[208:211], v[10:13]
	v_mfma_f32_16x16x32_bf16 v[62:65], v[156:159], v[188:191], v[62:65]
	v_mfma_f32_16x16x32_bf16 v[58:61], v[164:167], v[188:191], v[58:61]
	v_mfma_f32_16x16x32_bf16 v[46:49], v[156:159], v[196:199], v[46:49]
	v_mfma_f32_16x16x32_bf16 v[42:45], v[164:167], v[196:199], v[42:45]
	v_mfma_f32_16x16x32_bf16 v[30:33], v[156:159], v[204:207], v[30:33]
	v_mfma_f32_16x16x32_bf16 v[26:29], v[164:167], v[204:207], v[26:29]
	v_mfma_f32_16x16x32_bf16 v[14:17], v[156:159], v[212:215], v[14:17]
	v_mfma_f32_16x16x32_bf16 v[10:13], v[164:167], v[212:215], v[10:13]
	s_setprio 0
	s_setprio 1
	v_mfma_f32_16x16x32_bf16 v[54:57], v[168:171], v[184:187], v[54:57]
	v_mfma_f32_16x16x32_bf16 v[50:53], v[176:179], v[184:187], v[50:53]
	v_mfma_f32_16x16x32_bf16 v[38:41], v[168:171], v[192:195], v[38:41]
	v_mfma_f32_16x16x32_bf16 v[34:37], v[176:179], v[192:195], v[34:37]
	v_mfma_f32_16x16x32_bf16 v[22:25], v[168:171], v[200:203], v[22:25]
	v_mfma_f32_16x16x32_bf16 v[18:21], v[176:179], v[200:203], v[18:21]
	v_mfma_f32_16x16x32_bf16 v[6:9], v[168:171], v[208:211], v[6:9]
	v_mfma_f32_16x16x32_bf16 v[2:5], v[176:179], v[208:211], v[2:5]
	v_mfma_f32_16x16x32_bf16 v[54:57], v[172:175], v[188:191], v[54:57]
	v_mfma_f32_16x16x32_bf16 v[50:53], v[180:183], v[188:191], v[50:53]
	v_mfma_f32_16x16x32_bf16 v[38:41], v[172:175], v[196:199], v[38:41]
	v_mfma_f32_16x16x32_bf16 v[34:37], v[180:183], v[196:199], v[34:37]
	v_mfma_f32_16x16x32_bf16 v[22:25], v[172:175], v[204:207], v[22:25]
	v_mfma_f32_16x16x32_bf16 v[18:21], v[180:183], v[204:207], v[18:21]
	v_mfma_f32_16x16x32_bf16 v[6:9], v[172:175], v[212:215], v[6:9]
	v_mfma_f32_16x16x32_bf16 v[2:5], v[180:183], v[212:215], v[2:5]
	s_setprio 0
	s_barrier
	ds_read_b128 v[148:151], v146
	ds_read_b128 v[156:159], v146 offset:1024
	ds_read_b128 v[160:163], v146 offset:2048
	ds_read_b128 v[164:167], v146 offset:3072
	ds_read_b128 v[168:171], v147
	ds_read_b128 v[172:175], v147 offset:1024
	ds_read_b128 v[176:179], v147 offset:2048
	ds_read_b128 v[180:183], v147 offset:3072
	s_add_u32 s22, s22, 0x2b0000
	s_addc_u32 s23, s23, 0
	s_mov_b32 m0, s30
	ds_read_b128 v[184:187], v154 offset:32768
	ds_read_b128 v[188:191], v154 offset:33792
	ds_read_b128 v[192:195], v154 offset:34816
	ds_read_b128 v[196:199], v154 offset:35840
	ds_read_b128 v[200:203], v154 offset:36864
	ds_read_b128 v[204:207], v154 offset:37888
	ds_read_b128 v[208:211], v154 offset:38912
	ds_read_b128 v[212:215], v154 offset:39936
	global_load_lds_dwordx4 v130, s[22:23]
	s_mov_b32 m0, s31
	s_nop 0
	global_load_lds_dwordx4 v134, s[22:23]
	s_waitcnt vmcnt(8)
	s_waitcnt lgkmcnt(0)
	s_barrier
	s_setprio 1
	s_waitcnt lgkmcnt(0)
	v_mfma_f32_16x16x32_bf16 v[126:129], v[148:151], v[184:187], v[126:129]
	v_mfma_f32_16x16x32_bf16 v[122:125], v[160:163], v[184:187], v[122:125]
	v_mfma_f32_16x16x32_bf16 v[110:113], v[148:151], v[192:195], v[110:113]
	v_mfma_f32_16x16x32_bf16 v[106:109], v[160:163], v[192:195], v[106:109]
	v_mfma_f32_16x16x32_bf16 v[94:97], v[148:151], v[200:203], v[94:97]
	v_mfma_f32_16x16x32_bf16 v[90:93], v[160:163], v[200:203], v[90:93]
	v_mfma_f32_16x16x32_bf16 v[78:81], v[148:151], v[208:211], v[78:81]
	v_mfma_f32_16x16x32_bf16 v[74:77], v[160:163], v[208:211], v[74:77]
	v_mfma_f32_16x16x32_bf16 v[126:129], v[156:159], v[188:191], v[126:129]
	v_mfma_f32_16x16x32_bf16 v[122:125], v[164:167], v[188:191], v[122:125]
	v_mfma_f32_16x16x32_bf16 v[110:113], v[156:159], v[196:199], v[110:113]
	v_mfma_f32_16x16x32_bf16 v[106:109], v[164:167], v[196:199], v[106:109]
	v_mfma_f32_16x16x32_bf16 v[94:97], v[156:159], v[204:207], v[94:97]
	v_mfma_f32_16x16x32_bf16 v[90:93], v[164:167], v[204:207], v[90:93]
	v_mfma_f32_16x16x32_bf16 v[78:81], v[156:159], v[212:215], v[78:81]
	v_mfma_f32_16x16x32_bf16 v[74:77], v[164:167], v[212:215], v[74:77]
	s_setprio 0
	s_setprio 1
	v_mfma_f32_16x16x32_bf16 v[118:121], v[168:171], v[184:187], v[118:121]
	v_mfma_f32_16x16x32_bf16 v[114:117], v[176:179], v[184:187], v[114:117]
	v_mfma_f32_16x16x32_bf16 v[102:105], v[168:171], v[192:195], v[102:105]
	v_mfma_f32_16x16x32_bf16 v[98:101], v[176:179], v[192:195], v[98:101]
	v_mfma_f32_16x16x32_bf16 v[86:89], v[168:171], v[200:203], v[86:89]
	v_mfma_f32_16x16x32_bf16 v[82:85], v[176:179], v[200:203], v[82:85]
	v_mfma_f32_16x16x32_bf16 v[70:73], v[168:171], v[208:211], v[70:73]
	v_mfma_f32_16x16x32_bf16 v[66:69], v[176:179], v[208:211], v[66:69]
	v_mfma_f32_16x16x32_bf16 v[118:121], v[172:175], v[188:191], v[118:121]
	v_mfma_f32_16x16x32_bf16 v[114:117], v[180:183], v[188:191], v[114:117]
	v_mfma_f32_16x16x32_bf16 v[102:105], v[172:175], v[196:199], v[102:105]
	v_mfma_f32_16x16x32_bf16 v[98:101], v[180:183], v[196:199], v[98:101]
	v_mfma_f32_16x16x32_bf16 v[86:89], v[172:175], v[204:207], v[86:89]
	v_mfma_f32_16x16x32_bf16 v[82:85], v[180:183], v[204:207], v[82:85]
	v_mfma_f32_16x16x32_bf16 v[70:73], v[172:175], v[212:215], v[70:73]
	v_mfma_f32_16x16x32_bf16 v[66:69], v[180:183], v[212:215], v[66:69]
	s_setprio 0
	s_barrier
	s_mov_b32 m0, s53
	s_add_u32 s98, s98, 0x80
	s_addc_u32 s99, s99, 0
	s_add_u32 s100, s100, 0x80
	s_addc_u32 s101, s101, 0
	s_add_u32 s20, s20, 0x2b0080
	ds_read_b128 v[184:187], v154 offset:49152
	ds_read_b128 v[188:191], v154 offset:50176
	ds_read_b128 v[192:195], v154 offset:51200
	ds_read_b128 v[196:199], v154 offset:52224
	ds_read_b128 v[200:203], v154 offset:53248
	ds_read_b128 v[204:207], v154 offset:54272
	ds_read_b128 v[208:211], v154 offset:55296
	ds_read_b128 v[212:215], v154 offset:56320
	global_load_lds_dwordx4 v132, s[98:99]
	s_mov_b32 m0, s54
	s_addc_u32 s21, s21, 0
	global_load_lds_dwordx4 v136, s[98:99]
	s_mov_b32 m0, s55
	s_nop 0
	global_load_lds_dwordx4 v132, s[20:21]
	s_mov_b32 m0, s56
	s_nop 0
	global_load_lds_dwordx4 v136, s[20:21]
	s_mov_b32 m0, s34
	s_nop 0
	global_load_lds_dwordx4 v130, s[100:101]
	s_mov_b32 m0, s35
	s_nop 0
	global_load_lds_dwordx4 v134, s[100:101]
	s_waitcnt vmcnt(8)
	s_waitcnt lgkmcnt(0)
	s_barrier
	s_setprio 1
	s_waitcnt lgkmcnt(0)
	v_mfma_f32_16x16x32_bf16 v[62:65], v[148:151], v[184:187], v[62:65]
	v_mfma_f32_16x16x32_bf16 v[58:61], v[160:163], v[184:187], v[58:61]
	v_mfma_f32_16x16x32_bf16 v[46:49], v[148:151], v[192:195], v[46:49]
	v_mfma_f32_16x16x32_bf16 v[42:45], v[160:163], v[192:195], v[42:45]
	v_mfma_f32_16x16x32_bf16 v[30:33], v[148:151], v[200:203], v[30:33]
	v_mfma_f32_16x16x32_bf16 v[26:29], v[160:163], v[200:203], v[26:29]
	v_mfma_f32_16x16x32_bf16 v[14:17], v[148:151], v[208:211], v[14:17]
	v_mfma_f32_16x16x32_bf16 v[10:13], v[160:163], v[208:211], v[10:13]
	v_mfma_f32_16x16x32_bf16 v[62:65], v[156:159], v[188:191], v[62:65]
	v_mfma_f32_16x16x32_bf16 v[58:61], v[164:167], v[188:191], v[58:61]
	v_mfma_f32_16x16x32_bf16 v[46:49], v[156:159], v[196:199], v[46:49]
	v_mfma_f32_16x16x32_bf16 v[42:45], v[164:167], v[196:199], v[42:45]
	v_mfma_f32_16x16x32_bf16 v[30:33], v[156:159], v[204:207], v[30:33]
	v_mfma_f32_16x16x32_bf16 v[26:29], v[164:167], v[204:207], v[26:29]
	v_mfma_f32_16x16x32_bf16 v[14:17], v[156:159], v[212:215], v[14:17]
	v_mfma_f32_16x16x32_bf16 v[10:13], v[164:167], v[212:215], v[10:13]
	s_setprio 0
	s_setprio 1
	v_mfma_f32_16x16x32_bf16 v[54:57], v[168:171], v[184:187], v[54:57]
	v_mfma_f32_16x16x32_bf16 v[50:53], v[176:179], v[184:187], v[50:53]
	v_mfma_f32_16x16x32_bf16 v[38:41], v[168:171], v[192:195], v[38:41]
	v_mfma_f32_16x16x32_bf16 v[34:37], v[176:179], v[192:195], v[34:37]
	v_mfma_f32_16x16x32_bf16 v[22:25], v[168:171], v[200:203], v[22:25]
	v_mfma_f32_16x16x32_bf16 v[18:21], v[176:179], v[200:203], v[18:21]
	v_mfma_f32_16x16x32_bf16 v[6:9], v[168:171], v[208:211], v[6:9]
	v_mfma_f32_16x16x32_bf16 v[2:5], v[176:179], v[208:211], v[2:5]
	v_mfma_f32_16x16x32_bf16 v[54:57], v[172:175], v[188:191], v[54:57]
	v_mfma_f32_16x16x32_bf16 v[50:53], v[180:183], v[188:191], v[50:53]
	v_mfma_f32_16x16x32_bf16 v[38:41], v[172:175], v[196:199], v[38:41]
	v_mfma_f32_16x16x32_bf16 v[34:37], v[180:183], v[196:199], v[34:37]
	v_mfma_f32_16x16x32_bf16 v[22:25], v[172:175], v[204:207], v[22:25]
	v_mfma_f32_16x16x32_bf16 v[18:21], v[180:183], v[204:207], v[18:21]
	v_mfma_f32_16x16x32_bf16 v[6:9], v[172:175], v[212:215], v[6:9]
	v_mfma_f32_16x16x32_bf16 v[2:5], v[180:183], v[212:215], v[2:5]
	s_setprio 0
	s_barrier
	s_add_i32 s57, s57, 2
	s_add_u32 s18, s18, 0x100
	s_addc_u32 s19, s19, 0
	s_add_u32 s26, s26, 0x100
	s_addc_u32 s27, s27, 0
	s_cmpk_gt_u32 s57, 0xa9
	s_cbranch_scc0 .LBB0_1425
	s_and_b64 vcc, exec, s[10:11]
	s_cbranch_vccz .LBB0_1428
	s_barrier
